# accumulator clears removed: in a unit's first K-tile the first MFMA of every accumulator takes C=0 (separate copy of that 64-MFMA segment)
# baseline (speedup 1.0000x reference)
.LBB0_164:
	s_ashr_i32 s11, s10, 31
	s_lshl_b64 s[18:19], s[10:11], 20
	s_add_u32 s48, s66, s18
	s_addc_u32 s49, s67, s19
	s_and_b64 s[18:19], s[46:47], exec
	s_cselect_b32 s1, s49, s15
	s_cselect_b32 s4, s48, s14
	s_ashr_i32 s13, s12, 31
	s_lshl_b64 s[18:19], s[12:13], 20
	s_add_u32 s54, s28, s18
	s_addc_u32 s55, s29, s19
	s_and_b64 s[18:19], s[46:47], exec
	s_cselect_b32 s11, s55, s17
	s_cselect_b32 s13, s54, s16
	s_add_u32 s14, s14, 0x80080
	s_addc_u32 s15, s15, 0
	s_add_u32 s20, s16, 0x100
	s_addc_u32 s21, s17, 0
	s_mov_b32 s64, -2
.LBB0_165:
	s_add_u32 s16, s14, 0xfff80080
	s_addc_u32 s17, s15, -1
	s_cmp_eq_u32 s64, 28
	s_cselect_b32 s19, s1, s17
	s_cselect_b32 s18, s4, s16
	s_cselect_b32 s17, s11, s21
	s_cselect_b32 s16, s13, s20
	s_and_b64 vcc, exec, s[36:37]
	s_cbranch_vccz .Lk64_trail_p1
	s_sub_u32 vcc_lo, s20, 0x80
	s_subb_u32 vcc_hi, s21, 0
	s_add_i32 m0, s23, 0x18000
	s_nop 0
	global_load_lds_dwordx4 v130, vcc
	s_add_i32 m0, s23, 0x1a000
	s_nop 0
	global_load_lds_dwordx4 v134, vcc
	s_add_u32 vcc_lo, vcc_lo, 0x20000
	s_addc_u32 vcc_hi, vcc_hi, 0
	s_add_i32 m0, s23, 0x19000
	s_nop 0
	global_load_lds_dwordx4 v130, vcc
	s_add_i32 m0, s23, 0x1b000
	s_nop 0
	global_load_lds_dwordx4 v134, vcc
	s_add_u32 vcc_lo, vcc_lo, 0x60000
	s_addc_u32 vcc_hi, vcc_hi, 0
	s_add_i32 m0, s23, 0x1c000
	s_nop 0
	global_load_lds_dwordx4 v130, vcc
	s_add_i32 m0, s23, 0x1e000
	s_nop 0
	global_load_lds_dwordx4 v134, vcc
	s_add_u32 vcc_lo, vcc_lo, 0x20000
	s_addc_u32 vcc_hi, vcc_hi, 0
	s_add_i32 m0, s23, 0x1d000
	s_nop 0
	global_load_lds_dwordx4 v130, vcc
	s_add_i32 m0, s23, 0x1f000
	s_nop 0
	global_load_lds_dwordx4 v134, vcc
	ds_read_b128 v[148:151], v168 offset:0
	ds_read_b128 v[152:155], v168 offset:1024
	ds_read_b128 v[156:159], v168 offset:2048
	ds_read_b128 v[172:175], v168 offset:3072
	ds_read_b128 v[176:179], v169 offset:0
	ds_read_b128 v[180:183], v169 offset:1024
	ds_read_b128 v[184:187], v169 offset:2048
	ds_read_b128 v[188:191], v169 offset:3072
	ds_read_b128 v[192:195], v170 offset:0
	ds_read_b128 v[196:199], v170 offset:1024
	ds_read_b128 v[200:203], v170 offset:2048
	ds_read_b128 v[204:207], v170 offset:3072
	ds_read_b128 v[208:211], v170 offset:4096
	ds_read_b128 v[212:215], v170 offset:5120
	ds_read_b128 v[216:219], v170 offset:6144
	ds_read_b128 v[220:223], v170 offset:7168
	ds_read_b128 v[142:145], v170 offset:16384
	ds_read_b128 v[224:227], v170 offset:17408
	ds_read_b128 v[228:231], v170 offset:18432
	ds_read_b128 v[232:235], v170 offset:19456
	ds_read_b128 v[236:239], v170 offset:20480
	ds_read_b128 v[240:243], v170 offset:21504
	ds_read_b128 v[244:247], v170 offset:22528
	ds_read_b128 v[248:251], v170 offset:23552
	s_nop 15
	s_nop 15
	s_waitcnt lgkmcnt(0)
	s_barrier
	s_cmp_eq_i32 s64, -2
	s_cbranch_scc1 .Lk64_z_p1_l
	s_setprio 1
	v_mfma_f32_16x16x32_bf16 v[124:127], v[148:151], v[192:195], v[124:127]
	v_mfma_f32_16x16x32_bf16 v[120:123], v[156:159], v[192:195], v[120:123]
	v_mfma_f32_16x16x32_bf16 v[116:119], v[148:151], v[200:203], v[116:119]
	v_mfma_f32_16x16x32_bf16 v[112:115], v[156:159], v[200:203], v[112:115]
	v_mfma_f32_16x16x32_bf16 v[100:103], v[148:151], v[208:211], v[100:103]
	v_mfma_f32_16x16x32_bf16 v[96:99], v[156:159], v[208:211], v[96:99]
	v_mfma_f32_16x16x32_bf16 v[84:87], v[148:151], v[216:219], v[84:87]
	v_mfma_f32_16x16x32_bf16 v[80:83], v[156:159], v[216:219], v[80:83]
	v_mfma_f32_16x16x32_bf16 v[124:127], v[152:155], v[196:199], v[124:127]
	v_mfma_f32_16x16x32_bf16 v[120:123], v[172:175], v[196:199], v[120:123]
	v_mfma_f32_16x16x32_bf16 v[116:119], v[152:155], v[204:207], v[116:119]
	v_mfma_f32_16x16x32_bf16 v[112:115], v[172:175], v[204:207], v[112:115]
	v_mfma_f32_16x16x32_bf16 v[100:103], v[152:155], v[212:215], v[100:103]
	v_mfma_f32_16x16x32_bf16 v[96:99], v[172:175], v[212:215], v[96:99]
	v_mfma_f32_16x16x32_bf16 v[84:87], v[152:155], v[220:223], v[84:87]
	v_mfma_f32_16x16x32_bf16 v[80:83], v[172:175], v[220:223], v[80:83]
	s_setprio 0
	s_setprio 1
	v_mfma_f32_16x16x32_bf16 v[108:111], v[176:179], v[192:195], v[108:111]
	v_mfma_f32_16x16x32_bf16 v[104:107], v[184:187], v[192:195], v[104:107]
	v_mfma_f32_16x16x32_bf16 v[92:95], v[176:179], v[200:203], v[92:95]
	v_mfma_f32_16x16x32_bf16 v[88:91], v[184:187], v[200:203], v[88:91]
	v_mfma_f32_16x16x32_bf16 v[76:79], v[176:179], v[208:211], v[76:79]
	v_mfma_f32_16x16x32_bf16 v[72:75], v[184:187], v[208:211], v[72:75]
	v_mfma_f32_16x16x32_bf16 v[68:71], v[176:179], v[216:219], v[68:71]
	v_mfma_f32_16x16x32_bf16 v[64:67], v[184:187], v[216:219], v[64:67]
	v_mfma_f32_16x16x32_bf16 v[108:111], v[180:183], v[196:199], v[108:111]
	v_mfma_f32_16x16x32_bf16 v[104:107], v[188:191], v[196:199], v[104:107]
	v_mfma_f32_16x16x32_bf16 v[92:95], v[180:183], v[204:207], v[92:95]
	v_mfma_f32_16x16x32_bf16 v[88:91], v[188:191], v[204:207], v[88:91]
	v_mfma_f32_16x16x32_bf16 v[76:79], v[180:183], v[212:215], v[76:79]
	v_mfma_f32_16x16x32_bf16 v[72:75], v[188:191], v[212:215], v[72:75]
	v_mfma_f32_16x16x32_bf16 v[68:71], v[180:183], v[220:223], v[68:71]
	v_mfma_f32_16x16x32_bf16 v[64:67], v[188:191], v[220:223], v[64:67]
	s_setprio 0
	s_setprio 1
	v_mfma_f32_16x16x32_bf16 v[60:63], v[148:151], v[142:145], v[60:63]
	v_mfma_f32_16x16x32_bf16 v[56:59], v[156:159], v[142:145], v[56:59]
	v_mfma_f32_16x16x32_bf16 v[52:55], v[148:151], v[228:231], v[52:55]
	v_mfma_f32_16x16x32_bf16 v[48:51], v[156:159], v[228:231], v[48:51]
	v_mfma_f32_16x16x32_bf16 v[36:39], v[148:151], v[236:239], v[36:39]
	v_mfma_f32_16x16x32_bf16 v[32:35], v[156:159], v[236:239], v[32:35]
	v_mfma_f32_16x16x32_bf16 v[20:23], v[148:151], v[244:247], v[20:23]
	v_mfma_f32_16x16x32_bf16 v[16:19], v[156:159], v[244:247], v[16:19]
	v_mfma_f32_16x16x32_bf16 v[60:63], v[152:155], v[224:227], v[60:63]
	v_mfma_f32_16x16x32_bf16 v[56:59], v[172:175], v[224:227], v[56:59]
	v_mfma_f32_16x16x32_bf16 v[52:55], v[152:155], v[232:235], v[52:55]
	v_mfma_f32_16x16x32_bf16 v[48:51], v[172:175], v[232:235], v[48:51]
	v_mfma_f32_16x16x32_bf16 v[36:39], v[152:155], v[240:243], v[36:39]
	v_mfma_f32_16x16x32_bf16 v[32:35], v[172:175], v[240:243], v[32:35]
	v_mfma_f32_16x16x32_bf16 v[20:23], v[152:155], v[248:251], v[20:23]
	v_mfma_f32_16x16x32_bf16 v[16:19], v[172:175], v[248:251], v[16:19]
	s_setprio 0
	s_setprio 1
	v_mfma_f32_16x16x32_bf16 v[44:47], v[176:179], v[142:145], v[44:47]
	v_mfma_f32_16x16x32_bf16 v[40:43], v[184:187], v[142:145], v[40:43]
	v_mfma_f32_16x16x32_bf16 v[28:31], v[176:179], v[228:231], v[28:31]
	v_mfma_f32_16x16x32_bf16 v[24:27], v[184:187], v[228:231], v[24:27]
	v_mfma_f32_16x16x32_bf16 v[12:15], v[176:179], v[236:239], v[12:15]
	v_mfma_f32_16x16x32_bf16 v[8:11], v[184:187], v[236:239], v[8:11]
	v_mfma_f32_16x16x32_bf16 v[4:7], v[176:179], v[244:247], v[4:7]
	v_mfma_f32_16x16x32_bf16 v[0:3], v[184:187], v[244:247], v[0:3]
	v_mfma_f32_16x16x32_bf16 v[44:47], v[180:183], v[224:227], v[44:47]
	v_mfma_f32_16x16x32_bf16 v[40:43], v[188:191], v[224:227], v[40:43]
	v_mfma_f32_16x16x32_bf16 v[28:31], v[180:183], v[232:235], v[28:31]
	v_mfma_f32_16x16x32_bf16 v[24:27], v[188:191], v[232:235], v[24:27]
	v_mfma_f32_16x16x32_bf16 v[12:15], v[180:183], v[240:243], v[12:15]
	v_mfma_f32_16x16x32_bf16 v[8:11], v[188:191], v[240:243], v[8:11]
	v_mfma_f32_16x16x32_bf16 v[4:7], v[180:183], v[248:251], v[4:7]
	v_mfma_f32_16x16x32_bf16 v[0:3], v[188:191], v[248:251], v[0:3]
	s_setprio 0
.Lk64_zj_p1_l:
	s_waitcnt vmcnt(0)
	s_barrier
	s_add_u32 vcc_lo, s16, 0x0
	s_addc_u32 vcc_hi, s17, 0
	s_add_i32 m0, s23, 0x10000
	s_nop 0
	global_load_lds_dwordx4 v130, vcc
	s_add_i32 m0, s23, 0x12000
	s_nop 0
	global_load_lds_dwordx4 v134, vcc
	s_add_u32 vcc_lo, vcc_lo, 0x20000
	s_addc_u32 vcc_hi, vcc_hi, 0
	s_add_i32 m0, s23, 0x11000
	s_nop 0
	global_load_lds_dwordx4 v130, vcc
	s_add_i32 m0, s23, 0x13000
	s_nop 0
	global_load_lds_dwordx4 v134, vcc
	s_add_u32 vcc_lo, vcc_lo, 0x60000
	s_addc_u32 vcc_hi, vcc_hi, 0
	s_add_i32 m0, s23, 0x14000
	s_nop 0
	global_load_lds_dwordx4 v130, vcc
	s_add_i32 m0, s23, 0x16000
	s_nop 0
	global_load_lds_dwordx4 v134, vcc
	s_add_u32 vcc_lo, vcc_lo, 0x20000
	s_addc_u32 vcc_hi, vcc_hi, 0
	s_add_i32 m0, s23, 0x15000
	s_nop 0
	global_load_lds_dwordx4 v130, vcc
	s_add_i32 m0, s23, 0x17000
	s_nop 0
	global_load_lds_dwordx4 v134, vcc
	ds_read_b128 v[148:151], v168 offset:32768
	ds_read_b128 v[152:155], v168 offset:33792
	ds_read_b128 v[156:159], v168 offset:34816
	ds_read_b128 v[172:175], v168 offset:35840
	ds_read_b128 v[176:179], v169 offset:32768
	ds_read_b128 v[180:183], v169 offset:33792
	ds_read_b128 v[184:187], v169 offset:34816
	ds_read_b128 v[188:191], v169 offset:35840
	ds_read_b128 v[192:195], v170 offset:32768
	ds_read_b128 v[196:199], v170 offset:33792
	ds_read_b128 v[200:203], v170 offset:34816
	ds_read_b128 v[204:207], v170 offset:35840
	ds_read_b128 v[208:211], v170 offset:36864
	ds_read_b128 v[212:215], v170 offset:37888
	ds_read_b128 v[216:219], v170 offset:38912
	ds_read_b128 v[220:223], v170 offset:39936
	ds_read_b128 v[142:145], v170 offset:49152
	ds_read_b128 v[224:227], v170 offset:50176
	ds_read_b128 v[228:231], v170 offset:51200
	ds_read_b128 v[232:235], v170 offset:52224
	ds_read_b128 v[236:239], v170 offset:53248
	ds_read_b128 v[240:243], v170 offset:54272
	ds_read_b128 v[244:247], v170 offset:55296
	ds_read_b128 v[248:251], v170 offset:56320
	s_nop 15
	s_nop 15
	s_waitcnt lgkmcnt(0)
	s_barrier
	s_setprio 1
	v_mfma_f32_16x16x32_bf16 v[124:127], v[148:151], v[192:195], v[124:127]
	v_mfma_f32_16x16x32_bf16 v[120:123], v[156:159], v[192:195], v[120:123]
	v_mfma_f32_16x16x32_bf16 v[116:119], v[148:151], v[200:203], v[116:119]
	v_mfma_f32_16x16x32_bf16 v[112:115], v[156:159], v[200:203], v[112:115]
	v_mfma_f32_16x16x32_bf16 v[100:103], v[148:151], v[208:211], v[100:103]
	v_mfma_f32_16x16x32_bf16 v[96:99], v[156:159], v[208:211], v[96:99]
	v_mfma_f32_16x16x32_bf16 v[84:87], v[148:151], v[216:219], v[84:87]
	v_mfma_f32_16x16x32_bf16 v[80:83], v[156:159], v[216:219], v[80:83]
	v_mfma_f32_16x16x32_bf16 v[124:127], v[152:155], v[196:199], v[124:127]
	v_mfma_f32_16x16x32_bf16 v[120:123], v[172:175], v[196:199], v[120:123]
	v_mfma_f32_16x16x32_bf16 v[116:119], v[152:155], v[204:207], v[116:119]
	v_mfma_f32_16x16x32_bf16 v[112:115], v[172:175], v[204:207], v[112:115]
	v_mfma_f32_16x16x32_bf16 v[100:103], v[152:155], v[212:215], v[100:103]
	v_mfma_f32_16x16x32_bf16 v[96:99], v[172:175], v[212:215], v[96:99]
	v_mfma_f32_16x16x32_bf16 v[84:87], v[152:155], v[220:223], v[84:87]
	v_mfma_f32_16x16x32_bf16 v[80:83], v[172:175], v[220:223], v[80:83]
	s_setprio 0
	s_setprio 1
	v_mfma_f32_16x16x32_bf16 v[108:111], v[176:179], v[192:195], v[108:111]
	v_mfma_f32_16x16x32_bf16 v[104:107], v[184:187], v[192:195], v[104:107]
	v_mfma_f32_16x16x32_bf16 v[92:95], v[176:179], v[200:203], v[92:95]
	v_mfma_f32_16x16x32_bf16 v[88:91], v[184:187], v[200:203], v[88:91]
	v_mfma_f32_16x16x32_bf16 v[76:79], v[176:179], v[208:211], v[76:79]
	v_mfma_f32_16x16x32_bf16 v[72:75], v[184:187], v[208:211], v[72:75]
	v_mfma_f32_16x16x32_bf16 v[68:71], v[176:179], v[216:219], v[68:71]
	v_mfma_f32_16x16x32_bf16 v[64:67], v[184:187], v[216:219], v[64:67]
	v_mfma_f32_16x16x32_bf16 v[108:111], v[180:183], v[196:199], v[108:111]
	v_mfma_f32_16x16x32_bf16 v[104:107], v[188:191], v[196:199], v[104:107]
	v_mfma_f32_16x16x32_bf16 v[92:95], v[180:183], v[204:207], v[92:95]
	v_mfma_f32_16x16x32_bf16 v[88:91], v[188:191], v[204:207], v[88:91]
	v_mfma_f32_16x16x32_bf16 v[76:79], v[180:183], v[212:215], v[76:79]
	v_mfma_f32_16x16x32_bf16 v[72:75], v[188:191], v[212:215], v[72:75]
	v_mfma_f32_16x16x32_bf16 v[68:71], v[180:183], v[220:223], v[68:71]
	v_mfma_f32_16x16x32_bf16 v[64:67], v[188:191], v[220:223], v[64:67]
	s_setprio 0
	s_setprio 1
	v_mfma_f32_16x16x32_bf16 v[60:63], v[148:151], v[142:145], v[60:63]
	v_mfma_f32_16x16x32_bf16 v[56:59], v[156:159], v[142:145], v[56:59]
	v_mfma_f32_16x16x32_bf16 v[52:55], v[148:151], v[228:231], v[52:55]
	v_mfma_f32_16x16x32_bf16 v[48:51], v[156:159], v[228:231], v[48:51]
	v_mfma_f32_16x16x32_bf16 v[36:39], v[148:151], v[236:239], v[36:39]
	v_mfma_f32_16x16x32_bf16 v[32:35], v[156:159], v[236:239], v[32:35]
	v_mfma_f32_16x16x32_bf16 v[20:23], v[148:151], v[244:247], v[20:23]
	v_mfma_f32_16x16x32_bf16 v[16:19], v[156:159], v[244:247], v[16:19]
	v_mfma_f32_16x16x32_bf16 v[60:63], v[152:155], v[224:227], v[60:63]
	v_mfma_f32_16x16x32_bf16 v[56:59], v[172:175], v[224:227], v[56:59]
	v_mfma_f32_16x16x32_bf16 v[52:55], v[152:155], v[232:235], v[52:55]
	v_mfma_f32_16x16x32_bf16 v[48:51], v[172:175], v[232:235], v[48:51]
	v_mfma_f32_16x16x32_bf16 v[36:39], v[152:155], v[240:243], v[36:39]
	v_mfma_f32_16x16x32_bf16 v[32:35], v[172:175], v[240:243], v[32:35]
	v_mfma_f32_16x16x32_bf16 v[20:23], v[152:155], v[248:251], v[20:23]
	v_mfma_f32_16x16x32_bf16 v[16:19], v[172:175], v[248:251], v[16:19]
	s_setprio 0
	s_setprio 1
	v_mfma_f32_16x16x32_bf16 v[44:47], v[176:179], v[142:145], v[44:47]
	v_mfma_f32_16x16x32_bf16 v[40:43], v[184:187], v[142:145], v[40:43]
	v_mfma_f32_16x16x32_bf16 v[28:31], v[176:179], v[228:231], v[28:31]
	v_mfma_f32_16x16x32_bf16 v[24:27], v[184:187], v[228:231], v[24:27]
	v_mfma_f32_16x16x32_bf16 v[12:15], v[176:179], v[236:239], v[12:15]
	v_mfma_f32_16x16x32_bf16 v[8:11], v[184:187], v[236:239], v[8:11]
	v_mfma_f32_16x16x32_bf16 v[4:7], v[176:179], v[244:247], v[4:7]
	v_mfma_f32_16x16x32_bf16 v[0:3], v[184:187], v[244:247], v[0:3]
	v_mfma_f32_16x16x32_bf16 v[44:47], v[180:183], v[224:227], v[44:47]
	v_mfma_f32_16x16x32_bf16 v[40:43], v[188:191], v[224:227], v[40:43]
	v_mfma_f32_16x16x32_bf16 v[28:31], v[180:183], v[232:235], v[28:31]
	v_mfma_f32_16x16x32_bf16 v[24:27], v[188:191], v[232:235], v[24:27]
	v_mfma_f32_16x16x32_bf16 v[12:15], v[180:183], v[240:243], v[12:15]
	v_mfma_f32_16x16x32_bf16 v[8:11], v[188:191], v[240:243], v[8:11]
	v_mfma_f32_16x16x32_bf16 v[4:7], v[180:183], v[248:251], v[4:7]
	v_mfma_f32_16x16x32_bf16 v[0:3], v[188:191], v[248:251], v[0:3]
	s_setprio 0
	s_waitcnt vmcnt(0)
	s_barrier
	s_add_i32 s64, s64, 2
	s_add_u32 s14, s14, 0x100
	s_addc_u32 s15, s15, 0
	s_add_u32 s20, s20, 0x100
	s_addc_u32 s21, s21, 0
	s_cmp_gt_u32 s64, 29
	s_cbranch_scc0 .LBB0_165
	s_branch .Lk64_done_p1
.Lk64_z_p1_l:
	s_setprio 1
	v_mfma_f32_16x16x32_bf16 v[124:127], v[148:151], v[192:195], 0
	v_mfma_f32_16x16x32_bf16 v[120:123], v[156:159], v[192:195], 0
	v_mfma_f32_16x16x32_bf16 v[116:119], v[148:151], v[200:203], 0
	v_mfma_f32_16x16x32_bf16 v[112:115], v[156:159], v[200:203], 0
	v_mfma_f32_16x16x32_bf16 v[100:103], v[148:151], v[208:211], 0
	v_mfma_f32_16x16x32_bf16 v[96:99], v[156:159], v[208:211], 0
	v_mfma_f32_16x16x32_bf16 v[84:87], v[148:151], v[216:219], 0
	v_mfma_f32_16x16x32_bf16 v[80:83], v[156:159], v[216:219], 0
	v_mfma_f32_16x16x32_bf16 v[124:127], v[152:155], v[196:199], v[124:127]
	v_mfma_f32_16x16x32_bf16 v[120:123], v[172:175], v[196:199], v[120:123]
	v_mfma_f32_16x16x32_bf16 v[116:119], v[152:155], v[204:207], v[116:119]
	v_mfma_f32_16x16x32_bf16 v[112:115], v[172:175], v[204:207], v[112:115]
	v_mfma_f32_16x16x32_bf16 v[100:103], v[152:155], v[212:215], v[100:103]
	v_mfma_f32_16x16x32_bf16 v[96:99], v[172:175], v[212:215], v[96:99]
	v_mfma_f32_16x16x32_bf16 v[84:87], v[152:155], v[220:223], v[84:87]
	v_mfma_f32_16x16x32_bf16 v[80:83], v[172:175], v[220:223], v[80:83]
	s_setprio 0
	s_setprio 1
	v_mfma_f32_16x16x32_bf16 v[108:111], v[176:179], v[192:195], 0
	v_mfma_f32_16x16x32_bf16 v[104:107], v[184:187], v[192:195], 0
	v_mfma_f32_16x16x32_bf16 v[92:95], v[176:179], v[200:203], 0
	v_mfma_f32_16x16x32_bf16 v[88:91], v[184:187], v[200:203], 0
	v_mfma_f32_16x16x32_bf16 v[76:79], v[176:179], v[208:211], 0
	v_mfma_f32_16x16x32_bf16 v[72:75], v[184:187], v[208:211], 0
	v_mfma_f32_16x16x32_bf16 v[68:71], v[176:179], v[216:219], 0
	v_mfma_f32_16x16x32_bf16 v[64:67], v[184:187], v[216:219], 0
	v_mfma_f32_16x16x32_bf16 v[108:111], v[180:183], v[196:199], v[108:111]
	v_mfma_f32_16x16x32_bf16 v[104:107], v[188:191], v[196:199], v[104:107]
	v_mfma_f32_16x16x32_bf16 v[92:95], v[180:183], v[204:207], v[92:95]
	v_mfma_f32_16x16x32_bf16 v[88:91], v[188:191], v[204:207], v[88:91]
	v_mfma_f32_16x16x32_bf16 v[76:79], v[180:183], v[212:215], v[76:79]
	v_mfma_f32_16x16x32_bf16 v[72:75], v[188:191], v[212:215], v[72:75]
	v_mfma_f32_16x16x32_bf16 v[68:71], v[180:183], v[220:223], v[68:71]
	v_mfma_f32_16x16x32_bf16 v[64:67], v[188:191], v[220:223], v[64:67]
	s_setprio 0
	s_setprio 1
	v_mfma_f32_16x16x32_bf16 v[60:63], v[148:151], v[142:145], 0
	v_mfma_f32_16x16x32_bf16 v[56:59], v[156:159], v[142:145], 0
	v_mfma_f32_16x16x32_bf16 v[52:55], v[148:151], v[228:231], 0
	v_mfma_f32_16x16x32_bf16 v[48:51], v[156:159], v[228:231], 0
	v_mfma_f32_16x16x32_bf16 v[36:39], v[148:151], v[236:239], 0
	v_mfma_f32_16x16x32_bf16 v[32:35], v[156:159], v[236:239], 0
	v_mfma_f32_16x16x32_bf16 v[20:23], v[148:151], v[244:247], 0
	v_mfma_f32_16x16x32_bf16 v[16:19], v[156:159], v[244:247], 0
	v_mfma_f32_16x16x32_bf16 v[60:63], v[152:155], v[224:227], v[60:63]
	v_mfma_f32_16x16x32_bf16 v[56:59], v[172:175], v[224:227], v[56:59]
	v_mfma_f32_16x16x32_bf16 v[52:55], v[152:155], v[232:235], v[52:55]
	v_mfma_f32_16x16x32_bf16 v[48:51], v[172:175], v[232:235], v[48:51]
	v_mfma_f32_16x16x32_bf16 v[36:39], v[152:155], v[240:243], v[36:39]
	v_mfma_f32_16x16x32_bf16 v[32:35], v[172:175], v[240:243], v[32:35]
	v_mfma_f32_16x16x32_bf16 v[20:23], v[152:155], v[248:251], v[20:23]
	v_mfma_f32_16x16x32_bf16 v[16:19], v[172:175], v[248:251], v[16:19]
	s_setprio 0
	s_setprio 1
	v_mfma_f32_16x16x32_bf16 v[44:47], v[176:179], v[142:145], 0
	v_mfma_f32_16x16x32_bf16 v[40:43], v[184:187], v[142:145], 0
	v_mfma_f32_16x16x32_bf16 v[28:31], v[176:179], v[228:231], 0
	v_mfma_f32_16x16x32_bf16 v[24:27], v[184:187], v[228:231], 0
	v_mfma_f32_16x16x32_bf16 v[12:15], v[176:179], v[236:239], 0
	v_mfma_f32_16x16x32_bf16 v[8:11], v[184:187], v[236:239], 0
	v_mfma_f32_16x16x32_bf16 v[4:7], v[176:179], v[244:247], 0
	v_mfma_f32_16x16x32_bf16 v[0:3], v[184:187], v[244:247], 0
	v_mfma_f32_16x16x32_bf16 v[44:47], v[180:183], v[224:227], v[44:47]
	v_mfma_f32_16x16x32_bf16 v[40:43], v[188:191], v[224:227], v[40:43]
	v_mfma_f32_16x16x32_bf16 v[28:31], v[180:183], v[232:235], v[28:31]
	v_mfma_f32_16x16x32_bf16 v[24:27], v[188:191], v[232:235], v[24:27]
	v_mfma_f32_16x16x32_bf16 v[12:15], v[180:183], v[240:243], v[12:15]
	v_mfma_f32_16x16x32_bf16 v[8:11], v[188:191], v[240:243], v[8:11]
	v_mfma_f32_16x16x32_bf16 v[4:7], v[180:183], v[248:251], v[4:7]
	v_mfma_f32_16x16x32_bf16 v[0:3], v[188:191], v[248:251], v[0:3]
	s_setprio 0
	s_branch .Lk64_zj_p1_l
.Lk64_trail_p1:
	s_sub_u32 vcc_lo, s14, 0x80000
	s_subb_u32 vcc_hi, s15, 0
	s_add_i32 m0, s23, 0xa000
	s_nop 0
	global_load_lds_dwordx4 v132, vcc
	s_add_u32 vcc_lo, vcc_lo, 0x20000
	s_addc_u32 vcc_hi, vcc_hi, 0
	s_add_i32 m0, s23, 0x9000
	s_nop 0
	global_load_lds_dwordx4 v128, vcc
	s_add_u32 vcc_lo, vcc_lo, 0x60000
	s_addc_u32 vcc_hi, vcc_hi, 0
	s_add_i32 m0, s23, 0xe000
	s_nop 0
	global_load_lds_dwordx4 v132, vcc
	s_add_u32 vcc_lo, vcc_lo, 0x20000
	s_addc_u32 vcc_hi, vcc_hi, 0
	s_add_i32 m0, s23, 0xd000
	s_nop 0
	global_load_lds_dwordx4 v128, vcc
	s_add_u32 vcc_lo, s18, 0x0
	s_addc_u32 vcc_hi, s19, 0
	s_mov_b32 m0, s23
	s_nop 0
	global_load_lds_dwordx4 v128, vcc
	s_sub_u32 vcc_lo, vcc_lo, 0x20000
	s_subb_u32 vcc_hi, vcc_hi, 0
	s_sub_i32 m0, s23, 0x1000
	s_nop 0
	global_load_lds_dwordx4 v128, vcc
	s_add_u32 vcc_lo, vcc_lo, 0xa0000
	s_addc_u32 vcc_hi, vcc_hi, 0
	s_add_i32 m0, s23, 0x4000
	s_nop 0
	global_load_lds_dwordx4 v128, vcc
	s_sub_u32 vcc_lo, vcc_lo, 0x20000
	s_subb_u32 vcc_hi, vcc_hi, 0
	s_add_i32 m0, s23, 0x3000
	s_nop 0
	global_load_lds_dwordx4 v128, vcc
	ds_read_b128 v[148:151], v168 offset:0
	ds_read_b128 v[152:155], v168 offset:1024
	ds_read_b128 v[156:159], v168 offset:2048
	ds_read_b128 v[172:175], v168 offset:3072
	ds_read_b128 v[176:179], v169 offset:0
	ds_read_b128 v[180:183], v169 offset:1024
	ds_read_b128 v[184:187], v169 offset:2048
	ds_read_b128 v[188:191], v169 offset:3072
	ds_read_b128 v[192:195], v170 offset:0
	ds_read_b128 v[196:199], v170 offset:1024
	ds_read_b128 v[200:203], v170 offset:2048
	ds_read_b128 v[204:207], v170 offset:3072
	ds_read_b128 v[208:211], v170 offset:4096
	ds_read_b128 v[212:215], v170 offset:5120
	ds_read_b128 v[216:219], v170 offset:6144
	ds_read_b128 v[220:223], v170 offset:7168
	ds_read_b128 v[142:145], v170 offset:16384
	ds_read_b128 v[224:227], v170 offset:17408
	ds_read_b128 v[228:231], v170 offset:18432
	ds_read_b128 v[232:235], v170 offset:19456
	ds_read_b128 v[236:239], v170 offset:20480
	ds_read_b128 v[240:243], v170 offset:21504
	ds_read_b128 v[244:247], v170 offset:22528
	ds_read_b128 v[248:251], v170 offset:23552
	s_nop 15
	s_nop 15
	s_waitcnt lgkmcnt(0)
	s_barrier
	s_cmp_eq_i32 s64, -2
	s_cbranch_scc1 .Lk64_z_p1_t
	s_setprio 1
	v_mfma_f32_16x16x32_bf16 v[124:127], v[148:151], v[192:195], v[124:127]
	v_mfma_f32_16x16x32_bf16 v[120:123], v[156:159], v[192:195], v[120:123]
	v_mfma_f32_16x16x32_bf16 v[116:119], v[148:151], v[200:203], v[116:119]
	v_mfma_f32_16x16x32_bf16 v[112:115], v[156:159], v[200:203], v[112:115]
	v_mfma_f32_16x16x32_bf16 v[100:103], v[148:151], v[208:211], v[100:103]
	v_mfma_f32_16x16x32_bf16 v[96:99], v[156:159], v[208:211], v[96:99]
	v_mfma_f32_16x16x32_bf16 v[84:87], v[148:151], v[216:219], v[84:87]
	v_mfma_f32_16x16x32_bf16 v[80:83], v[156:159], v[216:219], v[80:83]
	v_mfma_f32_16x16x32_bf16 v[124:127], v[152:155], v[196:199], v[124:127]
	v_mfma_f32_16x16x32_bf16 v[120:123], v[172:175], v[196:199], v[120:123]
	v_mfma_f32_16x16x32_bf16 v[116:119], v[152:155], v[204:207], v[116:119]
	v_mfma_f32_16x16x32_bf16 v[112:115], v[172:175], v[204:207], v[112:115]
	v_mfma_f32_16x16x32_bf16 v[100:103], v[152:155], v[212:215], v[100:103]
	v_mfma_f32_16x16x32_bf16 v[96:99], v[172:175], v[212:215], v[96:99]
	v_mfma_f32_16x16x32_bf16 v[84:87], v[152:155], v[220:223], v[84:87]
	v_mfma_f32_16x16x32_bf16 v[80:83], v[172:175], v[220:223], v[80:83]
	s_setprio 0
	s_setprio 1
	v_mfma_f32_16x16x32_bf16 v[108:111], v[176:179], v[192:195], v[108:111]
	v_mfma_f32_16x16x32_bf16 v[104:107], v[184:187], v[192:195], v[104:107]
	v_mfma_f32_16x16x32_bf16 v[92:95], v[176:179], v[200:203], v[92:95]
	v_mfma_f32_16x16x32_bf16 v[88:91], v[184:187], v[200:203], v[88:91]
	v_mfma_f32_16x16x32_bf16 v[76:79], v[176:179], v[208:211], v[76:79]
	v_mfma_f32_16x16x32_bf16 v[72:75], v[184:187], v[208:211], v[72:75]
	v_mfma_f32_16x16x32_bf16 v[68:71], v[176:179], v[216:219], v[68:71]
	v_mfma_f32_16x16x32_bf16 v[64:67], v[184:187], v[216:219], v[64:67]
	v_mfma_f32_16x16x32_bf16 v[108:111], v[180:183], v[196:199], v[108:111]
	v_mfma_f32_16x16x32_bf16 v[104:107], v[188:191], v[196:199], v[104:107]
	v_mfma_f32_16x16x32_bf16 v[92:95], v[180:183], v[204:207], v[92:95]
	v_mfma_f32_16x16x32_bf16 v[88:91], v[188:191], v[204:207], v[88:91]
	v_mfma_f32_16x16x32_bf16 v[76:79], v[180:183], v[212:215], v[76:79]
	v_mfma_f32_16x16x32_bf16 v[72:75], v[188:191], v[212:215], v[72:75]
	v_mfma_f32_16x16x32_bf16 v[68:71], v[180:183], v[220:223], v[68:71]
	v_mfma_f32_16x16x32_bf16 v[64:67], v[188:191], v[220:223], v[64:67]
	s_setprio 0
	s_setprio 1
	v_mfma_f32_16x16x32_bf16 v[60:63], v[148:151], v[142:145], v[60:63]
	v_mfma_f32_16x16x32_bf16 v[56:59], v[156:159], v[142:145], v[56:59]
	v_mfma_f32_16x16x32_bf16 v[52:55], v[148:151], v[228:231], v[52:55]
	v_mfma_f32_16x16x32_bf16 v[48:51], v[156:159], v[228:231], v[48:51]
	v_mfma_f32_16x16x32_bf16 v[36:39], v[148:151], v[236:239], v[36:39]
	v_mfma_f32_16x16x32_bf16 v[32:35], v[156:159], v[236:239], v[32:35]
	v_mfma_f32_16x16x32_bf16 v[20:23], v[148:151], v[244:247], v[20:23]
	v_mfma_f32_16x16x32_bf16 v[16:19], v[156:159], v[244:247], v[16:19]
	v_mfma_f32_16x16x32_bf16 v[60:63], v[152:155], v[224:227], v[60:63]
	v_mfma_f32_16x16x32_bf16 v[56:59], v[172:175], v[224:227], v[56:59]
	v_mfma_f32_16x16x32_bf16 v[52:55], v[152:155], v[232:235], v[52:55]
	v_mfma_f32_16x16x32_bf16 v[48:51], v[172:175], v[232:235], v[48:51]
	v_mfma_f32_16x16x32_bf16 v[36:39], v[152:155], v[240:243], v[36:39]
	v_mfma_f32_16x16x32_bf16 v[32:35], v[172:175], v[240:243], v[32:35]
	v_mfma_f32_16x16x32_bf16 v[20:23], v[152:155], v[248:251], v[20:23]
	v_mfma_f32_16x16x32_bf16 v[16:19], v[172:175], v[248:251], v[16:19]
	s_setprio 0
	s_setprio 1
	v_mfma_f32_16x16x32_bf16 v[44:47], v[176:179], v[142:145], v[44:47]
	v_mfma_f32_16x16x32_bf16 v[40:43], v[184:187], v[142:145], v[40:43]
	v_mfma_f32_16x16x32_bf16 v[28:31], v[176:179], v[228:231], v[28:31]
	v_mfma_f32_16x16x32_bf16 v[24:27], v[184:187], v[228:231], v[24:27]
	v_mfma_f32_16x16x32_bf16 v[12:15], v[176:179], v[236:239], v[12:15]
	v_mfma_f32_16x16x32_bf16 v[8:11], v[184:187], v[236:239], v[8:11]
	v_mfma_f32_16x16x32_bf16 v[4:7], v[176:179], v[244:247], v[4:7]
	v_mfma_f32_16x16x32_bf16 v[0:3], v[184:187], v[244:247], v[0:3]
	v_mfma_f32_16x16x32_bf16 v[44:47], v[180:183], v[224:227], v[44:47]
	v_mfma_f32_16x16x32_bf16 v[40:43], v[188:191], v[224:227], v[40:43]
	v_mfma_f32_16x16x32_bf16 v[28:31], v[180:183], v[232:235], v[28:31]
	v_mfma_f32_16x16x32_bf16 v[24:27], v[188:191], v[232:235], v[24:27]
	v_mfma_f32_16x16x32_bf16 v[12:15], v[180:183], v[240:243], v[12:15]
	v_mfma_f32_16x16x32_bf16 v[8:11], v[188:191], v[240:243], v[8:11]
	v_mfma_f32_16x16x32_bf16 v[4:7], v[180:183], v[248:251], v[4:7]
	v_mfma_f32_16x16x32_bf16 v[0:3], v[188:191], v[248:251], v[0:3]
	s_setprio 0
.Lk64_zj_p1_t:
	s_waitcnt vmcnt(0)
	s_barrier
	s_add_u32 vcc_lo, s18, 0x0
	s_addc_u32 vcc_hi, s19, 0
	s_add_i32 m0, s23, 0x2000
	s_nop 0
	global_load_lds_dwordx4 v132, vcc
	s_add_u32 vcc_lo, vcc_lo, 0x20000
	s_addc_u32 vcc_hi, vcc_hi, 0
	s_add_i32 m0, s23, 0x1000
	s_nop 0
	global_load_lds_dwordx4 v128, vcc
	s_add_u32 vcc_lo, vcc_lo, 0x60000
	s_addc_u32 vcc_hi, vcc_hi, 0
	s_add_i32 m0, s23, 0x6000
	s_nop 0
	global_load_lds_dwordx4 v132, vcc
	s_add_u32 vcc_lo, vcc_lo, 0x20000
	s_addc_u32 vcc_hi, vcc_hi, 0
	s_add_i32 m0, s23, 0x5000
	s_nop 0
	global_load_lds_dwordx4 v128, vcc
	s_add_u32 vcc_lo, s18, 0x80
	s_addc_u32 vcc_hi, s19, 0
	s_add_i32 m0, s23, 0x8000
	s_nop 0
	global_load_lds_dwordx4 v128, vcc
	s_sub_u32 vcc_lo, vcc_lo, 0x20000
	s_subb_u32 vcc_hi, vcc_hi, 0
	s_add_i32 m0, s23, 0x7000
	s_nop 0
	global_load_lds_dwordx4 v128, vcc
	s_add_u32 vcc_lo, vcc_lo, 0xa0000
	s_addc_u32 vcc_hi, vcc_hi, 0
	s_add_i32 m0, s23, 0xc000
	s_nop 0
	global_load_lds_dwordx4 v128, vcc
	s_sub_u32 vcc_lo, vcc_lo, 0x20000
	s_subb_u32 vcc_hi, vcc_hi, 0
	s_add_i32 m0, s23, 0xb000
	s_nop 0
	global_load_lds_dwordx4 v128, vcc
	ds_read_b128 v[148:151], v168 offset:32768
	ds_read_b128 v[152:155], v168 offset:33792
	ds_read_b128 v[156:159], v168 offset:34816
	ds_read_b128 v[172:175], v168 offset:35840
	ds_read_b128 v[176:179], v169 offset:32768
	ds_read_b128 v[180:183], v169 offset:33792
	ds_read_b128 v[184:187], v169 offset:34816
	ds_read_b128 v[188:191], v169 offset:35840
	ds_read_b128 v[192:195], v170 offset:32768
	ds_read_b128 v[196:199], v170 offset:33792
	ds_read_b128 v[200:203], v170 offset:34816
	ds_read_b128 v[204:207], v170 offset:35840
	ds_read_b128 v[208:211], v170 offset:36864
	ds_read_b128 v[212:215], v170 offset:37888
	ds_read_b128 v[216:219], v170 offset:38912
	ds_read_b128 v[220:223], v170 offset:39936
	ds_read_b128 v[142:145], v170 offset:49152
	ds_read_b128 v[224:227], v170 offset:50176
	ds_read_b128 v[228:231], v170 offset:51200
	ds_read_b128 v[232:235], v170 offset:52224
	ds_read_b128 v[236:239], v170 offset:53248
	ds_read_b128 v[240:243], v170 offset:54272
	ds_read_b128 v[244:247], v170 offset:55296
	ds_read_b128 v[248:251], v170 offset:56320
	s_nop 15
	s_nop 15
	s_waitcnt lgkmcnt(0)
	s_barrier
	s_setprio 1
	v_mfma_f32_16x16x32_bf16 v[124:127], v[148:151], v[192:195], v[124:127]
	v_mfma_f32_16x16x32_bf16 v[120:123], v[156:159], v[192:195], v[120:123]
	v_mfma_f32_16x16x32_bf16 v[116:119], v[148:151], v[200:203], v[116:119]
	v_mfma_f32_16x16x32_bf16 v[112:115], v[156:159], v[200:203], v[112:115]
	v_mfma_f32_16x16x32_bf16 v[100:103], v[148:151], v[208:211], v[100:103]
	v_mfma_f32_16x16x32_bf16 v[96:99], v[156:159], v[208:211], v[96:99]
	v_mfma_f32_16x16x32_bf16 v[84:87], v[148:151], v[216:219], v[84:87]
	v_mfma_f32_16x16x32_bf16 v[80:83], v[156:159], v[216:219], v[80:83]
	v_mfma_f32_16x16x32_bf16 v[124:127], v[152:155], v[196:199], v[124:127]
	v_mfma_f32_16x16x32_bf16 v[120:123], v[172:175], v[196:199], v[120:123]
	v_mfma_f32_16x16x32_bf16 v[116:119], v[152:155], v[204:207], v[116:119]
	v_mfma_f32_16x16x32_bf16 v[112:115], v[172:175], v[204:207], v[112:115]
	v_mfma_f32_16x16x32_bf16 v[100:103], v[152:155], v[212:215], v[100:103]
	v_mfma_f32_16x16x32_bf16 v[96:99], v[172:175], v[212:215], v[96:99]
	v_mfma_f32_16x16x32_bf16 v[84:87], v[152:155], v[220:223], v[84:87]
	v_mfma_f32_16x16x32_bf16 v[80:83], v[172:175], v[220:223], v[80:83]
	s_setprio 0
	s_setprio 1
	v_mfma_f32_16x16x32_bf16 v[108:111], v[176:179], v[192:195], v[108:111]
	v_mfma_f32_16x16x32_bf16 v[104:107], v[184:187], v[192:195], v[104:107]
	v_mfma_f32_16x16x32_bf16 v[92:95], v[176:179], v[200:203], v[92:95]
	v_mfma_f32_16x16x32_bf16 v[88:91], v[184:187], v[200:203], v[88:91]
	v_mfma_f32_16x16x32_bf16 v[76:79], v[176:179], v[208:211], v[76:79]
	v_mfma_f32_16x16x32_bf16 v[72:75], v[184:187], v[208:211], v[72:75]
	v_mfma_f32_16x16x32_bf16 v[68:71], v[176:179], v[216:219], v[68:71]
	v_mfma_f32_16x16x32_bf16 v[64:67], v[184:187], v[216:219], v[64:67]
	v_mfma_f32_16x16x32_bf16 v[108:111], v[180:183], v[196:199], v[108:111]
	v_mfma_f32_16x16x32_bf16 v[104:107], v[188:191], v[196:199], v[104:107]
	v_mfma_f32_16x16x32_bf16 v[92:95], v[180:183], v[204:207], v[92:95]
	v_mfma_f32_16x16x32_bf16 v[88:91], v[188:191], v[204:207], v[88:91]
	v_mfma_f32_16x16x32_bf16 v[76:79], v[180:183], v[212:215], v[76:79]
	v_mfma_f32_16x16x32_bf16 v[72:75], v[188:191], v[212:215], v[72:75]
	v_mfma_f32_16x16x32_bf16 v[68:71], v[180:183], v[220:223], v[68:71]
	v_mfma_f32_16x16x32_bf16 v[64:67], v[188:191], v[220:223], v[64:67]
	s_setprio 0
	s_setprio 1
	v_mfma_f32_16x16x32_bf16 v[60:63], v[148:151], v[142:145], v[60:63]
	v_mfma_f32_16x16x32_bf16 v[56:59], v[156:159], v[142:145], v[56:59]
	v_mfma_f32_16x16x32_bf16 v[52:55], v[148:151], v[228:231], v[52:55]
	v_mfma_f32_16x16x32_bf16 v[48:51], v[156:159], v[228:231], v[48:51]
	v_mfma_f32_16x16x32_bf16 v[36:39], v[148:151], v[236:239], v[36:39]
	v_mfma_f32_16x16x32_bf16 v[32:35], v[156:159], v[236:239], v[32:35]
	v_mfma_f32_16x16x32_bf16 v[20:23], v[148:151], v[244:247], v[20:23]
	v_mfma_f32_16x16x32_bf16 v[16:19], v[156:159], v[244:247], v[16:19]
	v_mfma_f32_16x16x32_bf16 v[60:63], v[152:155], v[224:227], v[60:63]
	v_mfma_f32_16x16x32_bf16 v[56:59], v[172:175], v[224:227], v[56:59]
	v_mfma_f32_16x16x32_bf16 v[52:55], v[152:155], v[232:235], v[52:55]
	v_mfma_f32_16x16x32_bf16 v[48:51], v[172:175], v[232:235], v[48:51]
	v_mfma_f32_16x16x32_bf16 v[36:39], v[152:155], v[240:243], v[36:39]
	v_mfma_f32_16x16x32_bf16 v[32:35], v[172:175], v[240:243], v[32:35]
	v_mfma_f32_16x16x32_bf16 v[20:23], v[152:155], v[248:251], v[20:23]
	v_mfma_f32_16x16x32_bf16 v[16:19], v[172:175], v[248:251], v[16:19]
	s_setprio 0
	s_setprio 1
	v_mfma_f32_16x16x32_bf16 v[44:47], v[176:179], v[142:145], v[44:47]
	v_mfma_f32_16x16x32_bf16 v[40:43], v[184:187], v[142:145], v[40:43]
	v_mfma_f32_16x16x32_bf16 v[28:31], v[176:179], v[228:231], v[28:31]
	v_mfma_f32_16x16x32_bf16 v[24:27], v[184:187], v[228:231], v[24:27]
	v_mfma_f32_16x16x32_bf16 v[12:15], v[176:179], v[236:239], v[12:15]
	v_mfma_f32_16x16x32_bf16 v[8:11], v[184:187], v[236:239], v[8:11]
	v_mfma_f32_16x16x32_bf16 v[4:7], v[176:179], v[244:247], v[4:7]
	v_mfma_f32_16x16x32_bf16 v[0:3], v[184:187], v[244:247], v[0:3]
	v_mfma_f32_16x16x32_bf16 v[44:47], v[180:183], v[224:227], v[44:47]
	v_mfma_f32_16x16x32_bf16 v[40:43], v[188:191], v[224:227], v[40:43]
	v_mfma_f32_16x16x32_bf16 v[28:31], v[180:183], v[232:235], v[28:31]
	v_mfma_f32_16x16x32_bf16 v[24:27], v[188:191], v[232:235], v[24:27]
	v_mfma_f32_16x16x32_bf16 v[12:15], v[180:183], v[240:243], v[12:15]
	v_mfma_f32_16x16x32_bf16 v[8:11], v[188:191], v[240:243], v[8:11]
	v_mfma_f32_16x16x32_bf16 v[4:7], v[180:183], v[248:251], v[4:7]
	v_mfma_f32_16x16x32_bf16 v[0:3], v[188:191], v[248:251], v[0:3]
	s_setprio 0
	s_waitcnt vmcnt(0)
	s_barrier
	s_add_i32 s64, s64, 2
	s_add_u32 s14, s14, 0x100
	s_addc_u32 s15, s15, 0
	s_add_u32 s20, s20, 0x100
	s_addc_u32 s21, s21, 0
	s_cmp_gt_u32 s64, 29
	s_cbranch_scc0 .LBB0_165
	s_branch .Lk64_done_p1

.LBB0_612:
	s_ashr_i32 s13, s12, 31
	s_lshl_b64 s[16:17], s[12:13], 19
	s_add_u32 s16, s42, s16
	s_addc_u32 s17, s43, s17
	s_and_b64 s[18:19], s[38:39], exec
	s_cselect_b32 s13, s17, s23
	s_cselect_b32 s41, s16, s22
	s_ashr_i32 s11, s10, 31
	s_lshl_b64 s[18:19], s[10:11], 19
	s_add_u32 s18, s58, s18
	s_addc_u32 s19, s59, s19
	s_and_b64 s[26:27], s[38:39], exec
	s_cselect_b32 s11, s19, s25
	s_cselect_b32 s46, s18, s24
	s_add_u32 s22, s22, 0x40080
	s_addc_u32 s23, s23, 0
	s_add_u32 s47, s24, 0x100
	s_addc_u32 s48, s25, 0
	s_mov_b32 s49, -2
.LBB0_613:
	s_add_u32 s24, s22, 0xfffc0080
	s_addc_u32 s25, s23, -1
	s_cmp_eq_u32 s49, 12
	s_cselect_b32 s27, s13, s25
	s_cselect_b32 s26, s41, s24
	s_cselect_b32 s25, s11, s48
	s_cselect_b32 s24, s46, s47
	s_and_b64 vcc, exec, s[6:7]
	s_cbranch_vccz .Lk64_trail_glu
	s_sub_u32 vcc_lo, s47, 0x80
	s_subb_u32 vcc_hi, s48, 0
	s_add_i32 m0, s28, 0x18000
	s_nop 0
	global_load_lds_dwordx4 v132, vcc
	s_add_i32 m0, s28, 0x1a000
	s_nop 0
	global_load_lds_dwordx4 v128, vcc
	s_add_u32 vcc_lo, vcc_lo, 0x10000
	s_addc_u32 vcc_hi, vcc_hi, 0
	s_add_i32 m0, s28, 0x19000
	s_nop 0
	global_load_lds_dwordx4 v132, vcc
	s_add_i32 m0, s28, 0x1b000
	s_nop 0
	global_load_lds_dwordx4 v128, vcc
	s_add_u32 vcc_lo, vcc_lo, 0x30000
	s_addc_u32 vcc_hi, vcc_hi, 0
	s_add_i32 m0, s28, 0x1c000
	s_nop 0
	global_load_lds_dwordx4 v132, vcc
	s_add_i32 m0, s28, 0x1e000
	s_nop 0
	global_load_lds_dwordx4 v128, vcc
	s_add_u32 vcc_lo, vcc_lo, 0x10000
	s_addc_u32 vcc_hi, vcc_hi, 0
	s_add_i32 m0, s28, 0x1d000
	s_nop 0
	global_load_lds_dwordx4 v132, vcc
	s_add_i32 m0, s28, 0x1f000
	s_nop 0
	global_load_lds_dwordx4 v128, vcc
	ds_read_b128 v[144:147], v151 offset:0
	ds_read_b128 v[154:157], v151 offset:1024
	ds_read_b128 v[158:161], v151 offset:2048
	ds_read_b128 v[162:165], v151 offset:3072
	ds_read_b128 v[166:169], v152 offset:0
	ds_read_b128 v[170:173], v152 offset:1024
	ds_read_b128 v[174:177], v152 offset:2048
	ds_read_b128 v[178:181], v152 offset:3072
	ds_read_b128 v[182:185], v153 offset:0
	ds_read_b128 v[186:189], v153 offset:1024
	ds_read_b128 v[190:193], v153 offset:2048
	ds_read_b128 v[194:197], v153 offset:3072
	ds_read_b128 v[198:201], v153 offset:4096
	ds_read_b128 v[202:205], v153 offset:5120
	ds_read_b128 v[206:209], v153 offset:6144
	ds_read_b128 v[210:213], v153 offset:7168
	ds_read_b128 v[220:223], v153 offset:16384
	ds_read_b128 v[224:227], v153 offset:17408
	ds_read_b128 v[228:231], v153 offset:18432
	ds_read_b128 v[232:235], v153 offset:19456
	ds_read_b128 v[236:239], v153 offset:20480
	ds_read_b128 v[240:243], v153 offset:21504
	ds_read_b128 v[244:247], v153 offset:22528
	ds_read_b128 v[248:251], v153 offset:23552
	s_nop 15
	s_nop 15
	s_waitcnt lgkmcnt(0)
	s_barrier
	s_cmp_eq_i32 s49, -2
	s_cbranch_scc1 .Lk64_z_glu_l
	s_setprio 1
	v_mfma_f32_16x16x32_bf16 v[124:127], v[144:147], v[182:185], v[124:127]
	v_mfma_f32_16x16x32_bf16 v[120:123], v[158:161], v[182:185], v[120:123]
	v_mfma_f32_16x16x32_bf16 v[108:111], v[144:147], v[190:193], v[108:111]
	v_mfma_f32_16x16x32_bf16 v[104:107], v[158:161], v[190:193], v[104:107]
	v_mfma_f32_16x16x32_bf16 v[92:95], v[144:147], v[198:201], v[92:95]
	v_mfma_f32_16x16x32_bf16 v[88:91], v[158:161], v[198:201], v[88:91]
	v_mfma_f32_16x16x32_bf16 v[76:79], v[144:147], v[206:209], v[76:79]
	v_mfma_f32_16x16x32_bf16 v[72:75], v[158:161], v[206:209], v[72:75]
	v_mfma_f32_16x16x32_bf16 v[124:127], v[154:157], v[186:189], v[124:127]
	v_mfma_f32_16x16x32_bf16 v[120:123], v[162:165], v[186:189], v[120:123]
	v_mfma_f32_16x16x32_bf16 v[108:111], v[154:157], v[194:197], v[108:111]
	v_mfma_f32_16x16x32_bf16 v[104:107], v[162:165], v[194:197], v[104:107]
	v_mfma_f32_16x16x32_bf16 v[92:95], v[154:157], v[202:205], v[92:95]
	v_mfma_f32_16x16x32_bf16 v[88:91], v[162:165], v[202:205], v[88:91]
	v_mfma_f32_16x16x32_bf16 v[76:79], v[154:157], v[210:213], v[76:79]
	v_mfma_f32_16x16x32_bf16 v[72:75], v[162:165], v[210:213], v[72:75]
	s_setprio 0
	s_setprio 1
	v_mfma_f32_16x16x32_bf16 v[116:119], v[166:169], v[182:185], v[116:119]
	v_mfma_f32_16x16x32_bf16 v[112:115], v[174:177], v[182:185], v[112:115]
	v_mfma_f32_16x16x32_bf16 v[100:103], v[166:169], v[190:193], v[100:103]
	v_mfma_f32_16x16x32_bf16 v[96:99], v[174:177], v[190:193], v[96:99]
	v_mfma_f32_16x16x32_bf16 v[84:87], v[166:169], v[198:201], v[84:87]
	v_mfma_f32_16x16x32_bf16 v[80:83], v[174:177], v[198:201], v[80:83]
	v_mfma_f32_16x16x32_bf16 v[68:71], v[166:169], v[206:209], v[68:71]
	v_mfma_f32_16x16x32_bf16 v[64:67], v[174:177], v[206:209], v[64:67]
	v_mfma_f32_16x16x32_bf16 v[116:119], v[170:173], v[186:189], v[116:119]
	v_mfma_f32_16x16x32_bf16 v[112:115], v[178:181], v[186:189], v[112:115]
	v_mfma_f32_16x16x32_bf16 v[100:103], v[170:173], v[194:197], v[100:103]
	v_mfma_f32_16x16x32_bf16 v[96:99], v[178:181], v[194:197], v[96:99]
	v_mfma_f32_16x16x32_bf16 v[84:87], v[170:173], v[202:205], v[84:87]
	v_mfma_f32_16x16x32_bf16 v[80:83], v[178:181], v[202:205], v[80:83]
	v_mfma_f32_16x16x32_bf16 v[68:71], v[170:173], v[210:213], v[68:71]
	v_mfma_f32_16x16x32_bf16 v[64:67], v[178:181], v[210:213], v[64:67]
	s_setprio 0
	s_setprio 1
	v_mfma_f32_16x16x32_bf16 v[60:63], v[144:147], v[220:223], v[60:63]
	v_mfma_f32_16x16x32_bf16 v[56:59], v[158:161], v[220:223], v[56:59]
	v_mfma_f32_16x16x32_bf16 v[44:47], v[144:147], v[228:231], v[44:47]
	v_mfma_f32_16x16x32_bf16 v[40:43], v[158:161], v[228:231], v[40:43]
	v_mfma_f32_16x16x32_bf16 v[28:31], v[144:147], v[236:239], v[28:31]
	v_mfma_f32_16x16x32_bf16 v[24:27], v[158:161], v[236:239], v[24:27]
	v_mfma_f32_16x16x32_bf16 v[12:15], v[144:147], v[244:247], v[12:15]
	v_mfma_f32_16x16x32_bf16 v[8:11], v[158:161], v[244:247], v[8:11]
	v_mfma_f32_16x16x32_bf16 v[60:63], v[154:157], v[224:227], v[60:63]
	v_mfma_f32_16x16x32_bf16 v[56:59], v[162:165], v[224:227], v[56:59]
	v_mfma_f32_16x16x32_bf16 v[44:47], v[154:157], v[232:235], v[44:47]
	v_mfma_f32_16x16x32_bf16 v[40:43], v[162:165], v[232:235], v[40:43]
	v_mfma_f32_16x16x32_bf16 v[28:31], v[154:157], v[240:243], v[28:31]
	v_mfma_f32_16x16x32_bf16 v[24:27], v[162:165], v[240:243], v[24:27]
	v_mfma_f32_16x16x32_bf16 v[12:15], v[154:157], v[248:251], v[12:15]
	v_mfma_f32_16x16x32_bf16 v[8:11], v[162:165], v[248:251], v[8:11]
	s_setprio 0
	s_setprio 1
	v_mfma_f32_16x16x32_bf16 v[52:55], v[166:169], v[220:223], v[52:55]
	v_mfma_f32_16x16x32_bf16 v[48:51], v[174:177], v[220:223], v[48:51]
	v_mfma_f32_16x16x32_bf16 v[36:39], v[166:169], v[228:231], v[36:39]
	v_mfma_f32_16x16x32_bf16 v[32:35], v[174:177], v[228:231], v[32:35]
	v_mfma_f32_16x16x32_bf16 v[20:23], v[166:169], v[236:239], v[20:23]
	v_mfma_f32_16x16x32_bf16 v[16:19], v[174:177], v[236:239], v[16:19]
	v_mfma_f32_16x16x32_bf16 v[4:7], v[166:169], v[244:247], v[4:7]
	v_mfma_f32_16x16x32_bf16 v[0:3], v[174:177], v[244:247], v[0:3]
	v_mfma_f32_16x16x32_bf16 v[52:55], v[170:173], v[224:227], v[52:55]
	v_mfma_f32_16x16x32_bf16 v[48:51], v[178:181], v[224:227], v[48:51]
	v_mfma_f32_16x16x32_bf16 v[36:39], v[170:173], v[232:235], v[36:39]
	v_mfma_f32_16x16x32_bf16 v[32:35], v[178:181], v[232:235], v[32:35]
	v_mfma_f32_16x16x32_bf16 v[20:23], v[170:173], v[240:243], v[20:23]
	v_mfma_f32_16x16x32_bf16 v[16:19], v[178:181], v[240:243], v[16:19]
	v_mfma_f32_16x16x32_bf16 v[4:7], v[170:173], v[248:251], v[4:7]
	v_mfma_f32_16x16x32_bf16 v[0:3], v[178:181], v[248:251], v[0:3]
	s_setprio 0
.Lk64_zj_glu_l:
	s_waitcnt vmcnt(0)
	s_barrier
	s_add_u32 vcc_lo, s24, 0x0
	s_addc_u32 vcc_hi, s25, 0
	s_add_i32 m0, s28, 0x10000
	s_nop 0
	global_load_lds_dwordx4 v132, vcc
	s_add_i32 m0, s28, 0x12000
	s_nop 0
	global_load_lds_dwordx4 v128, vcc
	s_add_u32 vcc_lo, vcc_lo, 0x10000
	s_addc_u32 vcc_hi, vcc_hi, 0
	s_add_i32 m0, s28, 0x11000
	s_nop 0
	global_load_lds_dwordx4 v132, vcc
	s_add_i32 m0, s28, 0x13000
	s_nop 0
	global_load_lds_dwordx4 v128, vcc
	s_add_u32 vcc_lo, vcc_lo, 0x30000
	s_addc_u32 vcc_hi, vcc_hi, 0
	s_add_i32 m0, s28, 0x14000
	s_nop 0
	global_load_lds_dwordx4 v132, vcc
	s_add_i32 m0, s28, 0x16000
	s_nop 0
	global_load_lds_dwordx4 v128, vcc
	s_add_u32 vcc_lo, vcc_lo, 0x10000
	s_addc_u32 vcc_hi, vcc_hi, 0
	s_add_i32 m0, s28, 0x15000
	s_nop 0
	global_load_lds_dwordx4 v132, vcc
	s_add_i32 m0, s28, 0x17000
	s_nop 0
	global_load_lds_dwordx4 v128, vcc
	ds_read_b128 v[144:147], v151 offset:32768
	ds_read_b128 v[154:157], v151 offset:33792
	ds_read_b128 v[158:161], v151 offset:34816
	ds_read_b128 v[162:165], v151 offset:35840
	ds_read_b128 v[166:169], v152 offset:32768
	ds_read_b128 v[170:173], v152 offset:33792
	ds_read_b128 v[174:177], v152 offset:34816
	ds_read_b128 v[178:181], v152 offset:35840
	ds_read_b128 v[182:185], v153 offset:32768
	ds_read_b128 v[186:189], v153 offset:33792
	ds_read_b128 v[190:193], v153 offset:34816
	ds_read_b128 v[194:197], v153 offset:35840
	ds_read_b128 v[198:201], v153 offset:36864
	ds_read_b128 v[202:205], v153 offset:37888
	ds_read_b128 v[206:209], v153 offset:38912
	ds_read_b128 v[210:213], v153 offset:39936
	ds_read_b128 v[220:223], v153 offset:49152
	ds_read_b128 v[224:227], v153 offset:50176
	ds_read_b128 v[228:231], v153 offset:51200
	ds_read_b128 v[232:235], v153 offset:52224
	ds_read_b128 v[236:239], v153 offset:53248
	ds_read_b128 v[240:243], v153 offset:54272
	ds_read_b128 v[244:247], v153 offset:55296
	ds_read_b128 v[248:251], v153 offset:56320
	s_nop 15
	s_nop 15
	s_waitcnt lgkmcnt(0)
	s_barrier
	s_setprio 1
	v_mfma_f32_16x16x32_bf16 v[124:127], v[144:147], v[182:185], v[124:127]
	v_mfma_f32_16x16x32_bf16 v[120:123], v[158:161], v[182:185], v[120:123]
	v_mfma_f32_16x16x32_bf16 v[108:111], v[144:147], v[190:193], v[108:111]
	v_mfma_f32_16x16x32_bf16 v[104:107], v[158:161], v[190:193], v[104:107]
	v_mfma_f32_16x16x32_bf16 v[92:95], v[144:147], v[198:201], v[92:95]
	v_mfma_f32_16x16x32_bf16 v[88:91], v[158:161], v[198:201], v[88:91]
	v_mfma_f32_16x16x32_bf16 v[76:79], v[144:147], v[206:209], v[76:79]
	v_mfma_f32_16x16x32_bf16 v[72:75], v[158:161], v[206:209], v[72:75]
	v_mfma_f32_16x16x32_bf16 v[124:127], v[154:157], v[186:189], v[124:127]
	v_mfma_f32_16x16x32_bf16 v[120:123], v[162:165], v[186:189], v[120:123]
	v_mfma_f32_16x16x32_bf16 v[108:111], v[154:157], v[194:197], v[108:111]
	v_mfma_f32_16x16x32_bf16 v[104:107], v[162:165], v[194:197], v[104:107]
	v_mfma_f32_16x16x32_bf16 v[92:95], v[154:157], v[202:205], v[92:95]
	v_mfma_f32_16x16x32_bf16 v[88:91], v[162:165], v[202:205], v[88:91]
	v_mfma_f32_16x16x32_bf16 v[76:79], v[154:157], v[210:213], v[76:79]
	v_mfma_f32_16x16x32_bf16 v[72:75], v[162:165], v[210:213], v[72:75]
	s_setprio 0
	s_setprio 1
	v_mfma_f32_16x16x32_bf16 v[116:119], v[166:169], v[182:185], v[116:119]
	v_mfma_f32_16x16x32_bf16 v[112:115], v[174:177], v[182:185], v[112:115]
	v_mfma_f32_16x16x32_bf16 v[100:103], v[166:169], v[190:193], v[100:103]
	v_mfma_f32_16x16x32_bf16 v[96:99], v[174:177], v[190:193], v[96:99]
	v_mfma_f32_16x16x32_bf16 v[84:87], v[166:169], v[198:201], v[84:87]
	v_mfma_f32_16x16x32_bf16 v[80:83], v[174:177], v[198:201], v[80:83]
	v_mfma_f32_16x16x32_bf16 v[68:71], v[166:169], v[206:209], v[68:71]
	v_mfma_f32_16x16x32_bf16 v[64:67], v[174:177], v[206:209], v[64:67]
	v_mfma_f32_16x16x32_bf16 v[116:119], v[170:173], v[186:189], v[116:119]
	v_mfma_f32_16x16x32_bf16 v[112:115], v[178:181], v[186:189], v[112:115]
	v_mfma_f32_16x16x32_bf16 v[100:103], v[170:173], v[194:197], v[100:103]
	v_mfma_f32_16x16x32_bf16 v[96:99], v[178:181], v[194:197], v[96:99]
	v_mfma_f32_16x16x32_bf16 v[84:87], v[170:173], v[202:205], v[84:87]
	v_mfma_f32_16x16x32_bf16 v[80:83], v[178:181], v[202:205], v[80:83]
	v_mfma_f32_16x16x32_bf16 v[68:71], v[170:173], v[210:213], v[68:71]
	v_mfma_f32_16x16x32_bf16 v[64:67], v[178:181], v[210:213], v[64:67]
	s_setprio 0
	s_setprio 1
	v_mfma_f32_16x16x32_bf16 v[60:63], v[144:147], v[220:223], v[60:63]
	v_mfma_f32_16x16x32_bf16 v[56:59], v[158:161], v[220:223], v[56:59]
	v_mfma_f32_16x16x32_bf16 v[44:47], v[144:147], v[228:231], v[44:47]
	v_mfma_f32_16x16x32_bf16 v[40:43], v[158:161], v[228:231], v[40:43]
	v_mfma_f32_16x16x32_bf16 v[28:31], v[144:147], v[236:239], v[28:31]
	v_mfma_f32_16x16x32_bf16 v[24:27], v[158:161], v[236:239], v[24:27]
	v_mfma_f32_16x16x32_bf16 v[12:15], v[144:147], v[244:247], v[12:15]
	v_mfma_f32_16x16x32_bf16 v[8:11], v[158:161], v[244:247], v[8:11]
	v_mfma_f32_16x16x32_bf16 v[60:63], v[154:157], v[224:227], v[60:63]
	v_mfma_f32_16x16x32_bf16 v[56:59], v[162:165], v[224:227], v[56:59]
	v_mfma_f32_16x16x32_bf16 v[44:47], v[154:157], v[232:235], v[44:47]
	v_mfma_f32_16x16x32_bf16 v[40:43], v[162:165], v[232:235], v[40:43]
	v_mfma_f32_16x16x32_bf16 v[28:31], v[154:157], v[240:243], v[28:31]
	v_mfma_f32_16x16x32_bf16 v[24:27], v[162:165], v[240:243], v[24:27]
	v_mfma_f32_16x16x32_bf16 v[12:15], v[154:157], v[248:251], v[12:15]
	v_mfma_f32_16x16x32_bf16 v[8:11], v[162:165], v[248:251], v[8:11]
	s_setprio 0
	s_setprio 1
	v_mfma_f32_16x16x32_bf16 v[52:55], v[166:169], v[220:223], v[52:55]
	v_mfma_f32_16x16x32_bf16 v[48:51], v[174:177], v[220:223], v[48:51]
	v_mfma_f32_16x16x32_bf16 v[36:39], v[166:169], v[228:231], v[36:39]
	v_mfma_f32_16x16x32_bf16 v[32:35], v[174:177], v[228:231], v[32:35]
	v_mfma_f32_16x16x32_bf16 v[20:23], v[166:169], v[236:239], v[20:23]
	v_mfma_f32_16x16x32_bf16 v[16:19], v[174:177], v[236:239], v[16:19]
	v_mfma_f32_16x16x32_bf16 v[4:7], v[166:169], v[244:247], v[4:7]
	v_mfma_f32_16x16x32_bf16 v[0:3], v[174:177], v[244:247], v[0:3]
	v_mfma_f32_16x16x32_bf16 v[52:55], v[170:173], v[224:227], v[52:55]
	v_mfma_f32_16x16x32_bf16 v[48:51], v[178:181], v[224:227], v[48:51]
	v_mfma_f32_16x16x32_bf16 v[36:39], v[170:173], v[232:235], v[36:39]
	v_mfma_f32_16x16x32_bf16 v[32:35], v[178:181], v[232:235], v[32:35]
	v_mfma_f32_16x16x32_bf16 v[20:23], v[170:173], v[240:243], v[20:23]
	v_mfma_f32_16x16x32_bf16 v[16:19], v[178:181], v[240:243], v[16:19]
	v_mfma_f32_16x16x32_bf16 v[4:7], v[170:173], v[248:251], v[4:7]
	v_mfma_f32_16x16x32_bf16 v[0:3], v[178:181], v[248:251], v[0:3]
	s_setprio 0
	s_waitcnt vmcnt(0)
	s_barrier
	s_add_i32 s49, s49, 2
	s_add_u32 s22, s22, 0x100
	s_addc_u32 s23, s23, 0
	s_add_u32 s47, s47, 0x100
	s_addc_u32 s48, s48, 0
	s_cmp_gt_u32 s49, 13
	s_cbranch_scc0 .LBB0_613
	s_branch .Lk64_done_glu
.Lk64_z_glu_l:
	s_setprio 1
	v_mfma_f32_16x16x32_bf16 v[124:127], v[144:147], v[182:185], 0
	v_mfma_f32_16x16x32_bf16 v[120:123], v[158:161], v[182:185], 0
	v_mfma_f32_16x16x32_bf16 v[108:111], v[144:147], v[190:193], 0
	v_mfma_f32_16x16x32_bf16 v[104:107], v[158:161], v[190:193], 0
	v_mfma_f32_16x16x32_bf16 v[92:95], v[144:147], v[198:201], 0
	v_mfma_f32_16x16x32_bf16 v[88:91], v[158:161], v[198:201], 0
	v_mfma_f32_16x16x32_bf16 v[76:79], v[144:147], v[206:209], 0
	v_mfma_f32_16x16x32_bf16 v[72:75], v[158:161], v[206:209], 0
	v_mfma_f32_16x16x32_bf16 v[124:127], v[154:157], v[186:189], v[124:127]
	v_mfma_f32_16x16x32_bf16 v[120:123], v[162:165], v[186:189], v[120:123]
	v_mfma_f32_16x16x32_bf16 v[108:111], v[154:157], v[194:197], v[108:111]
	v_mfma_f32_16x16x32_bf16 v[104:107], v[162:165], v[194:197], v[104:107]
	v_mfma_f32_16x16x32_bf16 v[92:95], v[154:157], v[202:205], v[92:95]
	v_mfma_f32_16x16x32_bf16 v[88:91], v[162:165], v[202:205], v[88:91]
	v_mfma_f32_16x16x32_bf16 v[76:79], v[154:157], v[210:213], v[76:79]
	v_mfma_f32_16x16x32_bf16 v[72:75], v[162:165], v[210:213], v[72:75]
	s_setprio 0
	s_setprio 1
	v_mfma_f32_16x16x32_bf16 v[116:119], v[166:169], v[182:185], 0
	v_mfma_f32_16x16x32_bf16 v[112:115], v[174:177], v[182:185], 0
	v_mfma_f32_16x16x32_bf16 v[100:103], v[166:169], v[190:193], 0
	v_mfma_f32_16x16x32_bf16 v[96:99], v[174:177], v[190:193], 0
	v_mfma_f32_16x16x32_bf16 v[84:87], v[166:169], v[198:201], 0
	v_mfma_f32_16x16x32_bf16 v[80:83], v[174:177], v[198:201], 0
	v_mfma_f32_16x16x32_bf16 v[68:71], v[166:169], v[206:209], 0
	v_mfma_f32_16x16x32_bf16 v[64:67], v[174:177], v[206:209], 0
	v_mfma_f32_16x16x32_bf16 v[116:119], v[170:173], v[186:189], v[116:119]
	v_mfma_f32_16x16x32_bf16 v[112:115], v[178:181], v[186:189], v[112:115]
	v_mfma_f32_16x16x32_bf16 v[100:103], v[170:173], v[194:197], v[100:103]
	v_mfma_f32_16x16x32_bf16 v[96:99], v[178:181], v[194:197], v[96:99]
	v_mfma_f32_16x16x32_bf16 v[84:87], v[170:173], v[202:205], v[84:87]
	v_mfma_f32_16x16x32_bf16 v[80:83], v[178:181], v[202:205], v[80:83]
	v_mfma_f32_16x16x32_bf16 v[68:71], v[170:173], v[210:213], v[68:71]
	v_mfma_f32_16x16x32_bf16 v[64:67], v[178:181], v[210:213], v[64:67]
	s_setprio 0
	s_setprio 1
	v_mfma_f32_16x16x32_bf16 v[60:63], v[144:147], v[220:223], 0
	v_mfma_f32_16x16x32_bf16 v[56:59], v[158:161], v[220:223], 0
	v_mfma_f32_16x16x32_bf16 v[44:47], v[144:147], v[228:231], 0
	v_mfma_f32_16x16x32_bf16 v[40:43], v[158:161], v[228:231], 0
	v_mfma_f32_16x16x32_bf16 v[28:31], v[144:147], v[236:239], 0
	v_mfma_f32_16x16x32_bf16 v[24:27], v[158:161], v[236:239], 0
	v_mfma_f32_16x16x32_bf16 v[12:15], v[144:147], v[244:247], 0
	v_mfma_f32_16x16x32_bf16 v[8:11], v[158:161], v[244:247], 0
	v_mfma_f32_16x16x32_bf16 v[60:63], v[154:157], v[224:227], v[60:63]
	v_mfma_f32_16x16x32_bf16 v[56:59], v[162:165], v[224:227], v[56:59]
	v_mfma_f32_16x16x32_bf16 v[44:47], v[154:157], v[232:235], v[44:47]
	v_mfma_f32_16x16x32_bf16 v[40:43], v[162:165], v[232:235], v[40:43]
	v_mfma_f32_16x16x32_bf16 v[28:31], v[154:157], v[240:243], v[28:31]
	v_mfma_f32_16x16x32_bf16 v[24:27], v[162:165], v[240:243], v[24:27]
	v_mfma_f32_16x16x32_bf16 v[12:15], v[154:157], v[248:251], v[12:15]
	v_mfma_f32_16x16x32_bf16 v[8:11], v[162:165], v[248:251], v[8:11]
	s_setprio 0
	s_setprio 1
	v_mfma_f32_16x16x32_bf16 v[52:55], v[166:169], v[220:223], 0
	v_mfma_f32_16x16x32_bf16 v[48:51], v[174:177], v[220:223], 0
	v_mfma_f32_16x16x32_bf16 v[36:39], v[166:169], v[228:231], 0
	v_mfma_f32_16x16x32_bf16 v[32:35], v[174:177], v[228:231], 0
	v_mfma_f32_16x16x32_bf16 v[20:23], v[166:169], v[236:239], 0
	v_mfma_f32_16x16x32_bf16 v[16:19], v[174:177], v[236:239], 0
	v_mfma_f32_16x16x32_bf16 v[4:7], v[166:169], v[244:247], 0
	v_mfma_f32_16x16x32_bf16 v[0:3], v[174:177], v[244:247], 0
	v_mfma_f32_16x16x32_bf16 v[52:55], v[170:173], v[224:227], v[52:55]
	v_mfma_f32_16x16x32_bf16 v[48:51], v[178:181], v[224:227], v[48:51]
	v_mfma_f32_16x16x32_bf16 v[36:39], v[170:173], v[232:235], v[36:39]
	v_mfma_f32_16x16x32_bf16 v[32:35], v[178:181], v[232:235], v[32:35]
	v_mfma_f32_16x16x32_bf16 v[20:23], v[170:173], v[240:243], v[20:23]
	v_mfma_f32_16x16x32_bf16 v[16:19], v[178:181], v[240:243], v[16:19]
	v_mfma_f32_16x16x32_bf16 v[4:7], v[170:173], v[248:251], v[4:7]
	v_mfma_f32_16x16x32_bf16 v[0:3], v[178:181], v[248:251], v[0:3]
	s_setprio 0
	s_branch .Lk64_zj_glu_l
.Lk64_trail_glu:
	s_sub_u32 vcc_lo, s22, 0x40000
	s_subb_u32 vcc_hi, s23, 0
	s_add_i32 m0, s28, 0xa000
	s_nop 0
	global_load_lds_dwordx4 v130, vcc
	s_add_u32 vcc_lo, vcc_lo, 0x10000
	s_addc_u32 vcc_hi, vcc_hi, 0
	s_add_i32 m0, s28, 0x9000
	s_nop 0
	global_load_lds_dwordx4 v134, vcc
	s_add_u32 vcc_lo, vcc_lo, 0x30000
	s_addc_u32 vcc_hi, vcc_hi, 0
	s_add_i32 m0, s28, 0xe000
	s_nop 0
	global_load_lds_dwordx4 v130, vcc
	s_add_u32 vcc_lo, vcc_lo, 0x10000
	s_addc_u32 vcc_hi, vcc_hi, 0
	s_add_i32 m0, s28, 0xd000
	s_nop 0
	global_load_lds_dwordx4 v134, vcc
	s_add_u32 vcc_lo, s26, 0x0
	s_addc_u32 vcc_hi, s27, 0
	s_mov_b32 m0, s28
	s_nop 0
	global_load_lds_dwordx4 v134, vcc
	s_sub_u32 vcc_lo, vcc_lo, 0x10000
	s_subb_u32 vcc_hi, vcc_hi, 0
	s_sub_i32 m0, s28, 0x1000
	s_nop 0
	global_load_lds_dwordx4 v134, vcc
	s_add_u32 vcc_lo, vcc_lo, 0x50000
	s_addc_u32 vcc_hi, vcc_hi, 0
	s_add_i32 m0, s28, 0x4000
	s_nop 0
	global_load_lds_dwordx4 v134, vcc
	s_sub_u32 vcc_lo, vcc_lo, 0x10000
	s_subb_u32 vcc_hi, vcc_hi, 0
	s_add_i32 m0, s28, 0x3000
	s_nop 0
	global_load_lds_dwordx4 v134, vcc
	ds_read_b128 v[144:147], v151 offset:0
	ds_read_b128 v[154:157], v151 offset:1024
	ds_read_b128 v[158:161], v151 offset:2048
	ds_read_b128 v[162:165], v151 offset:3072
	ds_read_b128 v[166:169], v152 offset:0
	ds_read_b128 v[170:173], v152 offset:1024
	ds_read_b128 v[174:177], v152 offset:2048
	ds_read_b128 v[178:181], v152 offset:3072
	ds_read_b128 v[182:185], v153 offset:0
	ds_read_b128 v[186:189], v153 offset:1024
	ds_read_b128 v[190:193], v153 offset:2048
	ds_read_b128 v[194:197], v153 offset:3072
	ds_read_b128 v[198:201], v153 offset:4096
	ds_read_b128 v[202:205], v153 offset:5120
	ds_read_b128 v[206:209], v153 offset:6144
	ds_read_b128 v[210:213], v153 offset:7168
	ds_read_b128 v[220:223], v153 offset:16384
	ds_read_b128 v[224:227], v153 offset:17408
	ds_read_b128 v[228:231], v153 offset:18432
	ds_read_b128 v[232:235], v153 offset:19456
	ds_read_b128 v[236:239], v153 offset:20480
	ds_read_b128 v[240:243], v153 offset:21504
	ds_read_b128 v[244:247], v153 offset:22528
	ds_read_b128 v[248:251], v153 offset:23552
	s_nop 15
	s_nop 15
	s_waitcnt lgkmcnt(0)
	s_barrier
	s_cmp_eq_i32 s49, -2
	s_cbranch_scc1 .Lk64_z_glu_t
	s_setprio 1
	v_mfma_f32_16x16x32_bf16 v[124:127], v[144:147], v[182:185], v[124:127]
	v_mfma_f32_16x16x32_bf16 v[120:123], v[158:161], v[182:185], v[120:123]
	v_mfma_f32_16x16x32_bf16 v[108:111], v[144:147], v[190:193], v[108:111]
	v_mfma_f32_16x16x32_bf16 v[104:107], v[158:161], v[190:193], v[104:107]
	v_mfma_f32_16x16x32_bf16 v[92:95], v[144:147], v[198:201], v[92:95]
	v_mfma_f32_16x16x32_bf16 v[88:91], v[158:161], v[198:201], v[88:91]
	v_mfma_f32_16x16x32_bf16 v[76:79], v[144:147], v[206:209], v[76:79]
	v_mfma_f32_16x16x32_bf16 v[72:75], v[158:161], v[206:209], v[72:75]
	v_mfma_f32_16x16x32_bf16 v[124:127], v[154:157], v[186:189], v[124:127]
	v_mfma_f32_16x16x32_bf16 v[120:123], v[162:165], v[186:189], v[120:123]
	v_mfma_f32_16x16x32_bf16 v[108:111], v[154:157], v[194:197], v[108:111]
	v_mfma_f32_16x16x32_bf16 v[104:107], v[162:165], v[194:197], v[104:107]
	v_mfma_f32_16x16x32_bf16 v[92:95], v[154:157], v[202:205], v[92:95]
	v_mfma_f32_16x16x32_bf16 v[88:91], v[162:165], v[202:205], v[88:91]
	v_mfma_f32_16x16x32_bf16 v[76:79], v[154:157], v[210:213], v[76:79]
	v_mfma_f32_16x16x32_bf16 v[72:75], v[162:165], v[210:213], v[72:75]
	s_setprio 0
	s_setprio 1
	v_mfma_f32_16x16x32_bf16 v[116:119], v[166:169], v[182:185], v[116:119]
	v_mfma_f32_16x16x32_bf16 v[112:115], v[174:177], v[182:185], v[112:115]
	v_mfma_f32_16x16x32_bf16 v[100:103], v[166:169], v[190:193], v[100:103]
	v_mfma_f32_16x16x32_bf16 v[96:99], v[174:177], v[190:193], v[96:99]
	v_mfma_f32_16x16x32_bf16 v[84:87], v[166:169], v[198:201], v[84:87]
	v_mfma_f32_16x16x32_bf16 v[80:83], v[174:177], v[198:201], v[80:83]
	v_mfma_f32_16x16x32_bf16 v[68:71], v[166:169], v[206:209], v[68:71]
	v_mfma_f32_16x16x32_bf16 v[64:67], v[174:177], v[206:209], v[64:67]
	v_mfma_f32_16x16x32_bf16 v[116:119], v[170:173], v[186:189], v[116:119]
	v_mfma_f32_16x16x32_bf16 v[112:115], v[178:181], v[186:189], v[112:115]
	v_mfma_f32_16x16x32_bf16 v[100:103], v[170:173], v[194:197], v[100:103]
	v_mfma_f32_16x16x32_bf16 v[96:99], v[178:181], v[194:197], v[96:99]
	v_mfma_f32_16x16x32_bf16 v[84:87], v[170:173], v[202:205], v[84:87]
	v_mfma_f32_16x16x32_bf16 v[80:83], v[178:181], v[202:205], v[80:83]
	v_mfma_f32_16x16x32_bf16 v[68:71], v[170:173], v[210:213], v[68:71]
	v_mfma_f32_16x16x32_bf16 v[64:67], v[178:181], v[210:213], v[64:67]
	s_setprio 0
	s_setprio 1
	v_mfma_f32_16x16x32_bf16 v[60:63], v[144:147], v[220:223], v[60:63]
	v_mfma_f32_16x16x32_bf16 v[56:59], v[158:161], v[220:223], v[56:59]
	v_mfma_f32_16x16x32_bf16 v[44:47], v[144:147], v[228:231], v[44:47]
	v_mfma_f32_16x16x32_bf16 v[40:43], v[158:161], v[228:231], v[40:43]
	v_mfma_f32_16x16x32_bf16 v[28:31], v[144:147], v[236:239], v[28:31]
	v_mfma_f32_16x16x32_bf16 v[24:27], v[158:161], v[236:239], v[24:27]
	v_mfma_f32_16x16x32_bf16 v[12:15], v[144:147], v[244:247], v[12:15]
	v_mfma_f32_16x16x32_bf16 v[8:11], v[158:161], v[244:247], v[8:11]
	v_mfma_f32_16x16x32_bf16 v[60:63], v[154:157], v[224:227], v[60:63]
	v_mfma_f32_16x16x32_bf16 v[56:59], v[162:165], v[224:227], v[56:59]
	v_mfma_f32_16x16x32_bf16 v[44:47], v[154:157], v[232:235], v[44:47]
	v_mfma_f32_16x16x32_bf16 v[40:43], v[162:165], v[232:235], v[40:43]
	v_mfma_f32_16x16x32_bf16 v[28:31], v[154:157], v[240:243], v[28:31]
	v_mfma_f32_16x16x32_bf16 v[24:27], v[162:165], v[240:243], v[24:27]
	v_mfma_f32_16x16x32_bf16 v[12:15], v[154:157], v[248:251], v[12:15]
	v_mfma_f32_16x16x32_bf16 v[8:11], v[162:165], v[248:251], v[8:11]
	s_setprio 0
	s_setprio 1
	v_mfma_f32_16x16x32_bf16 v[52:55], v[166:169], v[220:223], v[52:55]
	v_mfma_f32_16x16x32_bf16 v[48:51], v[174:177], v[220:223], v[48:51]
	v_mfma_f32_16x16x32_bf16 v[36:39], v[166:169], v[228:231], v[36:39]
	v_mfma_f32_16x16x32_bf16 v[32:35], v[174:177], v[228:231], v[32:35]
	v_mfma_f32_16x16x32_bf16 v[20:23], v[166:169], v[236:239], v[20:23]
	v_mfma_f32_16x16x32_bf16 v[16:19], v[174:177], v[236:239], v[16:19]
	v_mfma_f32_16x16x32_bf16 v[4:7], v[166:169], v[244:247], v[4:7]
	v_mfma_f32_16x16x32_bf16 v[0:3], v[174:177], v[244:247], v[0:3]
	v_mfma_f32_16x16x32_bf16 v[52:55], v[170:173], v[224:227], v[52:55]
	v_mfma_f32_16x16x32_bf16 v[48:51], v[178:181], v[224:227], v[48:51]
	v_mfma_f32_16x16x32_bf16 v[36:39], v[170:173], v[232:235], v[36:39]
	v_mfma_f32_16x16x32_bf16 v[32:35], v[178:181], v[232:235], v[32:35]
	v_mfma_f32_16x16x32_bf16 v[20:23], v[170:173], v[240:243], v[20:23]
	v_mfma_f32_16x16x32_bf16 v[16:19], v[178:181], v[240:243], v[16:19]
	v_mfma_f32_16x16x32_bf16 v[4:7], v[170:173], v[248:251], v[4:7]
	v_mfma_f32_16x16x32_bf16 v[0:3], v[178:181], v[248:251], v[0:3]
	s_setprio 0
.Lk64_zj_glu_t:
	s_waitcnt vmcnt(0)
	s_barrier
	s_add_u32 vcc_lo, s26, 0x0
	s_addc_u32 vcc_hi, s27, 0
	s_add_i32 m0, s28, 0x2000
	s_nop 0
	global_load_lds_dwordx4 v130, vcc
	s_add_u32 vcc_lo, vcc_lo, 0x10000
	s_addc_u32 vcc_hi, vcc_hi, 0
	s_add_i32 m0, s28, 0x1000
	s_nop 0
	global_load_lds_dwordx4 v134, vcc
	s_add_u32 vcc_lo, vcc_lo, 0x30000
	s_addc_u32 vcc_hi, vcc_hi, 0
	s_add_i32 m0, s28, 0x6000
	s_nop 0
	global_load_lds_dwordx4 v130, vcc
	s_add_u32 vcc_lo, vcc_lo, 0x10000
	s_addc_u32 vcc_hi, vcc_hi, 0
	s_add_i32 m0, s28, 0x5000
	s_nop 0
	global_load_lds_dwordx4 v134, vcc
	s_add_u32 vcc_lo, s26, 0x80
	s_addc_u32 vcc_hi, s27, 0
	s_add_i32 m0, s28, 0x8000
	s_nop 0
	global_load_lds_dwordx4 v134, vcc
	s_sub_u32 vcc_lo, vcc_lo, 0x10000
	s_subb_u32 vcc_hi, vcc_hi, 0
	s_add_i32 m0, s28, 0x7000
	s_nop 0
	global_load_lds_dwordx4 v134, vcc
	s_add_u32 vcc_lo, vcc_lo, 0x50000
	s_addc_u32 vcc_hi, vcc_hi, 0
	s_add_i32 m0, s28, 0xc000
	s_nop 0
	global_load_lds_dwordx4 v134, vcc
	s_sub_u32 vcc_lo, vcc_lo, 0x10000
	s_subb_u32 vcc_hi, vcc_hi, 0
	s_add_i32 m0, s28, 0xb000
	s_nop 0
	global_load_lds_dwordx4 v134, vcc
	ds_read_b128 v[144:147], v151 offset:32768
	ds_read_b128 v[154:157], v151 offset:33792
	ds_read_b128 v[158:161], v151 offset:34816
	ds_read_b128 v[162:165], v151 offset:35840
	ds_read_b128 v[166:169], v152 offset:32768
	ds_read_b128 v[170:173], v152 offset:33792
	ds_read_b128 v[174:177], v152 offset:34816
	ds_read_b128 v[178:181], v152 offset:35840
	ds_read_b128 v[182:185], v153 offset:32768
	ds_read_b128 v[186:189], v153 offset:33792
	ds_read_b128 v[190:193], v153 offset:34816
	ds_read_b128 v[194:197], v153 offset:35840
	ds_read_b128 v[198:201], v153 offset:36864
	ds_read_b128 v[202:205], v153 offset:37888
	ds_read_b128 v[206:209], v153 offset:38912
	ds_read_b128 v[210:213], v153 offset:39936
	ds_read_b128 v[220:223], v153 offset:49152
	ds_read_b128 v[224:227], v153 offset:50176
	ds_read_b128 v[228:231], v153 offset:51200
	ds_read_b128 v[232:235], v153 offset:52224
	ds_read_b128 v[236:239], v153 offset:53248
	ds_read_b128 v[240:243], v153 offset:54272
	ds_read_b128 v[244:247], v153 offset:55296
	ds_read_b128 v[248:251], v153 offset:56320
	s_nop 15
	s_nop 15
	s_waitcnt lgkmcnt(0)
	s_barrier
	s_setprio 1
	v_mfma_f32_16x16x32_bf16 v[124:127], v[144:147], v[182:185], v[124:127]
	v_mfma_f32_16x16x32_bf16 v[120:123], v[158:161], v[182:185], v[120:123]
	v_mfma_f32_16x16x32_bf16 v[108:111], v[144:147], v[190:193], v[108:111]
	v_mfma_f32_16x16x32_bf16 v[104:107], v[158:161], v[190:193], v[104:107]
	v_mfma_f32_16x16x32_bf16 v[92:95], v[144:147], v[198:201], v[92:95]
	v_mfma_f32_16x16x32_bf16 v[88:91], v[158:161], v[198:201], v[88:91]
	v_mfma_f32_16x16x32_bf16 v[76:79], v[144:147], v[206:209], v[76:79]
	v_mfma_f32_16x16x32_bf16 v[72:75], v[158:161], v[206:209], v[72:75]
	v_mfma_f32_16x16x32_bf16 v[124:127], v[154:157], v[186:189], v[124:127]
	v_mfma_f32_16x16x32_bf16 v[120:123], v[162:165], v[186:189], v[120:123]
	v_mfma_f32_16x16x32_bf16 v[108:111], v[154:157], v[194:197], v[108:111]
	v_mfma_f32_16x16x32_bf16 v[104:107], v[162:165], v[194:197], v[104:107]
	v_mfma_f32_16x16x32_bf16 v[92:95], v[154:157], v[202:205], v[92:95]
	v_mfma_f32_16x16x32_bf16 v[88:91], v[162:165], v[202:205], v[88:91]
	v_mfma_f32_16x16x32_bf16 v[76:79], v[154:157], v[210:213], v[76:79]
	v_mfma_f32_16x16x32_bf16 v[72:75], v[162:165], v[210:213], v[72:75]
	s_setprio 0
	s_setprio 1
	v_mfma_f32_16x16x32_bf16 v[116:119], v[166:169], v[182:185], v[116:119]
	v_mfma_f32_16x16x32_bf16 v[112:115], v[174:177], v[182:185], v[112:115]
	v_mfma_f32_16x16x32_bf16 v[100:103], v[166:169], v[190:193], v[100:103]
	v_mfma_f32_16x16x32_bf16 v[96:99], v[174:177], v[190:193], v[96:99]
	v_mfma_f32_16x16x32_bf16 v[84:87], v[166:169], v[198:201], v[84:87]
	v_mfma_f32_16x16x32_bf16 v[80:83], v[174:177], v[198:201], v[80:83]
	v_mfma_f32_16x16x32_bf16 v[68:71], v[166:169], v[206:209], v[68:71]
	v_mfma_f32_16x16x32_bf16 v[64:67], v[174:177], v[206:209], v[64:67]
	v_mfma_f32_16x16x32_bf16 v[116:119], v[170:173], v[186:189], v[116:119]
	v_mfma_f32_16x16x32_bf16 v[112:115], v[178:181], v[186:189], v[112:115]
	v_mfma_f32_16x16x32_bf16 v[100:103], v[170:173], v[194:197], v[100:103]
	v_mfma_f32_16x16x32_bf16 v[96:99], v[178:181], v[194:197], v[96:99]
	v_mfma_f32_16x16x32_bf16 v[84:87], v[170:173], v[202:205], v[84:87]
	v_mfma_f32_16x16x32_bf16 v[80:83], v[178:181], v[202:205], v[80:83]
	v_mfma_f32_16x16x32_bf16 v[68:71], v[170:173], v[210:213], v[68:71]
	v_mfma_f32_16x16x32_bf16 v[64:67], v[178:181], v[210:213], v[64:67]
	s_setprio 0
	s_setprio 1
	v_mfma_f32_16x16x32_bf16 v[60:63], v[144:147], v[220:223], v[60:63]
	v_mfma_f32_16x16x32_bf16 v[56:59], v[158:161], v[220:223], v[56:59]
	v_mfma_f32_16x16x32_bf16 v[44:47], v[144:147], v[228:231], v[44:47]
	v_mfma_f32_16x16x32_bf16 v[40:43], v[158:161], v[228:231], v[40:43]
	v_mfma_f32_16x16x32_bf16 v[28:31], v[144:147], v[236:239], v[28:31]
	v_mfma_f32_16x16x32_bf16 v[24:27], v[158:161], v[236:239], v[24:27]
	v_mfma_f32_16x16x32_bf16 v[12:15], v[144:147], v[244:247], v[12:15]
	v_mfma_f32_16x16x32_bf16 v[8:11], v[158:161], v[244:247], v[8:11]
	v_mfma_f32_16x16x32_bf16 v[60:63], v[154:157], v[224:227], v[60:63]
	v_mfma_f32_16x16x32_bf16 v[56:59], v[162:165], v[224:227], v[56:59]
	v_mfma_f32_16x16x32_bf16 v[44:47], v[154:157], v[232:235], v[44:47]
	v_mfma_f32_16x16x32_bf16 v[40:43], v[162:165], v[232:235], v[40:43]
	v_mfma_f32_16x16x32_bf16 v[28:31], v[154:157], v[240:243], v[28:31]
	v_mfma_f32_16x16x32_bf16 v[24:27], v[162:165], v[240:243], v[24:27]
	v_mfma_f32_16x16x32_bf16 v[12:15], v[154:157], v[248:251], v[12:15]
	v_mfma_f32_16x16x32_bf16 v[8:11], v[162:165], v[248:251], v[8:11]
	s_setprio 0
	s_setprio 1
	v_mfma_f32_16x16x32_bf16 v[52:55], v[166:169], v[220:223], v[52:55]
	v_mfma_f32_16x16x32_bf16 v[48:51], v[174:177], v[220:223], v[48:51]
	v_mfma_f32_16x16x32_bf16 v[36:39], v[166:169], v[228:231], v[36:39]
	v_mfma_f32_16x16x32_bf16 v[32:35], v[174:177], v[228:231], v[32:35]
	v_mfma_f32_16x16x32_bf16 v[20:23], v[166:169], v[236:239], v[20:23]
	v_mfma_f32_16x16x32_bf16 v[16:19], v[174:177], v[236:239], v[16:19]
	v_mfma_f32_16x16x32_bf16 v[4:7], v[166:169], v[244:247], v[4:7]
	v_mfma_f32_16x16x32_bf16 v[0:3], v[174:177], v[244:247], v[0:3]
	v_mfma_f32_16x16x32_bf16 v[52:55], v[170:173], v[224:227], v[52:55]
	v_mfma_f32_16x16x32_bf16 v[48:51], v[178:181], v[224:227], v[48:51]
	v_mfma_f32_16x16x32_bf16 v[36:39], v[170:173], v[232:235], v[36:39]
	v_mfma_f32_16x16x32_bf16 v[32:35], v[178:181], v[232:235], v[32:35]
	v_mfma_f32_16x16x32_bf16 v[20:23], v[170:173], v[240:243], v[20:23]
	v_mfma_f32_16x16x32_bf16 v[16:19], v[178:181], v[240:243], v[16:19]
	v_mfma_f32_16x16x32_bf16 v[4:7], v[170:173], v[248:251], v[4:7]
	v_mfma_f32_16x16x32_bf16 v[0:3], v[178:181], v[248:251], v[0:3]
	s_setprio 0
	s_waitcnt vmcnt(0)
	s_barrier
	s_add_i32 s49, s49, 2
	s_add_u32 s22, s22, 0x100
	s_addc_u32 s23, s23, 0
	s_add_u32 s47, s47, 0x100
	s_addc_u32 s48, s48, 0
	s_cmp_gt_u32 s49, 13
	s_cbranch_scc0 .LBB0_613
	s_branch .Lk64_done_glu

.LBB0_685:
	s_ashr_i32 s25, s24, 31
	s_lshl_b64 s[26:27], s[24:25], 19
	s_add_u32 s26, s66, s26
	s_addc_u32 s27, s67, s27
	s_and_b64 s[28:29], s[38:39], exec
	s_cselect_b32 s25, s27, s13
	s_cselect_b32 s49, s26, s12
	s_ashr_i32 s23, s22, 31
	s_lshl_b64 s[28:29], s[22:23], 19
	s_add_u32 s28, s60, s28
	s_addc_u32 s29, s61, s29
	s_and_b64 s[34:35], s[38:39], exec
	s_cselect_b32 s23, s29, s31
	s_cselect_b32 s51, s28, s30
	s_add_u32 s12, s12, 0x40080
	s_addc_u32 s13, s13, 0
	s_add_u32 s54, s30, 0x100
	s_addc_u32 s55, s31, 0
	s_mov_b32 s56, -2
.LBB0_686:
	s_add_u32 s30, s12, 0xfffc0080
	s_addc_u32 s31, s13, -1
	s_cmp_eq_u32 s56, 12
	s_cselect_b32 s35, s25, s31
	s_cselect_b32 s34, s49, s30
	s_cselect_b32 s31, s23, s55
	s_cselect_b32 s30, s51, s54
	s_and_b64 vcc, exec, s[4:5]
	s_cbranch_vccz .Lk64_trail_p4
	s_sub_u32 vcc_lo, s54, 0x80
	s_subb_u32 vcc_hi, s55, 0
	s_add_i32 m0, s36, 0x18000
	s_nop 0
	global_load_lds_dwordx4 v132, vcc
	s_add_i32 m0, s36, 0x1a000
	s_nop 0
	global_load_lds_dwordx4 v128, vcc
	s_add_u32 vcc_lo, vcc_lo, 0x10000
	s_addc_u32 vcc_hi, vcc_hi, 0
	s_add_i32 m0, s36, 0x19000
	s_nop 0
	global_load_lds_dwordx4 v132, vcc
	s_add_i32 m0, s36, 0x1b000
	s_nop 0
	global_load_lds_dwordx4 v128, vcc
	s_add_u32 vcc_lo, vcc_lo, 0x30000
	s_addc_u32 vcc_hi, vcc_hi, 0
	s_add_i32 m0, s36, 0x1c000
	s_nop 0
	global_load_lds_dwordx4 v132, vcc
	s_add_i32 m0, s36, 0x1e000
	s_nop 0
	global_load_lds_dwordx4 v128, vcc
	s_add_u32 vcc_lo, vcc_lo, 0x10000
	s_addc_u32 vcc_hi, vcc_hi, 0
	s_add_i32 m0, s36, 0x1d000
	s_nop 0
	global_load_lds_dwordx4 v132, vcc
	s_add_i32 m0, s36, 0x1f000
	s_nop 0
	global_load_lds_dwordx4 v128, vcc
	ds_read_b128 v[144:147], v151 offset:0
	ds_read_b128 v[154:157], v151 offset:1024
	ds_read_b128 v[158:161], v151 offset:2048
	ds_read_b128 v[162:165], v151 offset:3072
	ds_read_b128 v[166:169], v152 offset:0
	ds_read_b128 v[170:173], v152 offset:1024
	ds_read_b128 v[174:177], v152 offset:2048
	ds_read_b128 v[178:181], v152 offset:3072
	ds_read_b128 v[182:185], v153 offset:0
	ds_read_b128 v[186:189], v153 offset:1024
	ds_read_b128 v[190:193], v153 offset:2048
	ds_read_b128 v[194:197], v153 offset:3072
	ds_read_b128 v[198:201], v153 offset:4096
	ds_read_b128 v[202:205], v153 offset:5120
	ds_read_b128 v[206:209], v153 offset:6144
	ds_read_b128 v[210:213], v153 offset:7168
	ds_read_b128 v[220:223], v153 offset:16384
	ds_read_b128 v[224:227], v153 offset:17408
	ds_read_b128 v[228:231], v153 offset:18432
	ds_read_b128 v[232:235], v153 offset:19456
	ds_read_b128 v[236:239], v153 offset:20480
	ds_read_b128 v[240:243], v153 offset:21504
	ds_read_b128 v[244:247], v153 offset:22528
	ds_read_b128 v[248:251], v153 offset:23552
	s_nop 15
	s_nop 15
	s_waitcnt lgkmcnt(0)
	s_barrier
	s_cmp_eq_i32 s56, -2
	s_cbranch_scc1 .Lk64_z_p4_l
	s_setprio 1
	v_mfma_f32_16x16x32_bf16 v[124:127], v[144:147], v[182:185], v[124:127]
	v_mfma_f32_16x16x32_bf16 v[120:123], v[158:161], v[182:185], v[120:123]
	v_mfma_f32_16x16x32_bf16 v[108:111], v[144:147], v[190:193], v[108:111]
	v_mfma_f32_16x16x32_bf16 v[104:107], v[158:161], v[190:193], v[104:107]
	v_mfma_f32_16x16x32_bf16 v[92:95], v[144:147], v[198:201], v[92:95]
	v_mfma_f32_16x16x32_bf16 v[88:91], v[158:161], v[198:201], v[88:91]
	v_mfma_f32_16x16x32_bf16 v[76:79], v[144:147], v[206:209], v[76:79]
	v_mfma_f32_16x16x32_bf16 v[72:75], v[158:161], v[206:209], v[72:75]
	v_mfma_f32_16x16x32_bf16 v[124:127], v[154:157], v[186:189], v[124:127]
	v_mfma_f32_16x16x32_bf16 v[120:123], v[162:165], v[186:189], v[120:123]
	v_mfma_f32_16x16x32_bf16 v[108:111], v[154:157], v[194:197], v[108:111]
	v_mfma_f32_16x16x32_bf16 v[104:107], v[162:165], v[194:197], v[104:107]
	v_mfma_f32_16x16x32_bf16 v[92:95], v[154:157], v[202:205], v[92:95]
	v_mfma_f32_16x16x32_bf16 v[88:91], v[162:165], v[202:205], v[88:91]
	v_mfma_f32_16x16x32_bf16 v[76:79], v[154:157], v[210:213], v[76:79]
	v_mfma_f32_16x16x32_bf16 v[72:75], v[162:165], v[210:213], v[72:75]
	s_setprio 0
	s_setprio 1
	v_mfma_f32_16x16x32_bf16 v[116:119], v[166:169], v[182:185], v[116:119]
	v_mfma_f32_16x16x32_bf16 v[112:115], v[174:177], v[182:185], v[112:115]
	v_mfma_f32_16x16x32_bf16 v[100:103], v[166:169], v[190:193], v[100:103]
	v_mfma_f32_16x16x32_bf16 v[96:99], v[174:177], v[190:193], v[96:99]
	v_mfma_f32_16x16x32_bf16 v[84:87], v[166:169], v[198:201], v[84:87]
	v_mfma_f32_16x16x32_bf16 v[80:83], v[174:177], v[198:201], v[80:83]
	v_mfma_f32_16x16x32_bf16 v[68:71], v[166:169], v[206:209], v[68:71]
	v_mfma_f32_16x16x32_bf16 v[64:67], v[174:177], v[206:209], v[64:67]
	v_mfma_f32_16x16x32_bf16 v[116:119], v[170:173], v[186:189], v[116:119]
	v_mfma_f32_16x16x32_bf16 v[112:115], v[178:181], v[186:189], v[112:115]
	v_mfma_f32_16x16x32_bf16 v[100:103], v[170:173], v[194:197], v[100:103]
	v_mfma_f32_16x16x32_bf16 v[96:99], v[178:181], v[194:197], v[96:99]
	v_mfma_f32_16x16x32_bf16 v[84:87], v[170:173], v[202:205], v[84:87]
	v_mfma_f32_16x16x32_bf16 v[80:83], v[178:181], v[202:205], v[80:83]
	v_mfma_f32_16x16x32_bf16 v[68:71], v[170:173], v[210:213], v[68:71]
	v_mfma_f32_16x16x32_bf16 v[64:67], v[178:181], v[210:213], v[64:67]
	s_setprio 0
	s_setprio 1
	v_mfma_f32_16x16x32_bf16 v[60:63], v[144:147], v[220:223], v[60:63]
	v_mfma_f32_16x16x32_bf16 v[56:59], v[158:161], v[220:223], v[56:59]
	v_mfma_f32_16x16x32_bf16 v[44:47], v[144:147], v[228:231], v[44:47]
	v_mfma_f32_16x16x32_bf16 v[40:43], v[158:161], v[228:231], v[40:43]
	v_mfma_f32_16x16x32_bf16 v[28:31], v[144:147], v[236:239], v[28:31]
	v_mfma_f32_16x16x32_bf16 v[24:27], v[158:161], v[236:239], v[24:27]
	v_mfma_f32_16x16x32_bf16 v[12:15], v[144:147], v[244:247], v[12:15]
	v_mfma_f32_16x16x32_bf16 v[8:11], v[158:161], v[244:247], v[8:11]
	v_mfma_f32_16x16x32_bf16 v[60:63], v[154:157], v[224:227], v[60:63]
	v_mfma_f32_16x16x32_bf16 v[56:59], v[162:165], v[224:227], v[56:59]
	v_mfma_f32_16x16x32_bf16 v[44:47], v[154:157], v[232:235], v[44:47]
	v_mfma_f32_16x16x32_bf16 v[40:43], v[162:165], v[232:235], v[40:43]
	v_mfma_f32_16x16x32_bf16 v[28:31], v[154:157], v[240:243], v[28:31]
	v_mfma_f32_16x16x32_bf16 v[24:27], v[162:165], v[240:243], v[24:27]
	v_mfma_f32_16x16x32_bf16 v[12:15], v[154:157], v[248:251], v[12:15]
	v_mfma_f32_16x16x32_bf16 v[8:11], v[162:165], v[248:251], v[8:11]
	s_setprio 0
	s_setprio 1
	v_mfma_f32_16x16x32_bf16 v[52:55], v[166:169], v[220:223], v[52:55]
	v_mfma_f32_16x16x32_bf16 v[48:51], v[174:177], v[220:223], v[48:51]
	v_mfma_f32_16x16x32_bf16 v[36:39], v[166:169], v[228:231], v[36:39]
	v_mfma_f32_16x16x32_bf16 v[32:35], v[174:177], v[228:231], v[32:35]
	v_mfma_f32_16x16x32_bf16 v[20:23], v[166:169], v[236:239], v[20:23]
	v_mfma_f32_16x16x32_bf16 v[16:19], v[174:177], v[236:239], v[16:19]
	v_mfma_f32_16x16x32_bf16 v[4:7], v[166:169], v[244:247], v[4:7]
	v_mfma_f32_16x16x32_bf16 v[0:3], v[174:177], v[244:247], v[0:3]
	v_mfma_f32_16x16x32_bf16 v[52:55], v[170:173], v[224:227], v[52:55]
	v_mfma_f32_16x16x32_bf16 v[48:51], v[178:181], v[224:227], v[48:51]
	v_mfma_f32_16x16x32_bf16 v[36:39], v[170:173], v[232:235], v[36:39]
	v_mfma_f32_16x16x32_bf16 v[32:35], v[178:181], v[232:235], v[32:35]
	v_mfma_f32_16x16x32_bf16 v[20:23], v[170:173], v[240:243], v[20:23]
	v_mfma_f32_16x16x32_bf16 v[16:19], v[178:181], v[240:243], v[16:19]
	v_mfma_f32_16x16x32_bf16 v[4:7], v[170:173], v[248:251], v[4:7]
	v_mfma_f32_16x16x32_bf16 v[0:3], v[178:181], v[248:251], v[0:3]
	s_setprio 0
.Lk64_zj_p4_l:
	s_waitcnt vmcnt(0)
	s_barrier
	s_add_u32 vcc_lo, s30, 0x0
	s_addc_u32 vcc_hi, s31, 0
	s_add_i32 m0, s36, 0x10000
	s_nop 0
	global_load_lds_dwordx4 v132, vcc
	s_add_i32 m0, s36, 0x12000
	s_nop 0
	global_load_lds_dwordx4 v128, vcc
	s_add_u32 vcc_lo, vcc_lo, 0x10000
	s_addc_u32 vcc_hi, vcc_hi, 0
	s_add_i32 m0, s36, 0x11000
	s_nop 0
	global_load_lds_dwordx4 v132, vcc
	s_add_i32 m0, s36, 0x13000
	s_nop 0
	global_load_lds_dwordx4 v128, vcc
	s_add_u32 vcc_lo, vcc_lo, 0x30000
	s_addc_u32 vcc_hi, vcc_hi, 0
	s_add_i32 m0, s36, 0x14000
	s_nop 0
	global_load_lds_dwordx4 v132, vcc
	s_add_i32 m0, s36, 0x16000
	s_nop 0
	global_load_lds_dwordx4 v128, vcc
	s_add_u32 vcc_lo, vcc_lo, 0x10000
	s_addc_u32 vcc_hi, vcc_hi, 0
	s_add_i32 m0, s36, 0x15000
	s_nop 0
	global_load_lds_dwordx4 v132, vcc
	s_add_i32 m0, s36, 0x17000
	s_nop 0
	global_load_lds_dwordx4 v128, vcc
	ds_read_b128 v[144:147], v151 offset:32768
	ds_read_b128 v[154:157], v151 offset:33792
	ds_read_b128 v[158:161], v151 offset:34816
	ds_read_b128 v[162:165], v151 offset:35840
	ds_read_b128 v[166:169], v152 offset:32768
	ds_read_b128 v[170:173], v152 offset:33792
	ds_read_b128 v[174:177], v152 offset:34816
	ds_read_b128 v[178:181], v152 offset:35840
	ds_read_b128 v[182:185], v153 offset:32768
	ds_read_b128 v[186:189], v153 offset:33792
	ds_read_b128 v[190:193], v153 offset:34816
	ds_read_b128 v[194:197], v153 offset:35840
	ds_read_b128 v[198:201], v153 offset:36864
	ds_read_b128 v[202:205], v153 offset:37888
	ds_read_b128 v[206:209], v153 offset:38912
	ds_read_b128 v[210:213], v153 offset:39936
	ds_read_b128 v[220:223], v153 offset:49152
	ds_read_b128 v[224:227], v153 offset:50176
	ds_read_b128 v[228:231], v153 offset:51200
	ds_read_b128 v[232:235], v153 offset:52224
	ds_read_b128 v[236:239], v153 offset:53248
	ds_read_b128 v[240:243], v153 offset:54272
	ds_read_b128 v[244:247], v153 offset:55296
	ds_read_b128 v[248:251], v153 offset:56320
	s_nop 15
	s_nop 15
	s_waitcnt lgkmcnt(0)
	s_barrier
	s_setprio 1
	v_mfma_f32_16x16x32_bf16 v[124:127], v[144:147], v[182:185], v[124:127]
	v_mfma_f32_16x16x32_bf16 v[120:123], v[158:161], v[182:185], v[120:123]
	v_mfma_f32_16x16x32_bf16 v[108:111], v[144:147], v[190:193], v[108:111]
	v_mfma_f32_16x16x32_bf16 v[104:107], v[158:161], v[190:193], v[104:107]
	v_mfma_f32_16x16x32_bf16 v[92:95], v[144:147], v[198:201], v[92:95]
	v_mfma_f32_16x16x32_bf16 v[88:91], v[158:161], v[198:201], v[88:91]
	v_mfma_f32_16x16x32_bf16 v[76:79], v[144:147], v[206:209], v[76:79]
	v_mfma_f32_16x16x32_bf16 v[72:75], v[158:161], v[206:209], v[72:75]
	v_mfma_f32_16x16x32_bf16 v[124:127], v[154:157], v[186:189], v[124:127]
	v_mfma_f32_16x16x32_bf16 v[120:123], v[162:165], v[186:189], v[120:123]
	v_mfma_f32_16x16x32_bf16 v[108:111], v[154:157], v[194:197], v[108:111]
	v_mfma_f32_16x16x32_bf16 v[104:107], v[162:165], v[194:197], v[104:107]
	v_mfma_f32_16x16x32_bf16 v[92:95], v[154:157], v[202:205], v[92:95]
	v_mfma_f32_16x16x32_bf16 v[88:91], v[162:165], v[202:205], v[88:91]
	v_mfma_f32_16x16x32_bf16 v[76:79], v[154:157], v[210:213], v[76:79]
	v_mfma_f32_16x16x32_bf16 v[72:75], v[162:165], v[210:213], v[72:75]
	s_setprio 0
	s_setprio 1
	v_mfma_f32_16x16x32_bf16 v[116:119], v[166:169], v[182:185], v[116:119]
	v_mfma_f32_16x16x32_bf16 v[112:115], v[174:177], v[182:185], v[112:115]
	v_mfma_f32_16x16x32_bf16 v[100:103], v[166:169], v[190:193], v[100:103]
	v_mfma_f32_16x16x32_bf16 v[96:99], v[174:177], v[190:193], v[96:99]
	v_mfma_f32_16x16x32_bf16 v[84:87], v[166:169], v[198:201], v[84:87]
	v_mfma_f32_16x16x32_bf16 v[80:83], v[174:177], v[198:201], v[80:83]
	v_mfma_f32_16x16x32_bf16 v[68:71], v[166:169], v[206:209], v[68:71]
	v_mfma_f32_16x16x32_bf16 v[64:67], v[174:177], v[206:209], v[64:67]
	v_mfma_f32_16x16x32_bf16 v[116:119], v[170:173], v[186:189], v[116:119]
	v_mfma_f32_16x16x32_bf16 v[112:115], v[178:181], v[186:189], v[112:115]
	v_mfma_f32_16x16x32_bf16 v[100:103], v[170:173], v[194:197], v[100:103]
	v_mfma_f32_16x16x32_bf16 v[96:99], v[178:181], v[194:197], v[96:99]
	v_mfma_f32_16x16x32_bf16 v[84:87], v[170:173], v[202:205], v[84:87]
	v_mfma_f32_16x16x32_bf16 v[80:83], v[178:181], v[202:205], v[80:83]
	v_mfma_f32_16x16x32_bf16 v[68:71], v[170:173], v[210:213], v[68:71]
	v_mfma_f32_16x16x32_bf16 v[64:67], v[178:181], v[210:213], v[64:67]
	s_setprio 0
	s_setprio 1
	v_mfma_f32_16x16x32_bf16 v[60:63], v[144:147], v[220:223], v[60:63]
	v_mfma_f32_16x16x32_bf16 v[56:59], v[158:161], v[220:223], v[56:59]
	v_mfma_f32_16x16x32_bf16 v[44:47], v[144:147], v[228:231], v[44:47]
	v_mfma_f32_16x16x32_bf16 v[40:43], v[158:161], v[228:231], v[40:43]
	v_mfma_f32_16x16x32_bf16 v[28:31], v[144:147], v[236:239], v[28:31]
	v_mfma_f32_16x16x32_bf16 v[24:27], v[158:161], v[236:239], v[24:27]
	v_mfma_f32_16x16x32_bf16 v[12:15], v[144:147], v[244:247], v[12:15]
	v_mfma_f32_16x16x32_bf16 v[8:11], v[158:161], v[244:247], v[8:11]
	v_mfma_f32_16x16x32_bf16 v[60:63], v[154:157], v[224:227], v[60:63]
	v_mfma_f32_16x16x32_bf16 v[56:59], v[162:165], v[224:227], v[56:59]
	v_mfma_f32_16x16x32_bf16 v[44:47], v[154:157], v[232:235], v[44:47]
	v_mfma_f32_16x16x32_bf16 v[40:43], v[162:165], v[232:235], v[40:43]
	v_mfma_f32_16x16x32_bf16 v[28:31], v[154:157], v[240:243], v[28:31]
	v_mfma_f32_16x16x32_bf16 v[24:27], v[162:165], v[240:243], v[24:27]
	v_mfma_f32_16x16x32_bf16 v[12:15], v[154:157], v[248:251], v[12:15]
	v_mfma_f32_16x16x32_bf16 v[8:11], v[162:165], v[248:251], v[8:11]
	s_setprio 0
	s_setprio 1
	v_mfma_f32_16x16x32_bf16 v[52:55], v[166:169], v[220:223], v[52:55]
	v_mfma_f32_16x16x32_bf16 v[48:51], v[174:177], v[220:223], v[48:51]
	v_mfma_f32_16x16x32_bf16 v[36:39], v[166:169], v[228:231], v[36:39]
	v_mfma_f32_16x16x32_bf16 v[32:35], v[174:177], v[228:231], v[32:35]
	v_mfma_f32_16x16x32_bf16 v[20:23], v[166:169], v[236:239], v[20:23]
	v_mfma_f32_16x16x32_bf16 v[16:19], v[174:177], v[236:239], v[16:19]
	v_mfma_f32_16x16x32_bf16 v[4:7], v[166:169], v[244:247], v[4:7]
	v_mfma_f32_16x16x32_bf16 v[0:3], v[174:177], v[244:247], v[0:3]
	v_mfma_f32_16x16x32_bf16 v[52:55], v[170:173], v[224:227], v[52:55]
	v_mfma_f32_16x16x32_bf16 v[48:51], v[178:181], v[224:227], v[48:51]
	v_mfma_f32_16x16x32_bf16 v[36:39], v[170:173], v[232:235], v[36:39]
	v_mfma_f32_16x16x32_bf16 v[32:35], v[178:181], v[232:235], v[32:35]
	v_mfma_f32_16x16x32_bf16 v[20:23], v[170:173], v[240:243], v[20:23]
	v_mfma_f32_16x16x32_bf16 v[16:19], v[178:181], v[240:243], v[16:19]
	v_mfma_f32_16x16x32_bf16 v[4:7], v[170:173], v[248:251], v[4:7]
	v_mfma_f32_16x16x32_bf16 v[0:3], v[178:181], v[248:251], v[0:3]
	s_setprio 0
	s_waitcnt vmcnt(0)
	s_barrier
	s_add_i32 s56, s56, 2
	s_add_u32 s12, s12, 0x100
	s_addc_u32 s13, s13, 0
	s_add_u32 s54, s54, 0x100
	s_addc_u32 s55, s55, 0
	s_cmp_gt_u32 s56, 13
	s_cbranch_scc0 .LBB0_686
	s_branch .Lk64_done_p4

.Lk64_trail_p4:
	s_sub_u32 vcc_lo, s12, 0x40000
	s_subb_u32 vcc_hi, s13, 0
	s_add_i32 m0, s36, 0xa000
	s_nop 0
	global_load_lds_dwordx4 v130, vcc
	s_add_u32 vcc_lo, vcc_lo, 0x10000
	s_addc_u32 vcc_hi, vcc_hi, 0
	s_add_i32 m0, s36, 0x9000
	s_nop 0
	global_load_lds_dwordx4 v134, vcc
	s_add_u32 vcc_lo, vcc_lo, 0x30000
	s_addc_u32 vcc_hi, vcc_hi, 0
	s_add_i32 m0, s36, 0xe000
	s_nop 0
	global_load_lds_dwordx4 v130, vcc
	s_add_u32 vcc_lo, vcc_lo, 0x10000
	s_addc_u32 vcc_hi, vcc_hi, 0
	s_add_i32 m0, s36, 0xd000
	s_nop 0
	global_load_lds_dwordx4 v134, vcc
	s_add_u32 vcc_lo, s34, 0x0
	s_addc_u32 vcc_hi, s35, 0
	s_mov_b32 m0, s36
	s_nop 0
	global_load_lds_dwordx4 v134, vcc
	s_sub_u32 vcc_lo, vcc_lo, 0x10000
	s_subb_u32 vcc_hi, vcc_hi, 0
	s_sub_i32 m0, s36, 0x1000
	s_nop 0
	global_load_lds_dwordx4 v134, vcc
	s_add_u32 vcc_lo, vcc_lo, 0x50000
	s_addc_u32 vcc_hi, vcc_hi, 0
	s_add_i32 m0, s36, 0x4000
	s_nop 0
	global_load_lds_dwordx4 v134, vcc
	s_sub_u32 vcc_lo, vcc_lo, 0x10000
	s_subb_u32 vcc_hi, vcc_hi, 0
	s_add_i32 m0, s36, 0x3000
	s_nop 0
	global_load_lds_dwordx4 v134, vcc
	ds_read_b128 v[144:147], v151 offset:0
	ds_read_b128 v[154:157], v151 offset:1024
	ds_read_b128 v[158:161], v151 offset:2048
	ds_read_b128 v[162:165], v151 offset:3072
	ds_read_b128 v[166:169], v152 offset:0
	ds_read_b128 v[170:173], v152 offset:1024
	ds_read_b128 v[174:177], v152 offset:2048
	ds_read_b128 v[178:181], v152 offset:3072
	ds_read_b128 v[182:185], v153 offset:0
	ds_read_b128 v[186:189], v153 offset:1024
	ds_read_b128 v[190:193], v153 offset:2048
	ds_read_b128 v[194:197], v153 offset:3072
	ds_read_b128 v[198:201], v153 offset:4096
	ds_read_b128 v[202:205], v153 offset:5120
	ds_read_b128 v[206:209], v153 offset:6144
	ds_read_b128 v[210:213], v153 offset:7168
	ds_read_b128 v[220:223], v153 offset:16384
	ds_read_b128 v[224:227], v153 offset:17408
	ds_read_b128 v[228:231], v153 offset:18432
	ds_read_b128 v[232:235], v153 offset:19456
	ds_read_b128 v[236:239], v153 offset:20480
	ds_read_b128 v[240:243], v153 offset:21504
	ds_read_b128 v[244:247], v153 offset:22528
	ds_read_b128 v[248:251], v153 offset:23552
	s_nop 15
	s_nop 15
	s_waitcnt lgkmcnt(0)
	s_barrier
	s_cmp_eq_i32 s56, -2
	s_cbranch_scc1 .Lk64_z_p4_t
	s_setprio 1
	v_mfma_f32_16x16x32_bf16 v[124:127], v[144:147], v[182:185], v[124:127]
	v_mfma_f32_16x16x32_bf16 v[120:123], v[158:161], v[182:185], v[120:123]
	v_mfma_f32_16x16x32_bf16 v[108:111], v[144:147], v[190:193], v[108:111]
	v_mfma_f32_16x16x32_bf16 v[104:107], v[158:161], v[190:193], v[104:107]
	v_mfma_f32_16x16x32_bf16 v[92:95], v[144:147], v[198:201], v[92:95]
	v_mfma_f32_16x16x32_bf16 v[88:91], v[158:161], v[198:201], v[88:91]
	v_mfma_f32_16x16x32_bf16 v[76:79], v[144:147], v[206:209], v[76:79]
	v_mfma_f32_16x16x32_bf16 v[72:75], v[158:161], v[206:209], v[72:75]
	v_mfma_f32_16x16x32_bf16 v[124:127], v[154:157], v[186:189], v[124:127]
	v_mfma_f32_16x16x32_bf16 v[120:123], v[162:165], v[186:189], v[120:123]
	v_mfma_f32_16x16x32_bf16 v[108:111], v[154:157], v[194:197], v[108:111]
	v_mfma_f32_16x16x32_bf16 v[104:107], v[162:165], v[194:197], v[104:107]
	v_mfma_f32_16x16x32_bf16 v[92:95], v[154:157], v[202:205], v[92:95]
	v_mfma_f32_16x16x32_bf16 v[88:91], v[162:165], v[202:205], v[88:91]
	v_mfma_f32_16x16x32_bf16 v[76:79], v[154:157], v[210:213], v[76:79]
	v_mfma_f32_16x16x32_bf16 v[72:75], v[162:165], v[210:213], v[72:75]
	s_setprio 0
	s_setprio 1
	v_mfma_f32_16x16x32_bf16 v[116:119], v[166:169], v[182:185], v[116:119]
	v_mfma_f32_16x16x32_bf16 v[112:115], v[174:177], v[182:185], v[112:115]
	v_mfma_f32_16x16x32_bf16 v[100:103], v[166:169], v[190:193], v[100:103]
	v_mfma_f32_16x16x32_bf16 v[96:99], v[174:177], v[190:193], v[96:99]
	v_mfma_f32_16x16x32_bf16 v[84:87], v[166:169], v[198:201], v[84:87]
	v_mfma_f32_16x16x32_bf16 v[80:83], v[174:177], v[198:201], v[80:83]
	v_mfma_f32_16x16x32_bf16 v[68:71], v[166:169], v[206:209], v[68:71]
	v_mfma_f32_16x16x32_bf16 v[64:67], v[174:177], v[206:209], v[64:67]
	v_mfma_f32_16x16x32_bf16 v[116:119], v[170:173], v[186:189], v[116:119]
	v_mfma_f32_16x16x32_bf16 v[112:115], v[178:181], v[186:189], v[112:115]
	v_mfma_f32_16x16x32_bf16 v[100:103], v[170:173], v[194:197], v[100:103]
	v_mfma_f32_16x16x32_bf16 v[96:99], v[178:181], v[194:197], v[96:99]
	v_mfma_f32_16x16x32_bf16 v[84:87], v[170:173], v[202:205], v[84:87]
	v_mfma_f32_16x16x32_bf16 v[80:83], v[178:181], v[202:205], v[80:83]
	v_mfma_f32_16x16x32_bf16 v[68:71], v[170:173], v[210:213], v[68:71]
	v_mfma_f32_16x16x32_bf16 v[64:67], v[178:181], v[210:213], v[64:67]
	s_setprio 0
	s_setprio 1
	v_mfma_f32_16x16x32_bf16 v[60:63], v[144:147], v[220:223], v[60:63]
	v_mfma_f32_16x16x32_bf16 v[56:59], v[158:161], v[220:223], v[56:59]
	v_mfma_f32_16x16x32_bf16 v[44:47], v[144:147], v[228:231], v[44:47]
	v_mfma_f32_16x16x32_bf16 v[40:43], v[158:161], v[228:231], v[40:43]
	v_mfma_f32_16x16x32_bf16 v[28:31], v[144:147], v[236:239], v[28:31]
	v_mfma_f32_16x16x32_bf16 v[24:27], v[158:161], v[236:239], v[24:27]
	v_mfma_f32_16x16x32_bf16 v[12:15], v[144:147], v[244:247], v[12:15]
	v_mfma_f32_16x16x32_bf16 v[8:11], v[158:161], v[244:247], v[8:11]
	v_mfma_f32_16x16x32_bf16 v[60:63], v[154:157], v[224:227], v[60:63]
	v_mfma_f32_16x16x32_bf16 v[56:59], v[162:165], v[224:227], v[56:59]
	v_mfma_f32_16x16x32_bf16 v[44:47], v[154:157], v[232:235], v[44:47]
	v_mfma_f32_16x16x32_bf16 v[40:43], v[162:165], v[232:235], v[40:43]
	v_mfma_f32_16x16x32_bf16 v[28:31], v[154:157], v[240:243], v[28:31]
	v_mfma_f32_16x16x32_bf16 v[24:27], v[162:165], v[240:243], v[24:27]
	v_mfma_f32_16x16x32_bf16 v[12:15], v[154:157], v[248:251], v[12:15]
	v_mfma_f32_16x16x32_bf16 v[8:11], v[162:165], v[248:251], v[8:11]
	s_setprio 0
	s_setprio 1
	v_mfma_f32_16x16x32_bf16 v[52:55], v[166:169], v[220:223], v[52:55]
	v_mfma_f32_16x16x32_bf16 v[48:51], v[174:177], v[220:223], v[48:51]
	v_mfma_f32_16x16x32_bf16 v[36:39], v[166:169], v[228:231], v[36:39]
	v_mfma_f32_16x16x32_bf16 v[32:35], v[174:177], v[228:231], v[32:35]
	v_mfma_f32_16x16x32_bf16 v[20:23], v[166:169], v[236:239], v[20:23]
	v_mfma_f32_16x16x32_bf16 v[16:19], v[174:177], v[236:239], v[16:19]
	v_mfma_f32_16x16x32_bf16 v[4:7], v[166:169], v[244:247], v[4:7]
	v_mfma_f32_16x16x32_bf16 v[0:3], v[174:177], v[244:247], v[0:3]
	v_mfma_f32_16x16x32_bf16 v[52:55], v[170:173], v[224:227], v[52:55]
	v_mfma_f32_16x16x32_bf16 v[48:51], v[178:181], v[224:227], v[48:51]
	v_mfma_f32_16x16x32_bf16 v[36:39], v[170:173], v[232:235], v[36:39]
	v_mfma_f32_16x16x32_bf16 v[32:35], v[178:181], v[232:235], v[32:35]
	v_mfma_f32_16x16x32_bf16 v[20:23], v[170:173], v[240:243], v[20:23]
	v_mfma_f32_16x16x32_bf16 v[16:19], v[178:181], v[240:243], v[16:19]
	v_mfma_f32_16x16x32_bf16 v[4:7], v[170:173], v[248:251], v[4:7]
	v_mfma_f32_16x16x32_bf16 v[0:3], v[178:181], v[248:251], v[0:3]
	s_setprio 0
.Lk64_zj_p4_t:
	s_waitcnt vmcnt(0)
	s_barrier
	s_add_u32 vcc_lo, s34, 0x0
	s_addc_u32 vcc_hi, s35, 0
	s_add_i32 m0, s36, 0x2000
	s_nop 0
	global_load_lds_dwordx4 v130, vcc
	s_add_u32 vcc_lo, vcc_lo, 0x10000
	s_addc_u32 vcc_hi, vcc_hi, 0
	s_add_i32 m0, s36, 0x1000
	s_nop 0
	global_load_lds_dwordx4 v134, vcc
	s_add_u32 vcc_lo, vcc_lo, 0x30000
	s_addc_u32 vcc_hi, vcc_hi, 0
	s_add_i32 m0, s36, 0x6000
	s_nop 0
	global_load_lds_dwordx4 v130, vcc
	s_add_u32 vcc_lo, vcc_lo, 0x10000
	s_addc_u32 vcc_hi, vcc_hi, 0
	s_add_i32 m0, s36, 0x5000
	s_nop 0
	global_load_lds_dwordx4 v134, vcc
	s_add_u32 vcc_lo, s34, 0x80
	s_addc_u32 vcc_hi, s35, 0
	s_add_i32 m0, s36, 0x8000
	s_nop 0
	global_load_lds_dwordx4 v134, vcc
	s_sub_u32 vcc_lo, vcc_lo, 0x10000
	s_subb_u32 vcc_hi, vcc_hi, 0
	s_add_i32 m0, s36, 0x7000
	s_nop 0
	global_load_lds_dwordx4 v134, vcc
	s_add_u32 vcc_lo, vcc_lo, 0x50000
	s_addc_u32 vcc_hi, vcc_hi, 0
	s_add_i32 m0, s36, 0xc000
	s_nop 0
	global_load_lds_dwordx4 v134, vcc
	s_sub_u32 vcc_lo, vcc_lo, 0x10000
	s_subb_u32 vcc_hi, vcc_hi, 0
	s_add_i32 m0, s36, 0xb000
	s_nop 0
	global_load_lds_dwordx4 v134, vcc
	ds_read_b128 v[144:147], v151 offset:32768
	ds_read_b128 v[154:157], v151 offset:33792
	ds_read_b128 v[158:161], v151 offset:34816
	ds_read_b128 v[162:165], v151 offset:35840
	ds_read_b128 v[166:169], v152 offset:32768
	ds_read_b128 v[170:173], v152 offset:33792
	ds_read_b128 v[174:177], v152 offset:34816
	ds_read_b128 v[178:181], v152 offset:35840
	ds_read_b128 v[182:185], v153 offset:32768
	ds_read_b128 v[186:189], v153 offset:33792
	ds_read_b128 v[190:193], v153 offset:34816
	ds_read_b128 v[194:197], v153 offset:35840
	ds_read_b128 v[198:201], v153 offset:36864
	ds_read_b128 v[202:205], v153 offset:37888
	ds_read_b128 v[206:209], v153 offset:38912
	ds_read_b128 v[210:213], v153 offset:39936
	ds_read_b128 v[220:223], v153 offset:49152
	ds_read_b128 v[224:227], v153 offset:50176
	ds_read_b128 v[228:231], v153 offset:51200
	ds_read_b128 v[232:235], v153 offset:52224
	ds_read_b128 v[236:239], v153 offset:53248
	ds_read_b128 v[240:243], v153 offset:54272
	ds_read_b128 v[244:247], v153 offset:55296
	ds_read_b128 v[248:251], v153 offset:56320
	s_nop 15
	s_nop 15
	s_waitcnt lgkmcnt(0)
	s_barrier
	s_setprio 1
	v_mfma_f32_16x16x32_bf16 v[124:127], v[144:147], v[182:185], v[124:127]
	v_mfma_f32_16x16x32_bf16 v[120:123], v[158:161], v[182:185], v[120:123]
	v_mfma_f32_16x16x32_bf16 v[108:111], v[144:147], v[190:193], v[108:111]
	v_mfma_f32_16x16x32_bf16 v[104:107], v[158:161], v[190:193], v[104:107]
	v_mfma_f32_16x16x32_bf16 v[92:95], v[144:147], v[198:201], v[92:95]
	v_mfma_f32_16x16x32_bf16 v[88:91], v[158:161], v[198:201], v[88:91]
	v_mfma_f32_16x16x32_bf16 v[76:79], v[144:147], v[206:209], v[76:79]
	v_mfma_f32_16x16x32_bf16 v[72:75], v[158:161], v[206:209], v[72:75]
	v_mfma_f32_16x16x32_bf16 v[124:127], v[154:157], v[186:189], v[124:127]
	v_mfma_f32_16x16x32_bf16 v[120:123], v[162:165], v[186:189], v[120:123]
	v_mfma_f32_16x16x32_bf16 v[108:111], v[154:157], v[194:197], v[108:111]
	v_mfma_f32_16x16x32_bf16 v[104:107], v[162:165], v[194:197], v[104:107]
	v_mfma_f32_16x16x32_bf16 v[92:95], v[154:157], v[202:205], v[92:95]
	v_mfma_f32_16x16x32_bf16 v[88:91], v[162:165], v[202:205], v[88:91]
	v_mfma_f32_16x16x32_bf16 v[76:79], v[154:157], v[210:213], v[76:79]
	v_mfma_f32_16x16x32_bf16 v[72:75], v[162:165], v[210:213], v[72:75]
	s_setprio 0
	s_setprio 1
	v_mfma_f32_16x16x32_bf16 v[116:119], v[166:169], v[182:185], v[116:119]
	v_mfma_f32_16x16x32_bf16 v[112:115], v[174:177], v[182:185], v[112:115]
	v_mfma_f32_16x16x32_bf16 v[100:103], v[166:169], v[190:193], v[100:103]
	v_mfma_f32_16x16x32_bf16 v[96:99], v[174:177], v[190:193], v[96:99]
	v_mfma_f32_16x16x32_bf16 v[84:87], v[166:169], v[198:201], v[84:87]
	v_mfma_f32_16x16x32_bf16 v[80:83], v[174:177], v[198:201], v[80:83]
	v_mfma_f32_16x16x32_bf16 v[68:71], v[166:169], v[206:209], v[68:71]
	v_mfma_f32_16x16x32_bf16 v[64:67], v[174:177], v[206:209], v[64:67]
	v_mfma_f32_16x16x32_bf16 v[116:119], v[170:173], v[186:189], v[116:119]
	v_mfma_f32_16x16x32_bf16 v[112:115], v[178:181], v[186:189], v[112:115]
	v_mfma_f32_16x16x32_bf16 v[100:103], v[170:173], v[194:197], v[100:103]
	v_mfma_f32_16x16x32_bf16 v[96:99], v[178:181], v[194:197], v[96:99]
	v_mfma_f32_16x16x32_bf16 v[84:87], v[170:173], v[202:205], v[84:87]
	v_mfma_f32_16x16x32_bf16 v[80:83], v[178:181], v[202:205], v[80:83]
	v_mfma_f32_16x16x32_bf16 v[68:71], v[170:173], v[210:213], v[68:71]
	v_mfma_f32_16x16x32_bf16 v[64:67], v[178:181], v[210:213], v[64:67]
	s_setprio 0
	s_setprio 1
	v_mfma_f32_16x16x32_bf16 v[60:63], v[144:147], v[220:223], v[60:63]
	v_mfma_f32_16x16x32_bf16 v[56:59], v[158:161], v[220:223], v[56:59]
	v_mfma_f32_16x16x32_bf16 v[44:47], v[144:147], v[228:231], v[44:47]
	v_mfma_f32_16x16x32_bf16 v[40:43], v[158:161], v[228:231], v[40:43]
	v_mfma_f32_16x16x32_bf16 v[28:31], v[144:147], v[236:239], v[28:31]
	v_mfma_f32_16x16x32_bf16 v[24:27], v[158:161], v[236:239], v[24:27]
	v_mfma_f32_16x16x32_bf16 v[12:15], v[144:147], v[244:247], v[12:15]
	v_mfma_f32_16x16x32_bf16 v[8:11], v[158:161], v[244:247], v[8:11]
	v_mfma_f32_16x16x32_bf16 v[60:63], v[154:157], v[224:227], v[60:63]
	v_mfma_f32_16x16x32_bf16 v[56:59], v[162:165], v[224:227], v[56:59]
	v_mfma_f32_16x16x32_bf16 v[44:47], v[154:157], v[232:235], v[44:47]
	v_mfma_f32_16x16x32_bf16 v[40:43], v[162:165], v[232:235], v[40:43]
	v_mfma_f32_16x16x32_bf16 v[28:31], v[154:157], v[240:243], v[28:31]
	v_mfma_f32_16x16x32_bf16 v[24:27], v[162:165], v[240:243], v[24:27]
	v_mfma_f32_16x16x32_bf16 v[12:15], v[154:157], v[248:251], v[12:15]
	v_mfma_f32_16x16x32_bf16 v[8:11], v[162:165], v[248:251], v[8:11]
	s_setprio 0
	s_setprio 1
	v_mfma_f32_16x16x32_bf16 v[52:55], v[166:169], v[220:223], v[52:55]
	v_mfma_f32_16x16x32_bf16 v[48:51], v[174:177], v[220:223], v[48:51]
	v_mfma_f32_16x16x32_bf16 v[36:39], v[166:169], v[228:231], v[36:39]
	v_mfma_f32_16x16x32_bf16 v[32:35], v[174:177], v[228:231], v[32:35]
	v_mfma_f32_16x16x32_bf16 v[20:23], v[166:169], v[236:239], v[20:23]
	v_mfma_f32_16x16x32_bf16 v[16:19], v[174:177], v[236:239], v[16:19]
	v_mfma_f32_16x16x32_bf16 v[4:7], v[166:169], v[244:247], v[4:7]
	v_mfma_f32_16x16x32_bf16 v[0:3], v[174:177], v[244:247], v[0:3]
	v_mfma_f32_16x16x32_bf16 v[52:55], v[170:173], v[224:227], v[52:55]
	v_mfma_f32_16x16x32_bf16 v[48:51], v[178:181], v[224:227], v[48:51]
	v_mfma_f32_16x16x32_bf16 v[36:39], v[170:173], v[232:235], v[36:39]
	v_mfma_f32_16x16x32_bf16 v[32:35], v[178:181], v[232:235], v[32:35]
	v_mfma_f32_16x16x32_bf16 v[20:23], v[170:173], v[240:243], v[20:23]
	v_mfma_f32_16x16x32_bf16 v[16:19], v[178:181], v[240:243], v[16:19]
	v_mfma_f32_16x16x32_bf16 v[4:7], v[170:173], v[248:251], v[4:7]
	v_mfma_f32_16x16x32_bf16 v[0:3], v[178:181], v[248:251], v[0:3]
	s_setprio 0
	s_waitcnt vmcnt(0)
	s_barrier
	s_add_i32 s56, s56, 2
	s_add_u32 s12, s12, 0x100
	s_addc_u32 s13, s13, 0
	s_add_u32 s54, s54, 0x100
	s_addc_u32 s55, s55, 0
	s_cmp_gt_u32 s56, 13
	s_cbranch_scc0 .LBB0_686
	s_branch .Lk64_done_p4

.LBB0_760:
	s_ashr_i32 s23, s22, 31
	s_lshl_b64 s[24:25], s[22:23], 20
	s_add_u32 s24, s16, s24
	s_addc_u32 s25, s17, s25
	s_and_b64 s[26:27], s[40:41], exec
	s_cselect_b32 s23, s25, s35
	s_cselect_b32 s29, s24, s34
	s_ashr_i32 s13, s12, 31
	s_lshl_b64 s[26:27], s[12:13], 20
	v_readlane_b32 s42, v255, 19
	v_readlane_b32 s43, v255, 20
	s_add_u32 s26, s42, s26
	s_addc_u32 s27, s43, s27
	s_and_b64 s[42:43], s[40:41], exec
	s_cselect_b32 s13, s27, s37
	s_cselect_b32 s31, s26, s36
	s_add_u32 s34, s34, 0x80080
	s_addc_u32 s35, s35, 0
	s_add_u32 s56, s36, 0x100
	s_addc_u32 s57, s37, 0
	s_mov_b32 s58, -2
	s_waitcnt lgkmcnt(0)
.LBB0_761:
	s_add_u32 s36, s34, 0xfff80080
	s_addc_u32 s37, s35, -1
	s_cmp_eq_u32 s58, 28
	s_cselect_b32 s43, s23, s37
	s_cselect_b32 s42, s29, s36
	s_cselect_b32 s37, s13, s57
	s_cselect_b32 s36, s31, s56
	s_and_b64 vcc, exec, s[10:11]
	s_cbranch_vccz .Lk64_trail_p5
	s_sub_u32 vcc_lo, s56, 0x80
	s_subb_u32 vcc_hi, s57, 0
	s_add_i32 m0, s44, 0x18000
	s_nop 0
	global_load_lds_dwordx4 v130, vcc
	s_add_i32 m0, s44, 0x1a000
	s_nop 0
	global_load_lds_dwordx4 v134, vcc
	s_add_u32 vcc_lo, vcc_lo, 0x20000
	s_addc_u32 vcc_hi, vcc_hi, 0
	s_add_i32 m0, s44, 0x19000
	s_nop 0
	global_load_lds_dwordx4 v130, vcc
	s_add_i32 m0, s44, 0x1b000
	s_nop 0
	global_load_lds_dwordx4 v134, vcc
	s_add_u32 vcc_lo, vcc_lo, 0x60000
	s_addc_u32 vcc_hi, vcc_hi, 0
	s_add_i32 m0, s44, 0x1c000
	s_nop 0
	global_load_lds_dwordx4 v130, vcc
	s_add_i32 m0, s44, 0x1e000
	s_nop 0
	global_load_lds_dwordx4 v134, vcc
	s_add_u32 vcc_lo, vcc_lo, 0x20000
	s_addc_u32 vcc_hi, vcc_hi, 0
	s_add_i32 m0, s44, 0x1d000
	s_nop 0
	global_load_lds_dwordx4 v130, vcc
	s_add_i32 m0, s44, 0x1f000
	s_nop 0
	global_load_lds_dwordx4 v134, vcc
	ds_read_b128 v[144:147], v153 offset:0
	ds_read_b128 v[158:161], v153 offset:1024
	ds_read_b128 v[162:165], v153 offset:2048
	ds_read_b128 v[166:169], v153 offset:3072
	ds_read_b128 v[170:173], v154 offset:0
	ds_read_b128 v[174:177], v154 offset:1024
	ds_read_b128 v[178:181], v154 offset:2048
	ds_read_b128 v[182:185], v154 offset:3072
	ds_read_b128 v[186:189], v155 offset:0
	ds_read_b128 v[190:193], v155 offset:1024
	ds_read_b128 v[194:197], v155 offset:2048
	ds_read_b128 v[198:201], v155 offset:3072
	ds_read_b128 v[202:205], v155 offset:4096
	ds_read_b128 v[206:209], v155 offset:5120
	ds_read_b128 v[210:213], v155 offset:6144
	ds_read_b128 v[214:217], v155 offset:7168
	ds_read_b128 v[220:223], v155 offset:16384
	ds_read_b128 v[224:227], v155 offset:17408
	ds_read_b128 v[228:231], v155 offset:18432
	ds_read_b128 v[232:235], v155 offset:19456
	ds_read_b128 v[236:239], v155 offset:20480
	ds_read_b128 v[240:243], v155 offset:21504
	ds_read_b128 v[244:247], v155 offset:22528
	ds_read_b128 v[248:251], v155 offset:23552
	s_nop 15
	s_nop 15
	s_waitcnt lgkmcnt(0)
	s_barrier
	s_cmp_eq_i32 s58, -2
	s_cbranch_scc1 .Lk64_z_p5_l
	s_setprio 1
	v_mfma_f32_16x16x32_bf16 v[124:127], v[144:147], v[186:189], v[124:127]
	v_mfma_f32_16x16x32_bf16 v[120:123], v[162:165], v[186:189], v[120:123]
	v_mfma_f32_16x16x32_bf16 v[108:111], v[144:147], v[194:197], v[108:111]
	v_mfma_f32_16x16x32_bf16 v[104:107], v[162:165], v[194:197], v[104:107]
	v_mfma_f32_16x16x32_bf16 v[92:95], v[144:147], v[202:205], v[92:95]
	v_mfma_f32_16x16x32_bf16 v[88:91], v[162:165], v[202:205], v[88:91]
	v_mfma_f32_16x16x32_bf16 v[76:79], v[144:147], v[210:213], v[76:79]
	v_mfma_f32_16x16x32_bf16 v[72:75], v[162:165], v[210:213], v[72:75]
	v_mfma_f32_16x16x32_bf16 v[124:127], v[158:161], v[190:193], v[124:127]
	v_mfma_f32_16x16x32_bf16 v[120:123], v[166:169], v[190:193], v[120:123]
	v_mfma_f32_16x16x32_bf16 v[108:111], v[158:161], v[198:201], v[108:111]
	v_mfma_f32_16x16x32_bf16 v[104:107], v[166:169], v[198:201], v[104:107]
	v_mfma_f32_16x16x32_bf16 v[92:95], v[158:161], v[206:209], v[92:95]
	v_mfma_f32_16x16x32_bf16 v[88:91], v[166:169], v[206:209], v[88:91]
	v_mfma_f32_16x16x32_bf16 v[76:79], v[158:161], v[214:217], v[76:79]
	v_mfma_f32_16x16x32_bf16 v[72:75], v[166:169], v[214:217], v[72:75]
	s_setprio 0
	s_setprio 1
	v_mfma_f32_16x16x32_bf16 v[116:119], v[170:173], v[186:189], v[116:119]
	v_mfma_f32_16x16x32_bf16 v[112:115], v[178:181], v[186:189], v[112:115]
	v_mfma_f32_16x16x32_bf16 v[100:103], v[170:173], v[194:197], v[100:103]
	v_mfma_f32_16x16x32_bf16 v[96:99], v[178:181], v[194:197], v[96:99]
	v_mfma_f32_16x16x32_bf16 v[84:87], v[170:173], v[202:205], v[84:87]
	v_mfma_f32_16x16x32_bf16 v[80:83], v[178:181], v[202:205], v[80:83]
	v_mfma_f32_16x16x32_bf16 v[68:71], v[170:173], v[210:213], v[68:71]
	v_mfma_f32_16x16x32_bf16 v[64:67], v[178:181], v[210:213], v[64:67]
	v_mfma_f32_16x16x32_bf16 v[116:119], v[174:177], v[190:193], v[116:119]
	v_mfma_f32_16x16x32_bf16 v[112:115], v[182:185], v[190:193], v[112:115]
	v_mfma_f32_16x16x32_bf16 v[100:103], v[174:177], v[198:201], v[100:103]
	v_mfma_f32_16x16x32_bf16 v[96:99], v[182:185], v[198:201], v[96:99]
	v_mfma_f32_16x16x32_bf16 v[84:87], v[174:177], v[206:209], v[84:87]
	v_mfma_f32_16x16x32_bf16 v[80:83], v[182:185], v[206:209], v[80:83]
	v_mfma_f32_16x16x32_bf16 v[68:71], v[174:177], v[214:217], v[68:71]
	v_mfma_f32_16x16x32_bf16 v[64:67], v[182:185], v[214:217], v[64:67]
	s_setprio 0
	s_setprio 1
	v_mfma_f32_16x16x32_bf16 v[60:63], v[144:147], v[220:223], v[60:63]
	v_mfma_f32_16x16x32_bf16 v[56:59], v[162:165], v[220:223], v[56:59]
	v_mfma_f32_16x16x32_bf16 v[44:47], v[144:147], v[228:231], v[44:47]
	v_mfma_f32_16x16x32_bf16 v[40:43], v[162:165], v[228:231], v[40:43]
	v_mfma_f32_16x16x32_bf16 v[28:31], v[144:147], v[236:239], v[28:31]
	v_mfma_f32_16x16x32_bf16 v[24:27], v[162:165], v[236:239], v[24:27]
	v_mfma_f32_16x16x32_bf16 v[12:15], v[144:147], v[244:247], v[12:15]
	v_mfma_f32_16x16x32_bf16 v[8:11], v[162:165], v[244:247], v[8:11]
	v_mfma_f32_16x16x32_bf16 v[60:63], v[158:161], v[224:227], v[60:63]
	v_mfma_f32_16x16x32_bf16 v[56:59], v[166:169], v[224:227], v[56:59]
	v_mfma_f32_16x16x32_bf16 v[44:47], v[158:161], v[232:235], v[44:47]
	v_mfma_f32_16x16x32_bf16 v[40:43], v[166:169], v[232:235], v[40:43]
	v_mfma_f32_16x16x32_bf16 v[28:31], v[158:161], v[240:243], v[28:31]
	v_mfma_f32_16x16x32_bf16 v[24:27], v[166:169], v[240:243], v[24:27]
	v_mfma_f32_16x16x32_bf16 v[12:15], v[158:161], v[248:251], v[12:15]
	v_mfma_f32_16x16x32_bf16 v[8:11], v[166:169], v[248:251], v[8:11]
	s_setprio 0
	s_setprio 1
	v_mfma_f32_16x16x32_bf16 v[52:55], v[170:173], v[220:223], v[52:55]
	v_mfma_f32_16x16x32_bf16 v[48:51], v[178:181], v[220:223], v[48:51]
	v_mfma_f32_16x16x32_bf16 v[36:39], v[170:173], v[228:231], v[36:39]
	v_mfma_f32_16x16x32_bf16 v[32:35], v[178:181], v[228:231], v[32:35]
	v_mfma_f32_16x16x32_bf16 v[20:23], v[170:173], v[236:239], v[20:23]
	v_mfma_f32_16x16x32_bf16 v[16:19], v[178:181], v[236:239], v[16:19]
	v_mfma_f32_16x16x32_bf16 v[4:7], v[170:173], v[244:247], v[4:7]
	v_mfma_f32_16x16x32_bf16 v[0:3], v[178:181], v[244:247], v[0:3]
	v_mfma_f32_16x16x32_bf16 v[52:55], v[174:177], v[224:227], v[52:55]
	v_mfma_f32_16x16x32_bf16 v[48:51], v[182:185], v[224:227], v[48:51]
	v_mfma_f32_16x16x32_bf16 v[36:39], v[174:177], v[232:235], v[36:39]
	v_mfma_f32_16x16x32_bf16 v[32:35], v[182:185], v[232:235], v[32:35]
	v_mfma_f32_16x16x32_bf16 v[20:23], v[174:177], v[240:243], v[20:23]
	v_mfma_f32_16x16x32_bf16 v[16:19], v[182:185], v[240:243], v[16:19]
	v_mfma_f32_16x16x32_bf16 v[4:7], v[174:177], v[248:251], v[4:7]
	v_mfma_f32_16x16x32_bf16 v[0:3], v[182:185], v[248:251], v[0:3]
	s_setprio 0
.Lk64_zj_p5_l:
	s_waitcnt vmcnt(0)
	s_barrier
	s_add_u32 vcc_lo, s36, 0x0
	s_addc_u32 vcc_hi, s37, 0
	s_add_i32 m0, s44, 0x10000
	s_nop 0
	global_load_lds_dwordx4 v130, vcc
	s_add_i32 m0, s44, 0x12000
	s_nop 0
	global_load_lds_dwordx4 v134, vcc
	s_add_u32 vcc_lo, vcc_lo, 0x20000
	s_addc_u32 vcc_hi, vcc_hi, 0
	s_add_i32 m0, s44, 0x11000
	s_nop 0
	global_load_lds_dwordx4 v130, vcc
	s_add_i32 m0, s44, 0x13000
	s_nop 0
	global_load_lds_dwordx4 v134, vcc
	s_add_u32 vcc_lo, vcc_lo, 0x60000
	s_addc_u32 vcc_hi, vcc_hi, 0
	s_add_i32 m0, s44, 0x14000
	s_nop 0
	global_load_lds_dwordx4 v130, vcc
	s_add_i32 m0, s44, 0x16000
	s_nop 0
	global_load_lds_dwordx4 v134, vcc
	s_add_u32 vcc_lo, vcc_lo, 0x20000
	s_addc_u32 vcc_hi, vcc_hi, 0
	s_add_i32 m0, s44, 0x15000
	s_nop 0
	global_load_lds_dwordx4 v130, vcc
	s_add_i32 m0, s44, 0x17000
	s_nop 0
	global_load_lds_dwordx4 v134, vcc
	ds_read_b128 v[144:147], v153 offset:32768
	ds_read_b128 v[158:161], v153 offset:33792
	ds_read_b128 v[162:165], v153 offset:34816
	ds_read_b128 v[166:169], v153 offset:35840
	ds_read_b128 v[170:173], v154 offset:32768
	ds_read_b128 v[174:177], v154 offset:33792
	ds_read_b128 v[178:181], v154 offset:34816
	ds_read_b128 v[182:185], v154 offset:35840
	ds_read_b128 v[186:189], v155 offset:32768
	ds_read_b128 v[190:193], v155 offset:33792
	ds_read_b128 v[194:197], v155 offset:34816
	ds_read_b128 v[198:201], v155 offset:35840
	ds_read_b128 v[202:205], v155 offset:36864
	ds_read_b128 v[206:209], v155 offset:37888
	ds_read_b128 v[210:213], v155 offset:38912
	ds_read_b128 v[214:217], v155 offset:39936
	ds_read_b128 v[220:223], v155 offset:49152
	ds_read_b128 v[224:227], v155 offset:50176
	ds_read_b128 v[228:231], v155 offset:51200
	ds_read_b128 v[232:235], v155 offset:52224
	ds_read_b128 v[236:239], v155 offset:53248
	ds_read_b128 v[240:243], v155 offset:54272
	ds_read_b128 v[244:247], v155 offset:55296
	ds_read_b128 v[248:251], v155 offset:56320
	s_nop 15
	s_nop 15
	s_waitcnt lgkmcnt(0)
	s_barrier
	s_setprio 1
	v_mfma_f32_16x16x32_bf16 v[124:127], v[144:147], v[186:189], v[124:127]
	v_mfma_f32_16x16x32_bf16 v[120:123], v[162:165], v[186:189], v[120:123]
	v_mfma_f32_16x16x32_bf16 v[108:111], v[144:147], v[194:197], v[108:111]
	v_mfma_f32_16x16x32_bf16 v[104:107], v[162:165], v[194:197], v[104:107]
	v_mfma_f32_16x16x32_bf16 v[92:95], v[144:147], v[202:205], v[92:95]
	v_mfma_f32_16x16x32_bf16 v[88:91], v[162:165], v[202:205], v[88:91]
	v_mfma_f32_16x16x32_bf16 v[76:79], v[144:147], v[210:213], v[76:79]
	v_mfma_f32_16x16x32_bf16 v[72:75], v[162:165], v[210:213], v[72:75]
	v_mfma_f32_16x16x32_bf16 v[124:127], v[158:161], v[190:193], v[124:127]
	v_mfma_f32_16x16x32_bf16 v[120:123], v[166:169], v[190:193], v[120:123]
	v_mfma_f32_16x16x32_bf16 v[108:111], v[158:161], v[198:201], v[108:111]
	v_mfma_f32_16x16x32_bf16 v[104:107], v[166:169], v[198:201], v[104:107]
	v_mfma_f32_16x16x32_bf16 v[92:95], v[158:161], v[206:209], v[92:95]
	v_mfma_f32_16x16x32_bf16 v[88:91], v[166:169], v[206:209], v[88:91]
	v_mfma_f32_16x16x32_bf16 v[76:79], v[158:161], v[214:217], v[76:79]
	v_mfma_f32_16x16x32_bf16 v[72:75], v[166:169], v[214:217], v[72:75]
	s_setprio 0
	s_setprio 1
	v_mfma_f32_16x16x32_bf16 v[116:119], v[170:173], v[186:189], v[116:119]
	v_mfma_f32_16x16x32_bf16 v[112:115], v[178:181], v[186:189], v[112:115]
	v_mfma_f32_16x16x32_bf16 v[100:103], v[170:173], v[194:197], v[100:103]
	v_mfma_f32_16x16x32_bf16 v[96:99], v[178:181], v[194:197], v[96:99]
	v_mfma_f32_16x16x32_bf16 v[84:87], v[170:173], v[202:205], v[84:87]
	v_mfma_f32_16x16x32_bf16 v[80:83], v[178:181], v[202:205], v[80:83]
	v_mfma_f32_16x16x32_bf16 v[68:71], v[170:173], v[210:213], v[68:71]
	v_mfma_f32_16x16x32_bf16 v[64:67], v[178:181], v[210:213], v[64:67]
	v_mfma_f32_16x16x32_bf16 v[116:119], v[174:177], v[190:193], v[116:119]
	v_mfma_f32_16x16x32_bf16 v[112:115], v[182:185], v[190:193], v[112:115]
	v_mfma_f32_16x16x32_bf16 v[100:103], v[174:177], v[198:201], v[100:103]
	v_mfma_f32_16x16x32_bf16 v[96:99], v[182:185], v[198:201], v[96:99]
	v_mfma_f32_16x16x32_bf16 v[84:87], v[174:177], v[206:209], v[84:87]
	v_mfma_f32_16x16x32_bf16 v[80:83], v[182:185], v[206:209], v[80:83]
	v_mfma_f32_16x16x32_bf16 v[68:71], v[174:177], v[214:217], v[68:71]
	v_mfma_f32_16x16x32_bf16 v[64:67], v[182:185], v[214:217], v[64:67]
	s_setprio 0
	s_setprio 1
	v_mfma_f32_16x16x32_bf16 v[60:63], v[144:147], v[220:223], v[60:63]
	v_mfma_f32_16x16x32_bf16 v[56:59], v[162:165], v[220:223], v[56:59]
	v_mfma_f32_16x16x32_bf16 v[44:47], v[144:147], v[228:231], v[44:47]
	v_mfma_f32_16x16x32_bf16 v[40:43], v[162:165], v[228:231], v[40:43]
	v_mfma_f32_16x16x32_bf16 v[28:31], v[144:147], v[236:239], v[28:31]
	v_mfma_f32_16x16x32_bf16 v[24:27], v[162:165], v[236:239], v[24:27]
	v_mfma_f32_16x16x32_bf16 v[12:15], v[144:147], v[244:247], v[12:15]
	v_mfma_f32_16x16x32_bf16 v[8:11], v[162:165], v[244:247], v[8:11]
	v_mfma_f32_16x16x32_bf16 v[60:63], v[158:161], v[224:227], v[60:63]
	v_mfma_f32_16x16x32_bf16 v[56:59], v[166:169], v[224:227], v[56:59]
	v_mfma_f32_16x16x32_bf16 v[44:47], v[158:161], v[232:235], v[44:47]
	v_mfma_f32_16x16x32_bf16 v[40:43], v[166:169], v[232:235], v[40:43]
	v_mfma_f32_16x16x32_bf16 v[28:31], v[158:161], v[240:243], v[28:31]
	v_mfma_f32_16x16x32_bf16 v[24:27], v[166:169], v[240:243], v[24:27]
	v_mfma_f32_16x16x32_bf16 v[12:15], v[158:161], v[248:251], v[12:15]
	v_mfma_f32_16x16x32_bf16 v[8:11], v[166:169], v[248:251], v[8:11]
	s_setprio 0
	s_setprio 1
	v_mfma_f32_16x16x32_bf16 v[52:55], v[170:173], v[220:223], v[52:55]
	v_mfma_f32_16x16x32_bf16 v[48:51], v[178:181], v[220:223], v[48:51]
	v_mfma_f32_16x16x32_bf16 v[36:39], v[170:173], v[228:231], v[36:39]
	v_mfma_f32_16x16x32_bf16 v[32:35], v[178:181], v[228:231], v[32:35]
	v_mfma_f32_16x16x32_bf16 v[20:23], v[170:173], v[236:239], v[20:23]
	v_mfma_f32_16x16x32_bf16 v[16:19], v[178:181], v[236:239], v[16:19]
	v_mfma_f32_16x16x32_bf16 v[4:7], v[170:173], v[244:247], v[4:7]
	v_mfma_f32_16x16x32_bf16 v[0:3], v[178:181], v[244:247], v[0:3]
	v_mfma_f32_16x16x32_bf16 v[52:55], v[174:177], v[224:227], v[52:55]
	v_mfma_f32_16x16x32_bf16 v[48:51], v[182:185], v[224:227], v[48:51]
	v_mfma_f32_16x16x32_bf16 v[36:39], v[174:177], v[232:235], v[36:39]
	v_mfma_f32_16x16x32_bf16 v[32:35], v[182:185], v[232:235], v[32:35]
	v_mfma_f32_16x16x32_bf16 v[20:23], v[174:177], v[240:243], v[20:23]
	v_mfma_f32_16x16x32_bf16 v[16:19], v[182:185], v[240:243], v[16:19]
	v_mfma_f32_16x16x32_bf16 v[4:7], v[174:177], v[248:251], v[4:7]
	v_mfma_f32_16x16x32_bf16 v[0:3], v[182:185], v[248:251], v[0:3]
	s_setprio 0
	s_waitcnt vmcnt(0)
	s_barrier
	s_add_i32 s58, s58, 2
	s_add_u32 s34, s34, 0x100
	s_addc_u32 s35, s35, 0
	s_add_u32 s56, s56, 0x100
	s_addc_u32 s57, s57, 0
	s_cmp_gt_u32 s58, 29
	s_cbranch_scc0 .LBB0_761
	s_branch .Lk64_done_p5
.Lk64_z_p5_l:
	s_setprio 1
	v_mfma_f32_16x16x32_bf16 v[124:127], v[144:147], v[186:189], 0
	v_mfma_f32_16x16x32_bf16 v[120:123], v[162:165], v[186:189], 0
	v_mfma_f32_16x16x32_bf16 v[108:111], v[144:147], v[194:197], 0
	v_mfma_f32_16x16x32_bf16 v[104:107], v[162:165], v[194:197], 0
	v_mfma_f32_16x16x32_bf16 v[92:95], v[144:147], v[202:205], 0
	v_mfma_f32_16x16x32_bf16 v[88:91], v[162:165], v[202:205], 0
	v_mfma_f32_16x16x32_bf16 v[76:79], v[144:147], v[210:213], 0
	v_mfma_f32_16x16x32_bf16 v[72:75], v[162:165], v[210:213], 0
	v_mfma_f32_16x16x32_bf16 v[124:127], v[158:161], v[190:193], v[124:127]
	v_mfma_f32_16x16x32_bf16 v[120:123], v[166:169], v[190:193], v[120:123]
	v_mfma_f32_16x16x32_bf16 v[108:111], v[158:161], v[198:201], v[108:111]
	v_mfma_f32_16x16x32_bf16 v[104:107], v[166:169], v[198:201], v[104:107]
	v_mfma_f32_16x16x32_bf16 v[92:95], v[158:161], v[206:209], v[92:95]
	v_mfma_f32_16x16x32_bf16 v[88:91], v[166:169], v[206:209], v[88:91]
	v_mfma_f32_16x16x32_bf16 v[76:79], v[158:161], v[214:217], v[76:79]
	v_mfma_f32_16x16x32_bf16 v[72:75], v[166:169], v[214:217], v[72:75]
	s_setprio 0
	s_setprio 1
	v_mfma_f32_16x16x32_bf16 v[116:119], v[170:173], v[186:189], 0
	v_mfma_f32_16x16x32_bf16 v[112:115], v[178:181], v[186:189], 0
	v_mfma_f32_16x16x32_bf16 v[100:103], v[170:173], v[194:197], 0
	v_mfma_f32_16x16x32_bf16 v[96:99], v[178:181], v[194:197], 0
	v_mfma_f32_16x16x32_bf16 v[84:87], v[170:173], v[202:205], 0
	v_mfma_f32_16x16x32_bf16 v[80:83], v[178:181], v[202:205], 0
	v_mfma_f32_16x16x32_bf16 v[68:71], v[170:173], v[210:213], 0
	v_mfma_f32_16x16x32_bf16 v[64:67], v[178:181], v[210:213], 0
	v_mfma_f32_16x16x32_bf16 v[116:119], v[174:177], v[190:193], v[116:119]
	v_mfma_f32_16x16x32_bf16 v[112:115], v[182:185], v[190:193], v[112:115]
	v_mfma_f32_16x16x32_bf16 v[100:103], v[174:177], v[198:201], v[100:103]
	v_mfma_f32_16x16x32_bf16 v[96:99], v[182:185], v[198:201], v[96:99]
	v_mfma_f32_16x16x32_bf16 v[84:87], v[174:177], v[206:209], v[84:87]
	v_mfma_f32_16x16x32_bf16 v[80:83], v[182:185], v[206:209], v[80:83]
	v_mfma_f32_16x16x32_bf16 v[68:71], v[174:177], v[214:217], v[68:71]
	v_mfma_f32_16x16x32_bf16 v[64:67], v[182:185], v[214:217], v[64:67]
	s_setprio 0
	s_setprio 1
	v_mfma_f32_16x16x32_bf16 v[60:63], v[144:147], v[220:223], 0
	v_mfma_f32_16x16x32_bf16 v[56:59], v[162:165], v[220:223], 0
	v_mfma_f32_16x16x32_bf16 v[44:47], v[144:147], v[228:231], 0
	v_mfma_f32_16x16x32_bf16 v[40:43], v[162:165], v[228:231], 0
	v_mfma_f32_16x16x32_bf16 v[28:31], v[144:147], v[236:239], 0
	v_mfma_f32_16x16x32_bf16 v[24:27], v[162:165], v[236:239], 0
	v_mfma_f32_16x16x32_bf16 v[12:15], v[144:147], v[244:247], 0
	v_mfma_f32_16x16x32_bf16 v[8:11], v[162:165], v[244:247], 0
	v_mfma_f32_16x16x32_bf16 v[60:63], v[158:161], v[224:227], v[60:63]
	v_mfma_f32_16x16x32_bf16 v[56:59], v[166:169], v[224:227], v[56:59]
	v_mfma_f32_16x16x32_bf16 v[44:47], v[158:161], v[232:235], v[44:47]
	v_mfma_f32_16x16x32_bf16 v[40:43], v[166:169], v[232:235], v[40:43]
	v_mfma_f32_16x16x32_bf16 v[28:31], v[158:161], v[240:243], v[28:31]
	v_mfma_f32_16x16x32_bf16 v[24:27], v[166:169], v[240:243], v[24:27]
	v_mfma_f32_16x16x32_bf16 v[12:15], v[158:161], v[248:251], v[12:15]
	v_mfma_f32_16x16x32_bf16 v[8:11], v[166:169], v[248:251], v[8:11]
	s_setprio 0
	s_setprio 1
	v_mfma_f32_16x16x32_bf16 v[52:55], v[170:173], v[220:223], 0
	v_mfma_f32_16x16x32_bf16 v[48:51], v[178:181], v[220:223], 0
	v_mfma_f32_16x16x32_bf16 v[36:39], v[170:173], v[228:231], 0
	v_mfma_f32_16x16x32_bf16 v[32:35], v[178:181], v[228:231], 0
	v_mfma_f32_16x16x32_bf16 v[20:23], v[170:173], v[236:239], 0
	v_mfma_f32_16x16x32_bf16 v[16:19], v[178:181], v[236:239], 0
	v_mfma_f32_16x16x32_bf16 v[4:7], v[170:173], v[244:247], 0
	v_mfma_f32_16x16x32_bf16 v[0:3], v[178:181], v[244:247], 0
	v_mfma_f32_16x16x32_bf16 v[52:55], v[174:177], v[224:227], v[52:55]
	v_mfma_f32_16x16x32_bf16 v[48:51], v[182:185], v[224:227], v[48:51]
	v_mfma_f32_16x16x32_bf16 v[36:39], v[174:177], v[232:235], v[36:39]
	v_mfma_f32_16x16x32_bf16 v[32:35], v[182:185], v[232:235], v[32:35]
	v_mfma_f32_16x16x32_bf16 v[20:23], v[174:177], v[240:243], v[20:23]
	v_mfma_f32_16x16x32_bf16 v[16:19], v[182:185], v[240:243], v[16:19]
	v_mfma_f32_16x16x32_bf16 v[4:7], v[174:177], v[248:251], v[4:7]
	v_mfma_f32_16x16x32_bf16 v[0:3], v[182:185], v[248:251], v[0:3]
	s_setprio 0
	s_branch .Lk64_zj_p5_l
.Lk64_trail_p5:
	s_sub_u32 vcc_lo, s34, 0x80000
	s_subb_u32 vcc_hi, s35, 0
	s_add_i32 m0, s44, 0xa000
	s_nop 0
	global_load_lds_dwordx4 v132, vcc
	s_add_u32 vcc_lo, vcc_lo, 0x20000
	s_addc_u32 vcc_hi, vcc_hi, 0
	s_add_i32 m0, s44, 0x9000
	s_nop 0
	global_load_lds_dwordx4 v128, vcc
	s_add_u32 vcc_lo, vcc_lo, 0x60000
	s_addc_u32 vcc_hi, vcc_hi, 0
	s_add_i32 m0, s44, 0xe000
	s_nop 0
	global_load_lds_dwordx4 v132, vcc
	s_add_u32 vcc_lo, vcc_lo, 0x20000
	s_addc_u32 vcc_hi, vcc_hi, 0
	s_add_i32 m0, s44, 0xd000
	s_nop 0
	global_load_lds_dwordx4 v128, vcc
	s_add_u32 vcc_lo, s42, 0x0
	s_addc_u32 vcc_hi, s43, 0
	s_mov_b32 m0, s44
	s_nop 0
	global_load_lds_dwordx4 v128, vcc
	s_sub_u32 vcc_lo, vcc_lo, 0x20000
	s_subb_u32 vcc_hi, vcc_hi, 0
	s_sub_i32 m0, s44, 0x1000
	s_nop 0
	global_load_lds_dwordx4 v128, vcc
	s_add_u32 vcc_lo, vcc_lo, 0xa0000
	s_addc_u32 vcc_hi, vcc_hi, 0
	s_add_i32 m0, s44, 0x4000
	s_nop 0
	global_load_lds_dwordx4 v128, vcc
	s_sub_u32 vcc_lo, vcc_lo, 0x20000
	s_subb_u32 vcc_hi, vcc_hi, 0
	s_add_i32 m0, s44, 0x3000
	s_nop 0
	global_load_lds_dwordx4 v128, vcc
	ds_read_b128 v[144:147], v153 offset:0
	ds_read_b128 v[158:161], v153 offset:1024
	ds_read_b128 v[162:165], v153 offset:2048
	ds_read_b128 v[166:169], v153 offset:3072
	ds_read_b128 v[170:173], v154 offset:0
	ds_read_b128 v[174:177], v154 offset:1024
	ds_read_b128 v[178:181], v154 offset:2048
	ds_read_b128 v[182:185], v154 offset:3072
	ds_read_b128 v[186:189], v155 offset:0
	ds_read_b128 v[190:193], v155 offset:1024
	ds_read_b128 v[194:197], v155 offset:2048
	ds_read_b128 v[198:201], v155 offset:3072
	ds_read_b128 v[202:205], v155 offset:4096
	ds_read_b128 v[206:209], v155 offset:5120
	ds_read_b128 v[210:213], v155 offset:6144
	ds_read_b128 v[214:217], v155 offset:7168
	ds_read_b128 v[220:223], v155 offset:16384
	ds_read_b128 v[224:227], v155 offset:17408
	ds_read_b128 v[228:231], v155 offset:18432
	ds_read_b128 v[232:235], v155 offset:19456
	ds_read_b128 v[236:239], v155 offset:20480
	ds_read_b128 v[240:243], v155 offset:21504
	ds_read_b128 v[244:247], v155 offset:22528
	ds_read_b128 v[248:251], v155 offset:23552
	s_nop 15
	s_nop 15
	s_waitcnt lgkmcnt(0)
	s_barrier
	s_cmp_eq_i32 s58, -2
	s_cbranch_scc1 .Lk64_z_p5_t
	s_setprio 1
	v_mfma_f32_16x16x32_bf16 v[124:127], v[144:147], v[186:189], v[124:127]
	v_mfma_f32_16x16x32_bf16 v[120:123], v[162:165], v[186:189], v[120:123]
	v_mfma_f32_16x16x32_bf16 v[108:111], v[144:147], v[194:197], v[108:111]
	v_mfma_f32_16x16x32_bf16 v[104:107], v[162:165], v[194:197], v[104:107]
	v_mfma_f32_16x16x32_bf16 v[92:95], v[144:147], v[202:205], v[92:95]
	v_mfma_f32_16x16x32_bf16 v[88:91], v[162:165], v[202:205], v[88:91]
	v_mfma_f32_16x16x32_bf16 v[76:79], v[144:147], v[210:213], v[76:79]
	v_mfma_f32_16x16x32_bf16 v[72:75], v[162:165], v[210:213], v[72:75]
	v_mfma_f32_16x16x32_bf16 v[124:127], v[158:161], v[190:193], v[124:127]
	v_mfma_f32_16x16x32_bf16 v[120:123], v[166:169], v[190:193], v[120:123]
	v_mfma_f32_16x16x32_bf16 v[108:111], v[158:161], v[198:201], v[108:111]
	v_mfma_f32_16x16x32_bf16 v[104:107], v[166:169], v[198:201], v[104:107]
	v_mfma_f32_16x16x32_bf16 v[92:95], v[158:161], v[206:209], v[92:95]
	v_mfma_f32_16x16x32_bf16 v[88:91], v[166:169], v[206:209], v[88:91]
	v_mfma_f32_16x16x32_bf16 v[76:79], v[158:161], v[214:217], v[76:79]
	v_mfma_f32_16x16x32_bf16 v[72:75], v[166:169], v[214:217], v[72:75]
	s_setprio 0
	s_setprio 1
	v_mfma_f32_16x16x32_bf16 v[116:119], v[170:173], v[186:189], v[116:119]
	v_mfma_f32_16x16x32_bf16 v[112:115], v[178:181], v[186:189], v[112:115]
	v_mfma_f32_16x16x32_bf16 v[100:103], v[170:173], v[194:197], v[100:103]
	v_mfma_f32_16x16x32_bf16 v[96:99], v[178:181], v[194:197], v[96:99]
	v_mfma_f32_16x16x32_bf16 v[84:87], v[170:173], v[202:205], v[84:87]
	v_mfma_f32_16x16x32_bf16 v[80:83], v[178:181], v[202:205], v[80:83]
	v_mfma_f32_16x16x32_bf16 v[68:71], v[170:173], v[210:213], v[68:71]
	v_mfma_f32_16x16x32_bf16 v[64:67], v[178:181], v[210:213], v[64:67]
	v_mfma_f32_16x16x32_bf16 v[116:119], v[174:177], v[190:193], v[116:119]
	v_mfma_f32_16x16x32_bf16 v[112:115], v[182:185], v[190:193], v[112:115]
	v_mfma_f32_16x16x32_bf16 v[100:103], v[174:177], v[198:201], v[100:103]
	v_mfma_f32_16x16x32_bf16 v[96:99], v[182:185], v[198:201], v[96:99]
	v_mfma_f32_16x16x32_bf16 v[84:87], v[174:177], v[206:209], v[84:87]
	v_mfma_f32_16x16x32_bf16 v[80:83], v[182:185], v[206:209], v[80:83]
	v_mfma_f32_16x16x32_bf16 v[68:71], v[174:177], v[214:217], v[68:71]
	v_mfma_f32_16x16x32_bf16 v[64:67], v[182:185], v[214:217], v[64:67]
	s_setprio 0
	s_setprio 1
	v_mfma_f32_16x16x32_bf16 v[60:63], v[144:147], v[220:223], v[60:63]
	v_mfma_f32_16x16x32_bf16 v[56:59], v[162:165], v[220:223], v[56:59]
	v_mfma_f32_16x16x32_bf16 v[44:47], v[144:147], v[228:231], v[44:47]
	v_mfma_f32_16x16x32_bf16 v[40:43], v[162:165], v[228:231], v[40:43]
	v_mfma_f32_16x16x32_bf16 v[28:31], v[144:147], v[236:239], v[28:31]
	v_mfma_f32_16x16x32_bf16 v[24:27], v[162:165], v[236:239], v[24:27]
	v_mfma_f32_16x16x32_bf16 v[12:15], v[144:147], v[244:247], v[12:15]
	v_mfma_f32_16x16x32_bf16 v[8:11], v[162:165], v[244:247], v[8:11]
	v_mfma_f32_16x16x32_bf16 v[60:63], v[158:161], v[224:227], v[60:63]
	v_mfma_f32_16x16x32_bf16 v[56:59], v[166:169], v[224:227], v[56:59]
	v_mfma_f32_16x16x32_bf16 v[44:47], v[158:161], v[232:235], v[44:47]
	v_mfma_f32_16x16x32_bf16 v[40:43], v[166:169], v[232:235], v[40:43]
	v_mfma_f32_16x16x32_bf16 v[28:31], v[158:161], v[240:243], v[28:31]
	v_mfma_f32_16x16x32_bf16 v[24:27], v[166:169], v[240:243], v[24:27]
	v_mfma_f32_16x16x32_bf16 v[12:15], v[158:161], v[248:251], v[12:15]
	v_mfma_f32_16x16x32_bf16 v[8:11], v[166:169], v[248:251], v[8:11]
	s_setprio 0
	s_setprio 1
	v_mfma_f32_16x16x32_bf16 v[52:55], v[170:173], v[220:223], v[52:55]
	v_mfma_f32_16x16x32_bf16 v[48:51], v[178:181], v[220:223], v[48:51]
	v_mfma_f32_16x16x32_bf16 v[36:39], v[170:173], v[228:231], v[36:39]
	v_mfma_f32_16x16x32_bf16 v[32:35], v[178:181], v[228:231], v[32:35]
	v_mfma_f32_16x16x32_bf16 v[20:23], v[170:173], v[236:239], v[20:23]
	v_mfma_f32_16x16x32_bf16 v[16:19], v[178:181], v[236:239], v[16:19]
	v_mfma_f32_16x16x32_bf16 v[4:7], v[170:173], v[244:247], v[4:7]
	v_mfma_f32_16x16x32_bf16 v[0:3], v[178:181], v[244:247], v[0:3]
	v_mfma_f32_16x16x32_bf16 v[52:55], v[174:177], v[224:227], v[52:55]
	v_mfma_f32_16x16x32_bf16 v[48:51], v[182:185], v[224:227], v[48:51]
	v_mfma_f32_16x16x32_bf16 v[36:39], v[174:177], v[232:235], v[36:39]
	v_mfma_f32_16x16x32_bf16 v[32:35], v[182:185], v[232:235], v[32:35]
	v_mfma_f32_16x16x32_bf16 v[20:23], v[174:177], v[240:243], v[20:23]
	v_mfma_f32_16x16x32_bf16 v[16:19], v[182:185], v[240:243], v[16:19]
	v_mfma_f32_16x16x32_bf16 v[4:7], v[174:177], v[248:251], v[4:7]
	v_mfma_f32_16x16x32_bf16 v[0:3], v[182:185], v[248:251], v[0:3]
	s_setprio 0
.Lk64_zj_p5_t:
	s_waitcnt vmcnt(0)
	s_barrier
	s_add_u32 vcc_lo, s42, 0x0
	s_addc_u32 vcc_hi, s43, 0
	s_add_i32 m0, s44, 0x2000
	s_nop 0
	global_load_lds_dwordx4 v132, vcc
	s_add_u32 vcc_lo, vcc_lo, 0x20000
	s_addc_u32 vcc_hi, vcc_hi, 0
	s_add_i32 m0, s44, 0x1000
	s_nop 0
	global_load_lds_dwordx4 v128, vcc
	s_add_u32 vcc_lo, vcc_lo, 0x60000
	s_addc_u32 vcc_hi, vcc_hi, 0
	s_add_i32 m0, s44, 0x6000
	s_nop 0
	global_load_lds_dwordx4 v132, vcc
	s_add_u32 vcc_lo, vcc_lo, 0x20000
	s_addc_u32 vcc_hi, vcc_hi, 0
	s_add_i32 m0, s44, 0x5000
	s_nop 0
	global_load_lds_dwordx4 v128, vcc
	s_add_u32 vcc_lo, s42, 0x80
	s_addc_u32 vcc_hi, s43, 0
	s_add_i32 m0, s44, 0x8000
	s_nop 0
	global_load_lds_dwordx4 v128, vcc
	s_sub_u32 vcc_lo, vcc_lo, 0x20000
	s_subb_u32 vcc_hi, vcc_hi, 0
	s_add_i32 m0, s44, 0x7000
	s_nop 0
	global_load_lds_dwordx4 v128, vcc
	s_add_u32 vcc_lo, vcc_lo, 0xa0000
	s_addc_u32 vcc_hi, vcc_hi, 0
	s_add_i32 m0, s44, 0xc000
	s_nop 0
	global_load_lds_dwordx4 v128, vcc
	s_sub_u32 vcc_lo, vcc_lo, 0x20000
	s_subb_u32 vcc_hi, vcc_hi, 0
	s_add_i32 m0, s44, 0xb000
	s_nop 0
	global_load_lds_dwordx4 v128, vcc
	ds_read_b128 v[144:147], v153 offset:32768
	ds_read_b128 v[158:161], v153 offset:33792
	ds_read_b128 v[162:165], v153 offset:34816
	ds_read_b128 v[166:169], v153 offset:35840
	ds_read_b128 v[170:173], v154 offset:32768
	ds_read_b128 v[174:177], v154 offset:33792
	ds_read_b128 v[178:181], v154 offset:34816
	ds_read_b128 v[182:185], v154 offset:35840
	ds_read_b128 v[186:189], v155 offset:32768
	ds_read_b128 v[190:193], v155 offset:33792
	ds_read_b128 v[194:197], v155 offset:34816
	ds_read_b128 v[198:201], v155 offset:35840
	ds_read_b128 v[202:205], v155 offset:36864
	ds_read_b128 v[206:209], v155 offset:37888
	ds_read_b128 v[210:213], v155 offset:38912
	ds_read_b128 v[214:217], v155 offset:39936
	ds_read_b128 v[220:223], v155 offset:49152
	ds_read_b128 v[224:227], v155 offset:50176
	ds_read_b128 v[228:231], v155 offset:51200
	ds_read_b128 v[232:235], v155 offset:52224
	ds_read_b128 v[236:239], v155 offset:53248
	ds_read_b128 v[240:243], v155 offset:54272
	ds_read_b128 v[244:247], v155 offset:55296
	ds_read_b128 v[248:251], v155 offset:56320
	s_nop 15
	s_nop 15
	s_waitcnt lgkmcnt(0)
	s_barrier
	s_setprio 1
	v_mfma_f32_16x16x32_bf16 v[124:127], v[144:147], v[186:189], v[124:127]
	v_mfma_f32_16x16x32_bf16 v[120:123], v[162:165], v[186:189], v[120:123]
	v_mfma_f32_16x16x32_bf16 v[108:111], v[144:147], v[194:197], v[108:111]
	v_mfma_f32_16x16x32_bf16 v[104:107], v[162:165], v[194:197], v[104:107]
	v_mfma_f32_16x16x32_bf16 v[92:95], v[144:147], v[202:205], v[92:95]
	v_mfma_f32_16x16x32_bf16 v[88:91], v[162:165], v[202:205], v[88:91]
	v_mfma_f32_16x16x32_bf16 v[76:79], v[144:147], v[210:213], v[76:79]
	v_mfma_f32_16x16x32_bf16 v[72:75], v[162:165], v[210:213], v[72:75]
	v_mfma_f32_16x16x32_bf16 v[124:127], v[158:161], v[190:193], v[124:127]
	v_mfma_f32_16x16x32_bf16 v[120:123], v[166:169], v[190:193], v[120:123]
	v_mfma_f32_16x16x32_bf16 v[108:111], v[158:161], v[198:201], v[108:111]
	v_mfma_f32_16x16x32_bf16 v[104:107], v[166:169], v[198:201], v[104:107]
	v_mfma_f32_16x16x32_bf16 v[92:95], v[158:161], v[206:209], v[92:95]
	v_mfma_f32_16x16x32_bf16 v[88:91], v[166:169], v[206:209], v[88:91]
	v_mfma_f32_16x16x32_bf16 v[76:79], v[158:161], v[214:217], v[76:79]
	v_mfma_f32_16x16x32_bf16 v[72:75], v[166:169], v[214:217], v[72:75]
	s_setprio 0
	s_setprio 1
	v_mfma_f32_16x16x32_bf16 v[116:119], v[170:173], v[186:189], v[116:119]
	v_mfma_f32_16x16x32_bf16 v[112:115], v[178:181], v[186:189], v[112:115]
	v_mfma_f32_16x16x32_bf16 v[100:103], v[170:173], v[194:197], v[100:103]
	v_mfma_f32_16x16x32_bf16 v[96:99], v[178:181], v[194:197], v[96:99]
	v_mfma_f32_16x16x32_bf16 v[84:87], v[170:173], v[202:205], v[84:87]
	v_mfma_f32_16x16x32_bf16 v[80:83], v[178:181], v[202:205], v[80:83]
	v_mfma_f32_16x16x32_bf16 v[68:71], v[170:173], v[210:213], v[68:71]
	v_mfma_f32_16x16x32_bf16 v[64:67], v[178:181], v[210:213], v[64:67]
	v_mfma_f32_16x16x32_bf16 v[116:119], v[174:177], v[190:193], v[116:119]
	v_mfma_f32_16x16x32_bf16 v[112:115], v[182:185], v[190:193], v[112:115]
	v_mfma_f32_16x16x32_bf16 v[100:103], v[174:177], v[198:201], v[100:103]
	v_mfma_f32_16x16x32_bf16 v[96:99], v[182:185], v[198:201], v[96:99]
	v_mfma_f32_16x16x32_bf16 v[84:87], v[174:177], v[206:209], v[84:87]
	v_mfma_f32_16x16x32_bf16 v[80:83], v[182:185], v[206:209], v[80:83]
	v_mfma_f32_16x16x32_bf16 v[68:71], v[174:177], v[214:217], v[68:71]
	v_mfma_f32_16x16x32_bf16 v[64:67], v[182:185], v[214:217], v[64:67]
	s_setprio 0
	s_setprio 1
	v_mfma_f32_16x16x32_bf16 v[60:63], v[144:147], v[220:223], v[60:63]
	v_mfma_f32_16x16x32_bf16 v[56:59], v[162:165], v[220:223], v[56:59]
	v_mfma_f32_16x16x32_bf16 v[44:47], v[144:147], v[228:231], v[44:47]
	v_mfma_f32_16x16x32_bf16 v[40:43], v[162:165], v[228:231], v[40:43]
	v_mfma_f32_16x16x32_bf16 v[28:31], v[144:147], v[236:239], v[28:31]
	v_mfma_f32_16x16x32_bf16 v[24:27], v[162:165], v[236:239], v[24:27]
	v_mfma_f32_16x16x32_bf16 v[12:15], v[144:147], v[244:247], v[12:15]
	v_mfma_f32_16x16x32_bf16 v[8:11], v[162:165], v[244:247], v[8:11]
	v_mfma_f32_16x16x32_bf16 v[60:63], v[158:161], v[224:227], v[60:63]
	v_mfma_f32_16x16x32_bf16 v[56:59], v[166:169], v[224:227], v[56:59]
	v_mfma_f32_16x16x32_bf16 v[44:47], v[158:161], v[232:235], v[44:47]
	v_mfma_f32_16x16x32_bf16 v[40:43], v[166:169], v[232:235], v[40:43]
	v_mfma_f32_16x16x32_bf16 v[28:31], v[158:161], v[240:243], v[28:31]
	v_mfma_f32_16x16x32_bf16 v[24:27], v[166:169], v[240:243], v[24:27]
	v_mfma_f32_16x16x32_bf16 v[12:15], v[158:161], v[248:251], v[12:15]
	v_mfma_f32_16x16x32_bf16 v[8:11], v[166:169], v[248:251], v[8:11]
	s_setprio 0
	s_setprio 1
	v_mfma_f32_16x16x32_bf16 v[52:55], v[170:173], v[220:223], v[52:55]
	v_mfma_f32_16x16x32_bf16 v[48:51], v[178:181], v[220:223], v[48:51]
	v_mfma_f32_16x16x32_bf16 v[36:39], v[170:173], v[228:231], v[36:39]
	v_mfma_f32_16x16x32_bf16 v[32:35], v[178:181], v[228:231], v[32:35]
	v_mfma_f32_16x16x32_bf16 v[20:23], v[170:173], v[236:239], v[20:23]
	v_mfma_f32_16x16x32_bf16 v[16:19], v[178:181], v[236:239], v[16:19]
	v_mfma_f32_16x16x32_bf16 v[4:7], v[170:173], v[244:247], v[4:7]
	v_mfma_f32_16x16x32_bf16 v[0:3], v[178:181], v[244:247], v[0:3]
	v_mfma_f32_16x16x32_bf16 v[52:55], v[174:177], v[224:227], v[52:55]
	v_mfma_f32_16x16x32_bf16 v[48:51], v[182:185], v[224:227], v[48:51]
	v_mfma_f32_16x16x32_bf16 v[36:39], v[174:177], v[232:235], v[36:39]
	v_mfma_f32_16x16x32_bf16 v[32:35], v[182:185], v[232:235], v[32:35]
	v_mfma_f32_16x16x32_bf16 v[20:23], v[174:177], v[240:243], v[20:23]
	v_mfma_f32_16x16x32_bf16 v[16:19], v[182:185], v[240:243], v[16:19]
	v_mfma_f32_16x16x32_bf16 v[4:7], v[174:177], v[248:251], v[4:7]
	v_mfma_f32_16x16x32_bf16 v[0:3], v[182:185], v[248:251], v[0:3]
	s_setprio 0
	s_waitcnt vmcnt(0)
	s_barrier
	s_add_i32 s58, s58, 2
	s_add_u32 s34, s34, 0x100
	s_addc_u32 s35, s35, 0
	s_add_u32 s56, s56, 0x100
	s_addc_u32 s57, s57, 0
	s_cmp_gt_u32 s58, 29
	s_cbranch_scc0 .LBB0_761
	s_branch .Lk64_done_p5

.LBB0_845:
	s_ashr_i32 s25, s24, 31
	s_lshl_b64 s[26:27], s[24:25], 20
	s_add_u32 s26, s20, s26
	s_addc_u32 s27, s21, s27
	s_and_b64 s[28:29], s[40:41], exec
	s_cselect_b32 s25, s27, s13
	s_cselect_b32 s52, s26, s12
	s_ashr_i32 s23, s22, 31
	s_lshl_b64 s[28:29], s[22:23], 20
	v_readlane_b32 s34, v255, 21
	v_readlane_b32 s35, v255, 22
	s_add_u32 s28, s34, s28
	s_addc_u32 s29, s35, s29
	s_and_b64 s[34:35], s[40:41], exec
	s_cselect_b32 s23, s29, s31
	s_cselect_b32 s53, s28, s30
	s_add_u32 s12, s12, 0x80080
	s_addc_u32 s13, s13, 0
	s_add_u32 s54, s30, 0x100
	s_addc_u32 s55, s31, 0
	s_mov_b32 s56, -2

.Lk64_epd_p6_l:
	ds_read_b128 v[32:35], v169 offset:0
	ds_read_b128 v[36:39], v169 offset:1024
	ds_read_b128 v[40:43], v169 offset:2048
	ds_read_b128 v[44:47], v169 offset:3072
	ds_read_b128 v[162:165], v170 offset:0
	ds_read_b128 v[174:177], v170 offset:1024
	ds_read_b128 v[178:181], v170 offset:2048
	ds_read_b128 v[182:185], v170 offset:3072
	ds_read_b128 v[186:189], v171 offset:0
	ds_read_b128 v[190:193], v171 offset:1024
	ds_read_b128 v[194:197], v171 offset:2048
	ds_read_b128 v[198:201], v171 offset:3072
	ds_read_b128 v[202:205], v171 offset:4096
	ds_read_b128 v[206:209], v171 offset:5120
	ds_read_b128 v[210:213], v171 offset:6144
	ds_read_b128 v[214:217], v171 offset:7168
	ds_read_b128 v[220:223], v171 offset:16384
	ds_read_b128 v[224:227], v171 offset:17408
	ds_read_b128 v[228:231], v171 offset:18432
	ds_read_b128 v[232:235], v171 offset:19456
	ds_read_b128 v[236:239], v171 offset:20480
	ds_read_b128 v[240:243], v171 offset:21504
	ds_read_b128 v[244:247], v171 offset:22528
	ds_read_b128 v[248:251], v171 offset:23552
	s_nop 15
	s_nop 15
	s_waitcnt lgkmcnt(0)
	s_barrier
	s_cmp_eq_i32 s56, -2
	s_cbranch_scc1 .Lk64_z_p6_l
	s_setprio 1
	v_mfma_f32_16x16x32_bf16 v[140:143], v[32:35], v[186:189], v[140:143]
	v_mfma_f32_16x16x32_bf16 v[136:139], v[40:43], v[186:189], v[136:139]
	v_mfma_f32_16x16x32_bf16 v[124:127], v[32:35], v[194:197], v[124:127]
	v_mfma_f32_16x16x32_bf16 v[120:123], v[40:43], v[194:197], v[120:123]
	v_mfma_f32_16x16x32_bf16 v[108:111], v[32:35], v[202:205], v[108:111]
	v_mfma_f32_16x16x32_bf16 v[104:107], v[40:43], v[202:205], v[104:107]
	v_mfma_f32_16x16x32_bf16 v[92:95], v[32:35], v[210:213], v[92:95]
	v_mfma_f32_16x16x32_bf16 v[88:91], v[40:43], v[210:213], v[88:91]
	v_mfma_f32_16x16x32_bf16 v[140:143], v[36:39], v[190:193], v[140:143]
	v_mfma_f32_16x16x32_bf16 v[136:139], v[44:47], v[190:193], v[136:139]
	v_mfma_f32_16x16x32_bf16 v[124:127], v[36:39], v[198:201], v[124:127]
	v_mfma_f32_16x16x32_bf16 v[120:123], v[44:47], v[198:201], v[120:123]
	v_mfma_f32_16x16x32_bf16 v[108:111], v[36:39], v[206:209], v[108:111]
	v_mfma_f32_16x16x32_bf16 v[104:107], v[44:47], v[206:209], v[104:107]
	v_mfma_f32_16x16x32_bf16 v[92:95], v[36:39], v[214:217], v[92:95]
	v_mfma_f32_16x16x32_bf16 v[88:91], v[44:47], v[214:217], v[88:91]
	s_setprio 0
	s_setprio 1
	v_mfma_f32_16x16x32_bf16 v[132:135], v[162:165], v[186:189], v[132:135]
	v_mfma_f32_16x16x32_bf16 v[128:131], v[178:181], v[186:189], v[128:131]
	v_mfma_f32_16x16x32_bf16 v[116:119], v[162:165], v[194:197], v[116:119]
	v_mfma_f32_16x16x32_bf16 v[112:115], v[178:181], v[194:197], v[112:115]
	v_mfma_f32_16x16x32_bf16 v[100:103], v[162:165], v[202:205], v[100:103]
	v_mfma_f32_16x16x32_bf16 v[96:99], v[178:181], v[202:205], v[96:99]
	v_mfma_f32_16x16x32_bf16 v[84:87], v[162:165], v[210:213], v[84:87]
	v_mfma_f32_16x16x32_bf16 v[80:83], v[178:181], v[210:213], v[80:83]
	v_mfma_f32_16x16x32_bf16 v[132:135], v[174:177], v[190:193], v[132:135]
	v_mfma_f32_16x16x32_bf16 v[128:131], v[182:185], v[190:193], v[128:131]
	v_mfma_f32_16x16x32_bf16 v[116:119], v[174:177], v[198:201], v[116:119]
	v_mfma_f32_16x16x32_bf16 v[112:115], v[182:185], v[198:201], v[112:115]
	v_mfma_f32_16x16x32_bf16 v[100:103], v[174:177], v[206:209], v[100:103]
	v_mfma_f32_16x16x32_bf16 v[96:99], v[182:185], v[206:209], v[96:99]
	v_mfma_f32_16x16x32_bf16 v[84:87], v[174:177], v[214:217], v[84:87]
	v_mfma_f32_16x16x32_bf16 v[80:83], v[182:185], v[214:217], v[80:83]
	s_setprio 0
	s_setprio 1
	v_mfma_f32_16x16x32_bf16 v[76:79], v[32:35], v[220:223], v[76:79]
	v_mfma_f32_16x16x32_bf16 v[72:75], v[40:43], v[220:223], v[72:75]
	v_mfma_f32_16x16x32_bf16 v[60:63], v[32:35], v[228:231], v[60:63]
	v_mfma_f32_16x16x32_bf16 v[56:59], v[40:43], v[228:231], v[56:59]
	v_mfma_f32_16x16x32_bf16 v[28:31], v[32:35], v[236:239], v[28:31]
	v_mfma_f32_16x16x32_bf16 v[24:27], v[40:43], v[236:239], v[24:27]
	v_mfma_f32_16x16x32_bf16 v[12:15], v[32:35], v[244:247], v[12:15]
	v_mfma_f32_16x16x32_bf16 v[8:11], v[40:43], v[244:247], v[8:11]
	v_mfma_f32_16x16x32_bf16 v[76:79], v[36:39], v[224:227], v[76:79]
	v_mfma_f32_16x16x32_bf16 v[72:75], v[44:47], v[224:227], v[72:75]
	v_mfma_f32_16x16x32_bf16 v[60:63], v[36:39], v[232:235], v[60:63]
	v_mfma_f32_16x16x32_bf16 v[56:59], v[44:47], v[232:235], v[56:59]
	v_mfma_f32_16x16x32_bf16 v[28:31], v[36:39], v[240:243], v[28:31]
	v_mfma_f32_16x16x32_bf16 v[24:27], v[44:47], v[240:243], v[24:27]
	v_mfma_f32_16x16x32_bf16 v[12:15], v[36:39], v[248:251], v[12:15]
	v_mfma_f32_16x16x32_bf16 v[8:11], v[44:47], v[248:251], v[8:11]
	s_setprio 0
	s_setprio 1
	v_mfma_f32_16x16x32_bf16 v[68:71], v[162:165], v[220:223], v[68:71]
	v_mfma_f32_16x16x32_bf16 v[64:67], v[178:181], v[220:223], v[64:67]
	v_mfma_f32_16x16x32_bf16 v[52:55], v[162:165], v[228:231], v[52:55]
	v_mfma_f32_16x16x32_bf16 v[48:51], v[178:181], v[228:231], v[48:51]
	v_mfma_f32_16x16x32_bf16 v[20:23], v[162:165], v[236:239], v[20:23]
	v_mfma_f32_16x16x32_bf16 v[16:19], v[178:181], v[236:239], v[16:19]
	v_mfma_f32_16x16x32_bf16 v[4:7], v[162:165], v[244:247], v[4:7]
	v_mfma_f32_16x16x32_bf16 v[0:3], v[178:181], v[244:247], v[0:3]
	v_mfma_f32_16x16x32_bf16 v[68:71], v[174:177], v[224:227], v[68:71]
	v_mfma_f32_16x16x32_bf16 v[64:67], v[182:185], v[224:227], v[64:67]
	v_mfma_f32_16x16x32_bf16 v[52:55], v[174:177], v[232:235], v[52:55]
	v_mfma_f32_16x16x32_bf16 v[48:51], v[182:185], v[232:235], v[48:51]
	v_mfma_f32_16x16x32_bf16 v[20:23], v[174:177], v[240:243], v[20:23]
	v_mfma_f32_16x16x32_bf16 v[16:19], v[182:185], v[240:243], v[16:19]
	v_mfma_f32_16x16x32_bf16 v[4:7], v[174:177], v[248:251], v[4:7]
	v_mfma_f32_16x16x32_bf16 v[0:3], v[182:185], v[248:251], v[0:3]
	s_setprio 0
.Lk64_zj_p6_l:
	s_waitcnt vmcnt(0)
	s_barrier
	s_add_u32 vcc_lo, s30, 0x0
	s_addc_u32 vcc_hi, s31, 0
	s_add_i32 m0, s37, 0x10000
	s_nop 0
	global_load_lds_dwordx4 v148, vcc
	s_add_i32 m0, s37, 0x12000
	s_nop 0
	global_load_lds_dwordx4 v144, vcc
	s_add_u32 vcc_lo, vcc_lo, 0x20000
	s_addc_u32 vcc_hi, vcc_hi, 0
	s_add_i32 m0, s37, 0x11000
	s_nop 0
	global_load_lds_dwordx4 v148, vcc
	s_add_i32 m0, s37, 0x13000
	s_nop 0
	global_load_lds_dwordx4 v144, vcc
	s_add_u32 vcc_lo, vcc_lo, 0x60000
	s_addc_u32 vcc_hi, vcc_hi, 0
	s_add_i32 m0, s37, 0x14000
	s_nop 0
	global_load_lds_dwordx4 v148, vcc
	s_add_i32 m0, s37, 0x16000
	s_nop 0
	global_load_lds_dwordx4 v144, vcc
	s_add_u32 vcc_lo, vcc_lo, 0x20000
	s_addc_u32 vcc_hi, vcc_hi, 0
	s_add_i32 m0, s37, 0x15000
	s_nop 0
	global_load_lds_dwordx4 v148, vcc
	s_add_i32 m0, s37, 0x17000
	s_nop 0
	global_load_lds_dwordx4 v144, vcc
	ds_read_b128 v[32:35], v169 offset:32768
	ds_read_b128 v[36:39], v169 offset:33792
	ds_read_b128 v[40:43], v169 offset:34816
	ds_read_b128 v[44:47], v169 offset:35840
	ds_read_b128 v[162:165], v170 offset:32768
	ds_read_b128 v[174:177], v170 offset:33792
	ds_read_b128 v[178:181], v170 offset:34816
	ds_read_b128 v[182:185], v170 offset:35840
	ds_read_b128 v[186:189], v171 offset:32768
	ds_read_b128 v[190:193], v171 offset:33792
	ds_read_b128 v[194:197], v171 offset:34816
	ds_read_b128 v[198:201], v171 offset:35840
	ds_read_b128 v[202:205], v171 offset:36864
	ds_read_b128 v[206:209], v171 offset:37888
	ds_read_b128 v[210:213], v171 offset:38912
	ds_read_b128 v[214:217], v171 offset:39936
	ds_read_b128 v[220:223], v171 offset:49152
	ds_read_b128 v[224:227], v171 offset:50176
	ds_read_b128 v[228:231], v171 offset:51200
	ds_read_b128 v[232:235], v171 offset:52224
	ds_read_b128 v[236:239], v171 offset:53248
	ds_read_b128 v[240:243], v171 offset:54272
	ds_read_b128 v[244:247], v171 offset:55296
	ds_read_b128 v[248:251], v171 offset:56320
	s_nop 15
	s_nop 15
	s_waitcnt lgkmcnt(0)
	s_barrier
	s_setprio 1
	v_mfma_f32_16x16x32_bf16 v[140:143], v[32:35], v[186:189], v[140:143]
	v_mfma_f32_16x16x32_bf16 v[136:139], v[40:43], v[186:189], v[136:139]
	v_mfma_f32_16x16x32_bf16 v[124:127], v[32:35], v[194:197], v[124:127]
	v_mfma_f32_16x16x32_bf16 v[120:123], v[40:43], v[194:197], v[120:123]
	v_mfma_f32_16x16x32_bf16 v[108:111], v[32:35], v[202:205], v[108:111]
	v_mfma_f32_16x16x32_bf16 v[104:107], v[40:43], v[202:205], v[104:107]
	v_mfma_f32_16x16x32_bf16 v[92:95], v[32:35], v[210:213], v[92:95]
	v_mfma_f32_16x16x32_bf16 v[88:91], v[40:43], v[210:213], v[88:91]
	v_mfma_f32_16x16x32_bf16 v[140:143], v[36:39], v[190:193], v[140:143]
	v_mfma_f32_16x16x32_bf16 v[136:139], v[44:47], v[190:193], v[136:139]
	v_mfma_f32_16x16x32_bf16 v[124:127], v[36:39], v[198:201], v[124:127]
	v_mfma_f32_16x16x32_bf16 v[120:123], v[44:47], v[198:201], v[120:123]
	v_mfma_f32_16x16x32_bf16 v[108:111], v[36:39], v[206:209], v[108:111]
	v_mfma_f32_16x16x32_bf16 v[104:107], v[44:47], v[206:209], v[104:107]
	v_mfma_f32_16x16x32_bf16 v[92:95], v[36:39], v[214:217], v[92:95]
	v_mfma_f32_16x16x32_bf16 v[88:91], v[44:47], v[214:217], v[88:91]
	s_setprio 0
	s_setprio 1
	v_mfma_f32_16x16x32_bf16 v[132:135], v[162:165], v[186:189], v[132:135]
	v_mfma_f32_16x16x32_bf16 v[128:131], v[178:181], v[186:189], v[128:131]
	v_mfma_f32_16x16x32_bf16 v[116:119], v[162:165], v[194:197], v[116:119]
	v_mfma_f32_16x16x32_bf16 v[112:115], v[178:181], v[194:197], v[112:115]
	v_mfma_f32_16x16x32_bf16 v[100:103], v[162:165], v[202:205], v[100:103]
	v_mfma_f32_16x16x32_bf16 v[96:99], v[178:181], v[202:205], v[96:99]
	v_mfma_f32_16x16x32_bf16 v[84:87], v[162:165], v[210:213], v[84:87]
	v_mfma_f32_16x16x32_bf16 v[80:83], v[178:181], v[210:213], v[80:83]
	v_mfma_f32_16x16x32_bf16 v[132:135], v[174:177], v[190:193], v[132:135]
	v_mfma_f32_16x16x32_bf16 v[128:131], v[182:185], v[190:193], v[128:131]
	v_mfma_f32_16x16x32_bf16 v[116:119], v[174:177], v[198:201], v[116:119]
	v_mfma_f32_16x16x32_bf16 v[112:115], v[182:185], v[198:201], v[112:115]
	v_mfma_f32_16x16x32_bf16 v[100:103], v[174:177], v[206:209], v[100:103]
	v_mfma_f32_16x16x32_bf16 v[96:99], v[182:185], v[206:209], v[96:99]
	v_mfma_f32_16x16x32_bf16 v[84:87], v[174:177], v[214:217], v[84:87]
	v_mfma_f32_16x16x32_bf16 v[80:83], v[182:185], v[214:217], v[80:83]
	s_setprio 0
	s_setprio 1
	v_mfma_f32_16x16x32_bf16 v[76:79], v[32:35], v[220:223], v[76:79]
	v_mfma_f32_16x16x32_bf16 v[72:75], v[40:43], v[220:223], v[72:75]
	v_mfma_f32_16x16x32_bf16 v[60:63], v[32:35], v[228:231], v[60:63]
	v_mfma_f32_16x16x32_bf16 v[56:59], v[40:43], v[228:231], v[56:59]
	v_mfma_f32_16x16x32_bf16 v[28:31], v[32:35], v[236:239], v[28:31]
	v_mfma_f32_16x16x32_bf16 v[24:27], v[40:43], v[236:239], v[24:27]
	v_mfma_f32_16x16x32_bf16 v[12:15], v[32:35], v[244:247], v[12:15]
	v_mfma_f32_16x16x32_bf16 v[8:11], v[40:43], v[244:247], v[8:11]
	v_mfma_f32_16x16x32_bf16 v[76:79], v[36:39], v[224:227], v[76:79]
	v_mfma_f32_16x16x32_bf16 v[72:75], v[44:47], v[224:227], v[72:75]
	v_mfma_f32_16x16x32_bf16 v[60:63], v[36:39], v[232:235], v[60:63]
	v_mfma_f32_16x16x32_bf16 v[56:59], v[44:47], v[232:235], v[56:59]
	v_mfma_f32_16x16x32_bf16 v[28:31], v[36:39], v[240:243], v[28:31]
	v_mfma_f32_16x16x32_bf16 v[24:27], v[44:47], v[240:243], v[24:27]
	v_mfma_f32_16x16x32_bf16 v[12:15], v[36:39], v[248:251], v[12:15]
	v_mfma_f32_16x16x32_bf16 v[8:11], v[44:47], v[248:251], v[8:11]
	s_setprio 0
	s_setprio 1
	v_mfma_f32_16x16x32_bf16 v[68:71], v[162:165], v[220:223], v[68:71]
	v_mfma_f32_16x16x32_bf16 v[64:67], v[178:181], v[220:223], v[64:67]
	v_mfma_f32_16x16x32_bf16 v[52:55], v[162:165], v[228:231], v[52:55]
	v_mfma_f32_16x16x32_bf16 v[48:51], v[178:181], v[228:231], v[48:51]
	v_mfma_f32_16x16x32_bf16 v[20:23], v[162:165], v[236:239], v[20:23]
	v_mfma_f32_16x16x32_bf16 v[16:19], v[178:181], v[236:239], v[16:19]
	v_mfma_f32_16x16x32_bf16 v[4:7], v[162:165], v[244:247], v[4:7]
	v_mfma_f32_16x16x32_bf16 v[0:3], v[178:181], v[244:247], v[0:3]
	v_mfma_f32_16x16x32_bf16 v[68:71], v[174:177], v[224:227], v[68:71]
	v_mfma_f32_16x16x32_bf16 v[64:67], v[182:185], v[224:227], v[64:67]
	v_mfma_f32_16x16x32_bf16 v[52:55], v[174:177], v[232:235], v[52:55]
	v_mfma_f32_16x16x32_bf16 v[48:51], v[182:185], v[232:235], v[48:51]
	v_mfma_f32_16x16x32_bf16 v[20:23], v[174:177], v[240:243], v[20:23]
	v_mfma_f32_16x16x32_bf16 v[16:19], v[182:185], v[240:243], v[16:19]
	v_mfma_f32_16x16x32_bf16 v[4:7], v[174:177], v[248:251], v[4:7]
	v_mfma_f32_16x16x32_bf16 v[0:3], v[182:185], v[248:251], v[0:3]
	s_setprio 0
	s_waitcnt vmcnt(0)
	s_barrier
	s_add_i32 s56, s56, 2
	s_add_u32 s12, s12, 0x100
	s_addc_u32 s13, s13, 0
	s_add_u32 s54, s54, 0x100
	s_addc_u32 s55, s55, 0
	s_cmp_gt_u32 s56, 29
	s_cbranch_scc0 .LBB0_846
	s_branch .Lk64_done_p6
.Lk64_z_p6_l:
	s_setprio 1
	v_mfma_f32_16x16x32_bf16 v[140:143], v[32:35], v[186:189], 0
	v_mfma_f32_16x16x32_bf16 v[136:139], v[40:43], v[186:189], 0
	v_mfma_f32_16x16x32_bf16 v[124:127], v[32:35], v[194:197], 0
	v_mfma_f32_16x16x32_bf16 v[120:123], v[40:43], v[194:197], 0
	v_mfma_f32_16x16x32_bf16 v[108:111], v[32:35], v[202:205], 0
	v_mfma_f32_16x16x32_bf16 v[104:107], v[40:43], v[202:205], 0
	v_mfma_f32_16x16x32_bf16 v[92:95], v[32:35], v[210:213], 0
	v_mfma_f32_16x16x32_bf16 v[88:91], v[40:43], v[210:213], 0
	v_mfma_f32_16x16x32_bf16 v[140:143], v[36:39], v[190:193], v[140:143]
	v_mfma_f32_16x16x32_bf16 v[136:139], v[44:47], v[190:193], v[136:139]
	v_mfma_f32_16x16x32_bf16 v[124:127], v[36:39], v[198:201], v[124:127]
	v_mfma_f32_16x16x32_bf16 v[120:123], v[44:47], v[198:201], v[120:123]
	v_mfma_f32_16x16x32_bf16 v[108:111], v[36:39], v[206:209], v[108:111]
	v_mfma_f32_16x16x32_bf16 v[104:107], v[44:47], v[206:209], v[104:107]
	v_mfma_f32_16x16x32_bf16 v[92:95], v[36:39], v[214:217], v[92:95]
	v_mfma_f32_16x16x32_bf16 v[88:91], v[44:47], v[214:217], v[88:91]
	s_setprio 0
	s_setprio 1
	v_mfma_f32_16x16x32_bf16 v[132:135], v[162:165], v[186:189], 0
	v_mfma_f32_16x16x32_bf16 v[128:131], v[178:181], v[186:189], 0
	v_mfma_f32_16x16x32_bf16 v[116:119], v[162:165], v[194:197], 0
	v_mfma_f32_16x16x32_bf16 v[112:115], v[178:181], v[194:197], 0
	v_mfma_f32_16x16x32_bf16 v[100:103], v[162:165], v[202:205], 0
	v_mfma_f32_16x16x32_bf16 v[96:99], v[178:181], v[202:205], 0
	v_mfma_f32_16x16x32_bf16 v[84:87], v[162:165], v[210:213], 0
	v_mfma_f32_16x16x32_bf16 v[80:83], v[178:181], v[210:213], 0
	v_mfma_f32_16x16x32_bf16 v[132:135], v[174:177], v[190:193], v[132:135]
	v_mfma_f32_16x16x32_bf16 v[128:131], v[182:185], v[190:193], v[128:131]
	v_mfma_f32_16x16x32_bf16 v[116:119], v[174:177], v[198:201], v[116:119]
	v_mfma_f32_16x16x32_bf16 v[112:115], v[182:185], v[198:201], v[112:115]
	v_mfma_f32_16x16x32_bf16 v[100:103], v[174:177], v[206:209], v[100:103]
	v_mfma_f32_16x16x32_bf16 v[96:99], v[182:185], v[206:209], v[96:99]
	v_mfma_f32_16x16x32_bf16 v[84:87], v[174:177], v[214:217], v[84:87]
	v_mfma_f32_16x16x32_bf16 v[80:83], v[182:185], v[214:217], v[80:83]
	s_setprio 0
	s_setprio 1
	v_mfma_f32_16x16x32_bf16 v[76:79], v[32:35], v[220:223], 0
	v_mfma_f32_16x16x32_bf16 v[72:75], v[40:43], v[220:223], 0
	v_mfma_f32_16x16x32_bf16 v[60:63], v[32:35], v[228:231], 0
	v_mfma_f32_16x16x32_bf16 v[56:59], v[40:43], v[228:231], 0
	v_mfma_f32_16x16x32_bf16 v[28:31], v[32:35], v[236:239], 0
	v_mfma_f32_16x16x32_bf16 v[24:27], v[40:43], v[236:239], 0
	v_mfma_f32_16x16x32_bf16 v[12:15], v[32:35], v[244:247], 0
	v_mfma_f32_16x16x32_bf16 v[8:11], v[40:43], v[244:247], 0
	v_mfma_f32_16x16x32_bf16 v[76:79], v[36:39], v[224:227], v[76:79]
	v_mfma_f32_16x16x32_bf16 v[72:75], v[44:47], v[224:227], v[72:75]
	v_mfma_f32_16x16x32_bf16 v[60:63], v[36:39], v[232:235], v[60:63]
	v_mfma_f32_16x16x32_bf16 v[56:59], v[44:47], v[232:235], v[56:59]
	v_mfma_f32_16x16x32_bf16 v[28:31], v[36:39], v[240:243], v[28:31]
	v_mfma_f32_16x16x32_bf16 v[24:27], v[44:47], v[240:243], v[24:27]
	v_mfma_f32_16x16x32_bf16 v[12:15], v[36:39], v[248:251], v[12:15]
	v_mfma_f32_16x16x32_bf16 v[8:11], v[44:47], v[248:251], v[8:11]
	s_setprio 0
	s_setprio 1
	v_mfma_f32_16x16x32_bf16 v[68:71], v[162:165], v[220:223], 0
	v_mfma_f32_16x16x32_bf16 v[64:67], v[178:181], v[220:223], 0
	v_mfma_f32_16x16x32_bf16 v[52:55], v[162:165], v[228:231], 0
	v_mfma_f32_16x16x32_bf16 v[48:51], v[178:181], v[228:231], 0
	v_mfma_f32_16x16x32_bf16 v[20:23], v[162:165], v[236:239], 0
	v_mfma_f32_16x16x32_bf16 v[16:19], v[178:181], v[236:239], 0
	v_mfma_f32_16x16x32_bf16 v[4:7], v[162:165], v[244:247], 0
	v_mfma_f32_16x16x32_bf16 v[0:3], v[178:181], v[244:247], 0
	v_mfma_f32_16x16x32_bf16 v[68:71], v[174:177], v[224:227], v[68:71]
	v_mfma_f32_16x16x32_bf16 v[64:67], v[182:185], v[224:227], v[64:67]
	v_mfma_f32_16x16x32_bf16 v[52:55], v[174:177], v[232:235], v[52:55]
	v_mfma_f32_16x16x32_bf16 v[48:51], v[182:185], v[232:235], v[48:51]
	v_mfma_f32_16x16x32_bf16 v[20:23], v[174:177], v[240:243], v[20:23]
	v_mfma_f32_16x16x32_bf16 v[16:19], v[182:185], v[240:243], v[16:19]
	v_mfma_f32_16x16x32_bf16 v[4:7], v[174:177], v[248:251], v[4:7]
	v_mfma_f32_16x16x32_bf16 v[0:3], v[182:185], v[248:251], v[0:3]
	s_setprio 0
	s_branch .Lk64_zj_p6_l

.Lk64_zj_p6_t:
	s_waitcnt vmcnt(0)
	s_barrier
	s_add_u32 vcc_lo, s34, 0x0
	s_addc_u32 vcc_hi, s35, 0
	s_add_i32 m0, s37, 0x2000
	s_nop 0
	global_load_lds_dwordx4 v146, vcc
	s_add_u32 vcc_lo, vcc_lo, 0x20000
	s_addc_u32 vcc_hi, vcc_hi, 0
	s_add_i32 m0, s37, 0x1000
	s_nop 0
	global_load_lds_dwordx4 v150, vcc
	s_add_u32 vcc_lo, vcc_lo, 0x60000
	s_addc_u32 vcc_hi, vcc_hi, 0
	s_add_i32 m0, s37, 0x6000
	s_nop 0
	global_load_lds_dwordx4 v146, vcc
	s_add_u32 vcc_lo, vcc_lo, 0x20000
	s_addc_u32 vcc_hi, vcc_hi, 0
	s_add_i32 m0, s37, 0x5000
	s_nop 0
	global_load_lds_dwordx4 v150, vcc
	s_add_u32 vcc_lo, s34, 0x80
	s_addc_u32 vcc_hi, s35, 0
	s_add_i32 m0, s37, 0x8000
	s_nop 0
	global_load_lds_dwordx4 v150, vcc
	s_sub_u32 vcc_lo, vcc_lo, 0x20000
	s_subb_u32 vcc_hi, vcc_hi, 0
	s_add_i32 m0, s37, 0x7000
	s_nop 0
	global_load_lds_dwordx4 v150, vcc
	s_add_u32 vcc_lo, vcc_lo, 0xa0000
	s_addc_u32 vcc_hi, vcc_hi, 0
	s_add_i32 m0, s37, 0xc000
	s_nop 0
	global_load_lds_dwordx4 v150, vcc
	s_sub_u32 vcc_lo, vcc_lo, 0x20000
	s_subb_u32 vcc_hi, vcc_hi, 0
	s_add_i32 m0, s37, 0xb000
	s_nop 0
	global_load_lds_dwordx4 v150, vcc
	ds_read_b128 v[32:35], v169 offset:32768
	ds_read_b128 v[36:39], v169 offset:33792
	ds_read_b128 v[40:43], v169 offset:34816
	ds_read_b128 v[44:47], v169 offset:35840
	ds_read_b128 v[162:165], v170 offset:32768
	ds_read_b128 v[174:177], v170 offset:33792
	ds_read_b128 v[178:181], v170 offset:34816
	ds_read_b128 v[182:185], v170 offset:35840
	ds_read_b128 v[186:189], v171 offset:32768
	ds_read_b128 v[190:193], v171 offset:33792
	ds_read_b128 v[194:197], v171 offset:34816
	ds_read_b128 v[198:201], v171 offset:35840
	ds_read_b128 v[202:205], v171 offset:36864
	ds_read_b128 v[206:209], v171 offset:37888
	ds_read_b128 v[210:213], v171 offset:38912
	ds_read_b128 v[214:217], v171 offset:39936
	ds_read_b128 v[220:223], v171 offset:49152
	ds_read_b128 v[224:227], v171 offset:50176
	ds_read_b128 v[228:231], v171 offset:51200
	ds_read_b128 v[232:235], v171 offset:52224
	ds_read_b128 v[236:239], v171 offset:53248
	ds_read_b128 v[240:243], v171 offset:54272
	ds_read_b128 v[244:247], v171 offset:55296
	ds_read_b128 v[248:251], v171 offset:56320
	s_nop 15
	s_nop 15
	s_waitcnt lgkmcnt(0)
	s_barrier
	s_setprio 1
	v_mfma_f32_16x16x32_bf16 v[140:143], v[32:35], v[186:189], v[140:143]
	v_mfma_f32_16x16x32_bf16 v[136:139], v[40:43], v[186:189], v[136:139]
	v_mfma_f32_16x16x32_bf16 v[124:127], v[32:35], v[194:197], v[124:127]
	v_mfma_f32_16x16x32_bf16 v[120:123], v[40:43], v[194:197], v[120:123]
	v_mfma_f32_16x16x32_bf16 v[108:111], v[32:35], v[202:205], v[108:111]
	v_mfma_f32_16x16x32_bf16 v[104:107], v[40:43], v[202:205], v[104:107]
	v_mfma_f32_16x16x32_bf16 v[92:95], v[32:35], v[210:213], v[92:95]
	v_mfma_f32_16x16x32_bf16 v[88:91], v[40:43], v[210:213], v[88:91]
	v_mfma_f32_16x16x32_bf16 v[140:143], v[36:39], v[190:193], v[140:143]
	v_mfma_f32_16x16x32_bf16 v[136:139], v[44:47], v[190:193], v[136:139]
	v_mfma_f32_16x16x32_bf16 v[124:127], v[36:39], v[198:201], v[124:127]
	v_mfma_f32_16x16x32_bf16 v[120:123], v[44:47], v[198:201], v[120:123]
	v_mfma_f32_16x16x32_bf16 v[108:111], v[36:39], v[206:209], v[108:111]
	v_mfma_f32_16x16x32_bf16 v[104:107], v[44:47], v[206:209], v[104:107]
	v_mfma_f32_16x16x32_bf16 v[92:95], v[36:39], v[214:217], v[92:95]
	v_mfma_f32_16x16x32_bf16 v[88:91], v[44:47], v[214:217], v[88:91]
	s_setprio 0
	s_setprio 1
	v_mfma_f32_16x16x32_bf16 v[132:135], v[162:165], v[186:189], v[132:135]
	v_mfma_f32_16x16x32_bf16 v[128:131], v[178:181], v[186:189], v[128:131]
	v_mfma_f32_16x16x32_bf16 v[116:119], v[162:165], v[194:197], v[116:119]
	v_mfma_f32_16x16x32_bf16 v[112:115], v[178:181], v[194:197], v[112:115]
	v_mfma_f32_16x16x32_bf16 v[100:103], v[162:165], v[202:205], v[100:103]
	v_mfma_f32_16x16x32_bf16 v[96:99], v[178:181], v[202:205], v[96:99]
	v_mfma_f32_16x16x32_bf16 v[84:87], v[162:165], v[210:213], v[84:87]
	v_mfma_f32_16x16x32_bf16 v[80:83], v[178:181], v[210:213], v[80:83]
	v_mfma_f32_16x16x32_bf16 v[132:135], v[174:177], v[190:193], v[132:135]
	v_mfma_f32_16x16x32_bf16 v[128:131], v[182:185], v[190:193], v[128:131]
	v_mfma_f32_16x16x32_bf16 v[116:119], v[174:177], v[198:201], v[116:119]
	v_mfma_f32_16x16x32_bf16 v[112:115], v[182:185], v[198:201], v[112:115]
	v_mfma_f32_16x16x32_bf16 v[100:103], v[174:177], v[206:209], v[100:103]
	v_mfma_f32_16x16x32_bf16 v[96:99], v[182:185], v[206:209], v[96:99]
	v_mfma_f32_16x16x32_bf16 v[84:87], v[174:177], v[214:217], v[84:87]
	v_mfma_f32_16x16x32_bf16 v[80:83], v[182:185], v[214:217], v[80:83]
	s_setprio 0
	s_setprio 1
	v_mfma_f32_16x16x32_bf16 v[76:79], v[32:35], v[220:223], v[76:79]
	v_mfma_f32_16x16x32_bf16 v[72:75], v[40:43], v[220:223], v[72:75]
	v_mfma_f32_16x16x32_bf16 v[60:63], v[32:35], v[228:231], v[60:63]
	v_mfma_f32_16x16x32_bf16 v[56:59], v[40:43], v[228:231], v[56:59]
	v_mfma_f32_16x16x32_bf16 v[28:31], v[32:35], v[236:239], v[28:31]
	v_mfma_f32_16x16x32_bf16 v[24:27], v[40:43], v[236:239], v[24:27]
	v_mfma_f32_16x16x32_bf16 v[12:15], v[32:35], v[244:247], v[12:15]
	v_mfma_f32_16x16x32_bf16 v[8:11], v[40:43], v[244:247], v[8:11]
	v_mfma_f32_16x16x32_bf16 v[76:79], v[36:39], v[224:227], v[76:79]
	v_mfma_f32_16x16x32_bf16 v[72:75], v[44:47], v[224:227], v[72:75]
	v_mfma_f32_16x16x32_bf16 v[60:63], v[36:39], v[232:235], v[60:63]
	v_mfma_f32_16x16x32_bf16 v[56:59], v[44:47], v[232:235], v[56:59]
	v_mfma_f32_16x16x32_bf16 v[28:31], v[36:39], v[240:243], v[28:31]
	v_mfma_f32_16x16x32_bf16 v[24:27], v[44:47], v[240:243], v[24:27]
	v_mfma_f32_16x16x32_bf16 v[12:15], v[36:39], v[248:251], v[12:15]
	v_mfma_f32_16x16x32_bf16 v[8:11], v[44:47], v[248:251], v[8:11]
	s_setprio 0
	s_setprio 1
	v_mfma_f32_16x16x32_bf16 v[68:71], v[162:165], v[220:223], v[68:71]
	v_mfma_f32_16x16x32_bf16 v[64:67], v[178:181], v[220:223], v[64:67]
	v_mfma_f32_16x16x32_bf16 v[52:55], v[162:165], v[228:231], v[52:55]
	v_mfma_f32_16x16x32_bf16 v[48:51], v[178:181], v[228:231], v[48:51]
	v_mfma_f32_16x16x32_bf16 v[20:23], v[162:165], v[236:239], v[20:23]
	v_mfma_f32_16x16x32_bf16 v[16:19], v[178:181], v[236:239], v[16:19]
	v_mfma_f32_16x16x32_bf16 v[4:7], v[162:165], v[244:247], v[4:7]
	v_mfma_f32_16x16x32_bf16 v[0:3], v[178:181], v[244:247], v[0:3]
	v_mfma_f32_16x16x32_bf16 v[68:71], v[174:177], v[224:227], v[68:71]
	v_mfma_f32_16x16x32_bf16 v[64:67], v[182:185], v[224:227], v[64:67]
	v_mfma_f32_16x16x32_bf16 v[52:55], v[174:177], v[232:235], v[52:55]
	v_mfma_f32_16x16x32_bf16 v[48:51], v[182:185], v[232:235], v[48:51]
	v_mfma_f32_16x16x32_bf16 v[20:23], v[174:177], v[240:243], v[20:23]
	v_mfma_f32_16x16x32_bf16 v[16:19], v[182:185], v[240:243], v[16:19]
	v_mfma_f32_16x16x32_bf16 v[4:7], v[174:177], v[248:251], v[4:7]
	v_mfma_f32_16x16x32_bf16 v[0:3], v[182:185], v[248:251], v[0:3]
	s_setprio 0
	s_waitcnt vmcnt(0)
	s_barrier
	s_add_i32 s56, s56, 2
	s_add_u32 s12, s12, 0x100
	s_addc_u32 s13, s13, 0
	s_add_u32 s54, s54, 0x100
	s_addc_u32 s55, s55, 0
	s_cmp_gt_u32 s56, 29
	s_cbranch_scc0 .LBB0_846
	s_branch .Lk64_done_p6

.LBB0_939:
	s_add_u32 s46, s24, 0x100
	s_addc_u32 s47, s25, 0
	s_mov_b32 s56, -2
	s_waitcnt vmcnt(0)
.LBB0_940:
	s_add_u32 s24, s22, 0x100
	s_addc_u32 s25, s23, 0
	s_cmpk_eq_i32 s56, 0x54
	s_cselect_b32 s29, s19, s25
	s_cselect_b32 s28, s18, s24
	s_cselect_b32 s27, s21, s47
	s_cselect_b32 s26, s20, s46
	s_and_b64 vcc, exec, s[12:13]
	s_cbranch_vccz .Lk64_trail_p7
	s_sub_u32 vcc_lo, s46, 0x80
	s_subb_u32 vcc_hi, s47, 0
	s_add_i32 m0, s30, 0x18000
	s_nop 0
	global_load_lds_dwordx4 v130, vcc
	s_add_i32 m0, s30, 0x1a000
	s_nop 0
	global_load_lds_dwordx4 v134, vcc
	s_add_u32 vcc_lo, vcc_lo, 0x58000
	s_addc_u32 vcc_hi, vcc_hi, 0
	s_add_i32 m0, s30, 0x19000
	s_nop 0
	global_load_lds_dwordx4 v130, vcc
	s_add_i32 m0, s30, 0x1b000
	s_nop 0
	global_load_lds_dwordx4 v134, vcc
	s_add_u32 vcc_lo, vcc_lo, 0x108000
	s_addc_u32 vcc_hi, vcc_hi, 0
	s_add_i32 m0, s30, 0x1c000
	s_nop 0
	global_load_lds_dwordx4 v130, vcc
	s_add_i32 m0, s30, 0x1e000
	s_nop 0
	global_load_lds_dwordx4 v134, vcc
	s_add_u32 vcc_lo, vcc_lo, 0x58000
	s_addc_u32 vcc_hi, vcc_hi, 0
	s_add_i32 m0, s30, 0x1d000
	s_nop 0
	global_load_lds_dwordx4 v130, vcc
	s_add_i32 m0, s30, 0x1f000
	s_nop 0
	global_load_lds_dwordx4 v134, vcc
	ds_read_b128 v[144:147], v185 offset:0
	ds_read_b128 v[148:151], v185 offset:1024
	ds_read_b128 v[152:155], v185 offset:2048
	ds_read_b128 v[156:159], v185 offset:3072
	ds_read_b128 v[160:163], v186 offset:0
	ds_read_b128 v[164:167], v186 offset:1024
	ds_read_b128 v[168:171], v186 offset:2048
	ds_read_b128 v[172:175], v186 offset:3072
	ds_read_b128 v[176:179], v187 offset:0
	ds_read_b128 v[190:193], v187 offset:1024
	ds_read_b128 v[194:197], v187 offset:2048
	ds_read_b128 v[198:201], v187 offset:3072
	ds_read_b128 v[202:205], v187 offset:4096
	ds_read_b128 v[206:209], v187 offset:5120
	ds_read_b128 v[210:213], v187 offset:6144
	ds_read_b128 v[214:217], v187 offset:7168
	ds_read_b128 v[220:223], v187 offset:16384
	ds_read_b128 v[224:227], v187 offset:17408
	ds_read_b128 v[228:231], v187 offset:18432
	ds_read_b128 v[232:235], v187 offset:19456
	ds_read_b128 v[236:239], v187 offset:20480
	ds_read_b128 v[240:243], v187 offset:21504
	ds_read_b128 v[244:247], v187 offset:22528
	ds_read_b128 v[248:251], v187 offset:23552
	s_nop 15
	s_nop 15
	s_waitcnt lgkmcnt(0)
	s_barrier
	s_cmp_eq_i32 s56, -2
	s_cbranch_scc1 .Lk64_z_p7_l
	s_setprio 1
	v_mfma_f32_16x16x32_bf16 v[72:75], v[144:147], v[176:179], v[72:75]
	v_mfma_f32_16x16x32_bf16 v[76:79], v[152:155], v[176:179], v[76:79]
	v_mfma_f32_16x16x32_bf16 v[96:99], v[144:147], v[194:197], v[96:99]
	v_mfma_f32_16x16x32_bf16 v[100:103], v[152:155], v[194:197], v[100:103]
	v_mfma_f32_16x16x32_bf16 v[120:123], v[144:147], v[202:205], v[120:123]
	v_mfma_f32_16x16x32_bf16 v[124:127], v[152:155], v[202:205], v[124:127]
	v_mfma_f32_16x16x32_bf16 v[92:95], v[144:147], v[210:213], v[92:95]
	v_mfma_f32_16x16x32_bf16 v[84:87], v[152:155], v[210:213], v[84:87]
	v_mfma_f32_16x16x32_bf16 v[72:75], v[148:151], v[190:193], v[72:75]
	v_mfma_f32_16x16x32_bf16 v[76:79], v[156:159], v[190:193], v[76:79]
	v_mfma_f32_16x16x32_bf16 v[96:99], v[148:151], v[198:201], v[96:99]
	v_mfma_f32_16x16x32_bf16 v[100:103], v[156:159], v[198:201], v[100:103]
	v_mfma_f32_16x16x32_bf16 v[120:123], v[148:151], v[206:209], v[120:123]
	v_mfma_f32_16x16x32_bf16 v[124:127], v[156:159], v[206:209], v[124:127]
	v_mfma_f32_16x16x32_bf16 v[92:95], v[148:151], v[214:217], v[92:95]
	v_mfma_f32_16x16x32_bf16 v[84:87], v[156:159], v[214:217], v[84:87]
	s_setprio 0
	s_setprio 1
	v_mfma_f32_16x16x32_bf16 v[80:83], v[160:163], v[176:179], v[80:83]
	v_mfma_f32_16x16x32_bf16 v[88:91], v[168:171], v[176:179], v[88:91]
	v_mfma_f32_16x16x32_bf16 v[108:111], v[160:163], v[194:197], v[108:111]
	v_mfma_f32_16x16x32_bf16 v[112:115], v[168:171], v[194:197], v[112:115]
	v_mfma_f32_16x16x32_bf16 v[116:119], v[160:163], v[202:205], v[116:119]
	v_mfma_f32_16x16x32_bf16 v[104:107], v[168:171], v[202:205], v[104:107]
	v_mfma_f32_16x16x32_bf16 v[68:71], v[160:163], v[210:213], v[68:71]
	v_mfma_f32_16x16x32_bf16 v[64:67], v[168:171], v[210:213], v[64:67]
	v_mfma_f32_16x16x32_bf16 v[80:83], v[164:167], v[190:193], v[80:83]
	v_mfma_f32_16x16x32_bf16 v[88:91], v[172:175], v[190:193], v[88:91]
	v_mfma_f32_16x16x32_bf16 v[108:111], v[164:167], v[198:201], v[108:111]
	v_mfma_f32_16x16x32_bf16 v[112:115], v[172:175], v[198:201], v[112:115]
	v_mfma_f32_16x16x32_bf16 v[116:119], v[164:167], v[206:209], v[116:119]
	v_mfma_f32_16x16x32_bf16 v[104:107], v[172:175], v[206:209], v[104:107]
	v_mfma_f32_16x16x32_bf16 v[68:71], v[164:167], v[214:217], v[68:71]
	v_mfma_f32_16x16x32_bf16 v[64:67], v[172:175], v[214:217], v[64:67]
	s_setprio 0
	s_setprio 1
	v_mfma_f32_16x16x32_bf16 v[60:63], v[144:147], v[220:223], v[60:63]
	v_mfma_f32_16x16x32_bf16 v[56:59], v[152:155], v[220:223], v[56:59]
	v_mfma_f32_16x16x32_bf16 v[44:47], v[144:147], v[228:231], v[44:47]
	v_mfma_f32_16x16x32_bf16 v[40:43], v[152:155], v[228:231], v[40:43]
	v_mfma_f32_16x16x32_bf16 v[28:31], v[144:147], v[236:239], v[28:31]
	v_mfma_f32_16x16x32_bf16 v[24:27], v[152:155], v[236:239], v[24:27]
	v_mfma_f32_16x16x32_bf16 v[12:15], v[144:147], v[244:247], v[12:15]
	v_mfma_f32_16x16x32_bf16 v[8:11], v[152:155], v[244:247], v[8:11]
	v_mfma_f32_16x16x32_bf16 v[60:63], v[148:151], v[224:227], v[60:63]
	v_mfma_f32_16x16x32_bf16 v[56:59], v[156:159], v[224:227], v[56:59]
	v_mfma_f32_16x16x32_bf16 v[44:47], v[148:151], v[232:235], v[44:47]
	v_mfma_f32_16x16x32_bf16 v[40:43], v[156:159], v[232:235], v[40:43]
	v_mfma_f32_16x16x32_bf16 v[28:31], v[148:151], v[240:243], v[28:31]
	v_mfma_f32_16x16x32_bf16 v[24:27], v[156:159], v[240:243], v[24:27]
	v_mfma_f32_16x16x32_bf16 v[12:15], v[148:151], v[248:251], v[12:15]
	v_mfma_f32_16x16x32_bf16 v[8:11], v[156:159], v[248:251], v[8:11]
	s_setprio 0
	s_setprio 1
	v_mfma_f32_16x16x32_bf16 v[52:55], v[160:163], v[220:223], v[52:55]
	v_mfma_f32_16x16x32_bf16 v[48:51], v[168:171], v[220:223], v[48:51]
	v_mfma_f32_16x16x32_bf16 v[36:39], v[160:163], v[228:231], v[36:39]
	v_mfma_f32_16x16x32_bf16 v[32:35], v[168:171], v[228:231], v[32:35]
	v_mfma_f32_16x16x32_bf16 v[20:23], v[160:163], v[236:239], v[20:23]
	v_mfma_f32_16x16x32_bf16 v[16:19], v[168:171], v[236:239], v[16:19]
	v_mfma_f32_16x16x32_bf16 v[4:7], v[160:163], v[244:247], v[4:7]
	v_mfma_f32_16x16x32_bf16 v[0:3], v[168:171], v[244:247], v[0:3]
	v_mfma_f32_16x16x32_bf16 v[52:55], v[164:167], v[224:227], v[52:55]
	v_mfma_f32_16x16x32_bf16 v[48:51], v[172:175], v[224:227], v[48:51]
	v_mfma_f32_16x16x32_bf16 v[36:39], v[164:167], v[232:235], v[36:39]
	v_mfma_f32_16x16x32_bf16 v[32:35], v[172:175], v[232:235], v[32:35]
	v_mfma_f32_16x16x32_bf16 v[20:23], v[164:167], v[240:243], v[20:23]
	v_mfma_f32_16x16x32_bf16 v[16:19], v[172:175], v[240:243], v[16:19]
	v_mfma_f32_16x16x32_bf16 v[4:7], v[164:167], v[248:251], v[4:7]
	v_mfma_f32_16x16x32_bf16 v[0:3], v[172:175], v[248:251], v[0:3]
	s_setprio 0
.Lk64_zj_p7_l:
	s_waitcnt vmcnt(0)
	s_barrier
	s_add_u32 vcc_lo, s26, 0x0
	s_addc_u32 vcc_hi, s27, 0
	s_add_i32 m0, s30, 0x10000
	s_nop 0
	global_load_lds_dwordx4 v130, vcc
	s_add_i32 m0, s30, 0x12000
	s_nop 0
	global_load_lds_dwordx4 v134, vcc
	s_add_u32 vcc_lo, vcc_lo, 0x58000
	s_addc_u32 vcc_hi, vcc_hi, 0
	s_add_i32 m0, s30, 0x11000
	s_nop 0
	global_load_lds_dwordx4 v130, vcc
	s_add_i32 m0, s30, 0x13000
	s_nop 0
	global_load_lds_dwordx4 v134, vcc
	s_add_u32 vcc_lo, vcc_lo, 0x108000
	s_addc_u32 vcc_hi, vcc_hi, 0
	s_add_i32 m0, s30, 0x14000
	s_nop 0
	global_load_lds_dwordx4 v130, vcc
	s_add_i32 m0, s30, 0x16000
	s_nop 0
	global_load_lds_dwordx4 v134, vcc
	s_add_u32 vcc_lo, vcc_lo, 0x58000
	s_addc_u32 vcc_hi, vcc_hi, 0
	s_add_i32 m0, s30, 0x15000
	s_nop 0
	global_load_lds_dwordx4 v130, vcc
	s_add_i32 m0, s30, 0x17000
	s_nop 0
	global_load_lds_dwordx4 v134, vcc
	ds_read_b128 v[144:147], v185 offset:32768
	ds_read_b128 v[148:151], v185 offset:33792
	ds_read_b128 v[152:155], v185 offset:34816
	ds_read_b128 v[156:159], v185 offset:35840
	ds_read_b128 v[160:163], v186 offset:32768
	ds_read_b128 v[164:167], v186 offset:33792
	ds_read_b128 v[168:171], v186 offset:34816
	ds_read_b128 v[172:175], v186 offset:35840
	ds_read_b128 v[176:179], v187 offset:32768
	ds_read_b128 v[190:193], v187 offset:33792
	ds_read_b128 v[194:197], v187 offset:34816
	ds_read_b128 v[198:201], v187 offset:35840
	ds_read_b128 v[202:205], v187 offset:36864
	ds_read_b128 v[206:209], v187 offset:37888
	ds_read_b128 v[210:213], v187 offset:38912
	ds_read_b128 v[214:217], v187 offset:39936
	ds_read_b128 v[220:223], v187 offset:49152
	ds_read_b128 v[224:227], v187 offset:50176
	ds_read_b128 v[228:231], v187 offset:51200
	ds_read_b128 v[232:235], v187 offset:52224
	ds_read_b128 v[236:239], v187 offset:53248
	ds_read_b128 v[240:243], v187 offset:54272
	ds_read_b128 v[244:247], v187 offset:55296
	ds_read_b128 v[248:251], v187 offset:56320
	s_nop 15
	s_nop 15
	s_waitcnt lgkmcnt(0)
	s_barrier
	s_setprio 1
	v_mfma_f32_16x16x32_bf16 v[72:75], v[144:147], v[176:179], v[72:75]
	v_mfma_f32_16x16x32_bf16 v[76:79], v[152:155], v[176:179], v[76:79]
	v_mfma_f32_16x16x32_bf16 v[96:99], v[144:147], v[194:197], v[96:99]
	v_mfma_f32_16x16x32_bf16 v[100:103], v[152:155], v[194:197], v[100:103]
	v_mfma_f32_16x16x32_bf16 v[120:123], v[144:147], v[202:205], v[120:123]
	v_mfma_f32_16x16x32_bf16 v[124:127], v[152:155], v[202:205], v[124:127]
	v_mfma_f32_16x16x32_bf16 v[92:95], v[144:147], v[210:213], v[92:95]
	v_mfma_f32_16x16x32_bf16 v[84:87], v[152:155], v[210:213], v[84:87]
	v_mfma_f32_16x16x32_bf16 v[72:75], v[148:151], v[190:193], v[72:75]
	v_mfma_f32_16x16x32_bf16 v[76:79], v[156:159], v[190:193], v[76:79]
	v_mfma_f32_16x16x32_bf16 v[96:99], v[148:151], v[198:201], v[96:99]
	v_mfma_f32_16x16x32_bf16 v[100:103], v[156:159], v[198:201], v[100:103]
	v_mfma_f32_16x16x32_bf16 v[120:123], v[148:151], v[206:209], v[120:123]
	v_mfma_f32_16x16x32_bf16 v[124:127], v[156:159], v[206:209], v[124:127]
	v_mfma_f32_16x16x32_bf16 v[92:95], v[148:151], v[214:217], v[92:95]
	v_mfma_f32_16x16x32_bf16 v[84:87], v[156:159], v[214:217], v[84:87]
	s_setprio 0
	s_setprio 1
	v_mfma_f32_16x16x32_bf16 v[80:83], v[160:163], v[176:179], v[80:83]
	v_mfma_f32_16x16x32_bf16 v[88:91], v[168:171], v[176:179], v[88:91]
	v_mfma_f32_16x16x32_bf16 v[108:111], v[160:163], v[194:197], v[108:111]
	v_mfma_f32_16x16x32_bf16 v[112:115], v[168:171], v[194:197], v[112:115]
	v_mfma_f32_16x16x32_bf16 v[116:119], v[160:163], v[202:205], v[116:119]
	v_mfma_f32_16x16x32_bf16 v[104:107], v[168:171], v[202:205], v[104:107]
	v_mfma_f32_16x16x32_bf16 v[68:71], v[160:163], v[210:213], v[68:71]
	v_mfma_f32_16x16x32_bf16 v[64:67], v[168:171], v[210:213], v[64:67]
	v_mfma_f32_16x16x32_bf16 v[80:83], v[164:167], v[190:193], v[80:83]
	v_mfma_f32_16x16x32_bf16 v[88:91], v[172:175], v[190:193], v[88:91]
	v_mfma_f32_16x16x32_bf16 v[108:111], v[164:167], v[198:201], v[108:111]
	v_mfma_f32_16x16x32_bf16 v[112:115], v[172:175], v[198:201], v[112:115]
	v_mfma_f32_16x16x32_bf16 v[116:119], v[164:167], v[206:209], v[116:119]
	v_mfma_f32_16x16x32_bf16 v[104:107], v[172:175], v[206:209], v[104:107]
	v_mfma_f32_16x16x32_bf16 v[68:71], v[164:167], v[214:217], v[68:71]
	v_mfma_f32_16x16x32_bf16 v[64:67], v[172:175], v[214:217], v[64:67]
	s_setprio 0
	s_setprio 1
	v_mfma_f32_16x16x32_bf16 v[60:63], v[144:147], v[220:223], v[60:63]
	v_mfma_f32_16x16x32_bf16 v[56:59], v[152:155], v[220:223], v[56:59]
	v_mfma_f32_16x16x32_bf16 v[44:47], v[144:147], v[228:231], v[44:47]
	v_mfma_f32_16x16x32_bf16 v[40:43], v[152:155], v[228:231], v[40:43]
	v_mfma_f32_16x16x32_bf16 v[28:31], v[144:147], v[236:239], v[28:31]
	v_mfma_f32_16x16x32_bf16 v[24:27], v[152:155], v[236:239], v[24:27]
	v_mfma_f32_16x16x32_bf16 v[12:15], v[144:147], v[244:247], v[12:15]
	v_mfma_f32_16x16x32_bf16 v[8:11], v[152:155], v[244:247], v[8:11]
	v_mfma_f32_16x16x32_bf16 v[60:63], v[148:151], v[224:227], v[60:63]
	v_mfma_f32_16x16x32_bf16 v[56:59], v[156:159], v[224:227], v[56:59]
	v_mfma_f32_16x16x32_bf16 v[44:47], v[148:151], v[232:235], v[44:47]
	v_mfma_f32_16x16x32_bf16 v[40:43], v[156:159], v[232:235], v[40:43]
	v_mfma_f32_16x16x32_bf16 v[28:31], v[148:151], v[240:243], v[28:31]
	v_mfma_f32_16x16x32_bf16 v[24:27], v[156:159], v[240:243], v[24:27]
	v_mfma_f32_16x16x32_bf16 v[12:15], v[148:151], v[248:251], v[12:15]
	v_mfma_f32_16x16x32_bf16 v[8:11], v[156:159], v[248:251], v[8:11]
	s_setprio 0
	s_setprio 1
	v_mfma_f32_16x16x32_bf16 v[52:55], v[160:163], v[220:223], v[52:55]
	v_mfma_f32_16x16x32_bf16 v[48:51], v[168:171], v[220:223], v[48:51]
	v_mfma_f32_16x16x32_bf16 v[36:39], v[160:163], v[228:231], v[36:39]
	v_mfma_f32_16x16x32_bf16 v[32:35], v[168:171], v[228:231], v[32:35]
	v_mfma_f32_16x16x32_bf16 v[20:23], v[160:163], v[236:239], v[20:23]
	v_mfma_f32_16x16x32_bf16 v[16:19], v[168:171], v[236:239], v[16:19]
	v_mfma_f32_16x16x32_bf16 v[4:7], v[160:163], v[244:247], v[4:7]
	v_mfma_f32_16x16x32_bf16 v[0:3], v[168:171], v[244:247], v[0:3]
	v_mfma_f32_16x16x32_bf16 v[52:55], v[164:167], v[224:227], v[52:55]
	v_mfma_f32_16x16x32_bf16 v[48:51], v[172:175], v[224:227], v[48:51]
	v_mfma_f32_16x16x32_bf16 v[36:39], v[164:167], v[232:235], v[36:39]
	v_mfma_f32_16x16x32_bf16 v[32:35], v[172:175], v[232:235], v[32:35]
	v_mfma_f32_16x16x32_bf16 v[20:23], v[164:167], v[240:243], v[20:23]
	v_mfma_f32_16x16x32_bf16 v[16:19], v[172:175], v[240:243], v[16:19]
	v_mfma_f32_16x16x32_bf16 v[4:7], v[164:167], v[248:251], v[4:7]
	v_mfma_f32_16x16x32_bf16 v[0:3], v[172:175], v[248:251], v[0:3]
	s_setprio 0
	s_waitcnt vmcnt(0)
	s_barrier
	s_add_i32 s56, s56, 2
	s_add_u32 s46, s46, 0x100
	s_addc_u32 s47, s47, 0
	s_cmpk_gt_u32 s56, 0x55
	s_mov_b64 s[22:23], s[24:25]
	s_cbranch_scc0 .LBB0_940
	s_branch .Lk64_done_p7
.Lk64_z_p7_l:
	s_setprio 1
	v_mfma_f32_16x16x32_bf16 v[72:75], v[144:147], v[176:179], 0
	v_mfma_f32_16x16x32_bf16 v[76:79], v[152:155], v[176:179], 0
	v_mfma_f32_16x16x32_bf16 v[96:99], v[144:147], v[194:197], 0
	v_mfma_f32_16x16x32_bf16 v[100:103], v[152:155], v[194:197], 0
	v_mfma_f32_16x16x32_bf16 v[120:123], v[144:147], v[202:205], 0
	v_mfma_f32_16x16x32_bf16 v[124:127], v[152:155], v[202:205], 0
	v_mfma_f32_16x16x32_bf16 v[92:95], v[144:147], v[210:213], 0
	v_mfma_f32_16x16x32_bf16 v[84:87], v[152:155], v[210:213], 0
	v_mfma_f32_16x16x32_bf16 v[72:75], v[148:151], v[190:193], v[72:75]
	v_mfma_f32_16x16x32_bf16 v[76:79], v[156:159], v[190:193], v[76:79]
	v_mfma_f32_16x16x32_bf16 v[96:99], v[148:151], v[198:201], v[96:99]
	v_mfma_f32_16x16x32_bf16 v[100:103], v[156:159], v[198:201], v[100:103]
	v_mfma_f32_16x16x32_bf16 v[120:123], v[148:151], v[206:209], v[120:123]
	v_mfma_f32_16x16x32_bf16 v[124:127], v[156:159], v[206:209], v[124:127]
	v_mfma_f32_16x16x32_bf16 v[92:95], v[148:151], v[214:217], v[92:95]
	v_mfma_f32_16x16x32_bf16 v[84:87], v[156:159], v[214:217], v[84:87]
	s_setprio 0
	s_setprio 1
	v_mfma_f32_16x16x32_bf16 v[80:83], v[160:163], v[176:179], 0
	v_mfma_f32_16x16x32_bf16 v[88:91], v[168:171], v[176:179], 0
	v_mfma_f32_16x16x32_bf16 v[108:111], v[160:163], v[194:197], 0
	v_mfma_f32_16x16x32_bf16 v[112:115], v[168:171], v[194:197], 0
	v_mfma_f32_16x16x32_bf16 v[116:119], v[160:163], v[202:205], 0
	v_mfma_f32_16x16x32_bf16 v[104:107], v[168:171], v[202:205], 0
	v_mfma_f32_16x16x32_bf16 v[68:71], v[160:163], v[210:213], 0
	v_mfma_f32_16x16x32_bf16 v[64:67], v[168:171], v[210:213], 0
	v_mfma_f32_16x16x32_bf16 v[80:83], v[164:167], v[190:193], v[80:83]
	v_mfma_f32_16x16x32_bf16 v[88:91], v[172:175], v[190:193], v[88:91]
	v_mfma_f32_16x16x32_bf16 v[108:111], v[164:167], v[198:201], v[108:111]
	v_mfma_f32_16x16x32_bf16 v[112:115], v[172:175], v[198:201], v[112:115]
	v_mfma_f32_16x16x32_bf16 v[116:119], v[164:167], v[206:209], v[116:119]
	v_mfma_f32_16x16x32_bf16 v[104:107], v[172:175], v[206:209], v[104:107]
	v_mfma_f32_16x16x32_bf16 v[68:71], v[164:167], v[214:217], v[68:71]
	v_mfma_f32_16x16x32_bf16 v[64:67], v[172:175], v[214:217], v[64:67]
	s_setprio 0
	s_setprio 1
	v_mfma_f32_16x16x32_bf16 v[60:63], v[144:147], v[220:223], 0
	v_mfma_f32_16x16x32_bf16 v[56:59], v[152:155], v[220:223], 0
	v_mfma_f32_16x16x32_bf16 v[44:47], v[144:147], v[228:231], 0
	v_mfma_f32_16x16x32_bf16 v[40:43], v[152:155], v[228:231], 0
	v_mfma_f32_16x16x32_bf16 v[28:31], v[144:147], v[236:239], 0
	v_mfma_f32_16x16x32_bf16 v[24:27], v[152:155], v[236:239], 0
	v_mfma_f32_16x16x32_bf16 v[12:15], v[144:147], v[244:247], 0
	v_mfma_f32_16x16x32_bf16 v[8:11], v[152:155], v[244:247], 0
	v_mfma_f32_16x16x32_bf16 v[60:63], v[148:151], v[224:227], v[60:63]
	v_mfma_f32_16x16x32_bf16 v[56:59], v[156:159], v[224:227], v[56:59]
	v_mfma_f32_16x16x32_bf16 v[44:47], v[148:151], v[232:235], v[44:47]
	v_mfma_f32_16x16x32_bf16 v[40:43], v[156:159], v[232:235], v[40:43]
	v_mfma_f32_16x16x32_bf16 v[28:31], v[148:151], v[240:243], v[28:31]
	v_mfma_f32_16x16x32_bf16 v[24:27], v[156:159], v[240:243], v[24:27]
	v_mfma_f32_16x16x32_bf16 v[12:15], v[148:151], v[248:251], v[12:15]
	v_mfma_f32_16x16x32_bf16 v[8:11], v[156:159], v[248:251], v[8:11]
	s_setprio 0
	s_setprio 1
	v_mfma_f32_16x16x32_bf16 v[52:55], v[160:163], v[220:223], 0
	v_mfma_f32_16x16x32_bf16 v[48:51], v[168:171], v[220:223], 0
	v_mfma_f32_16x16x32_bf16 v[36:39], v[160:163], v[228:231], 0
	v_mfma_f32_16x16x32_bf16 v[32:35], v[168:171], v[228:231], 0
	v_mfma_f32_16x16x32_bf16 v[20:23], v[160:163], v[236:239], 0
	v_mfma_f32_16x16x32_bf16 v[16:19], v[168:171], v[236:239], 0
	v_mfma_f32_16x16x32_bf16 v[4:7], v[160:163], v[244:247], 0
	v_mfma_f32_16x16x32_bf16 v[0:3], v[168:171], v[244:247], 0
	v_mfma_f32_16x16x32_bf16 v[52:55], v[164:167], v[224:227], v[52:55]
	v_mfma_f32_16x16x32_bf16 v[48:51], v[172:175], v[224:227], v[48:51]
	v_mfma_f32_16x16x32_bf16 v[36:39], v[164:167], v[232:235], v[36:39]
	v_mfma_f32_16x16x32_bf16 v[32:35], v[172:175], v[232:235], v[32:35]
	v_mfma_f32_16x16x32_bf16 v[20:23], v[164:167], v[240:243], v[20:23]
	v_mfma_f32_16x16x32_bf16 v[16:19], v[172:175], v[240:243], v[16:19]
	v_mfma_f32_16x16x32_bf16 v[4:7], v[164:167], v[248:251], v[4:7]
	v_mfma_f32_16x16x32_bf16 v[0:3], v[172:175], v[248:251], v[0:3]
	s_setprio 0
	s_branch .Lk64_zj_p7_l
.Lk64_trail_p7:
	s_add_u32 vcc_lo, s22, 0x80
	s_addc_u32 vcc_hi, s23, 0
	s_add_i32 m0, s30, 0xa000
	s_nop 0
	global_load_lds_dwordx4 v132, vcc
	s_add_u32 vcc_lo, vcc_lo, 0x58000
	s_addc_u32 vcc_hi, vcc_hi, 0
	s_add_i32 m0, s30, 0x9000
	s_nop 0
	global_load_lds_dwordx4 v128, vcc
	s_add_u32 vcc_lo, vcc_lo, 0x108000
	s_addc_u32 vcc_hi, vcc_hi, 0
	s_add_i32 m0, s30, 0xe000
	s_nop 0
	global_load_lds_dwordx4 v132, vcc
	s_add_u32 vcc_lo, vcc_lo, 0x58000
	s_addc_u32 vcc_hi, vcc_hi, 0
	s_add_i32 m0, s30, 0xd000
	s_nop 0
	global_load_lds_dwordx4 v128, vcc
	s_add_u32 vcc_lo, s28, 0x0
	s_addc_u32 vcc_hi, s29, 0
	s_mov_b32 m0, s30
	s_nop 0
	global_load_lds_dwordx4 v128, vcc
	s_sub_u32 vcc_lo, vcc_lo, 0x58000
	s_subb_u32 vcc_hi, vcc_hi, 0
	s_sub_i32 m0, s30, 0x1000
	s_nop 0
	global_load_lds_dwordx4 v128, vcc
	s_add_u32 vcc_lo, vcc_lo, 0x1b8000
	s_addc_u32 vcc_hi, vcc_hi, 0
	s_add_i32 m0, s30, 0x4000
	s_nop 0
	global_load_lds_dwordx4 v128, vcc
	s_sub_u32 vcc_lo, vcc_lo, 0x58000
	s_subb_u32 vcc_hi, vcc_hi, 0
	s_add_i32 m0, s30, 0x3000
	s_nop 0
	global_load_lds_dwordx4 v128, vcc
	ds_read_b128 v[144:147], v185 offset:0
	ds_read_b128 v[148:151], v185 offset:1024
	ds_read_b128 v[152:155], v185 offset:2048
	ds_read_b128 v[156:159], v185 offset:3072
	ds_read_b128 v[160:163], v186 offset:0
	ds_read_b128 v[164:167], v186 offset:1024
	ds_read_b128 v[168:171], v186 offset:2048
	ds_read_b128 v[172:175], v186 offset:3072
	ds_read_b128 v[176:179], v187 offset:0
	ds_read_b128 v[190:193], v187 offset:1024
	ds_read_b128 v[194:197], v187 offset:2048
	ds_read_b128 v[198:201], v187 offset:3072
	ds_read_b128 v[202:205], v187 offset:4096
	ds_read_b128 v[206:209], v187 offset:5120
	ds_read_b128 v[210:213], v187 offset:6144
	ds_read_b128 v[214:217], v187 offset:7168
	ds_read_b128 v[220:223], v187 offset:16384
	ds_read_b128 v[224:227], v187 offset:17408
	ds_read_b128 v[228:231], v187 offset:18432
	ds_read_b128 v[232:235], v187 offset:19456
	ds_read_b128 v[236:239], v187 offset:20480
	ds_read_b128 v[240:243], v187 offset:21504
	ds_read_b128 v[244:247], v187 offset:22528
	ds_read_b128 v[248:251], v187 offset:23552
	s_nop 15
	s_nop 15
	s_waitcnt lgkmcnt(0)
	s_barrier
	s_cmp_eq_i32 s56, -2
	s_cbranch_scc1 .Lk64_z_p7_t
	s_setprio 1
	v_mfma_f32_16x16x32_bf16 v[72:75], v[144:147], v[176:179], v[72:75]
	v_mfma_f32_16x16x32_bf16 v[76:79], v[152:155], v[176:179], v[76:79]
	v_mfma_f32_16x16x32_bf16 v[96:99], v[144:147], v[194:197], v[96:99]
	v_mfma_f32_16x16x32_bf16 v[100:103], v[152:155], v[194:197], v[100:103]
	v_mfma_f32_16x16x32_bf16 v[120:123], v[144:147], v[202:205], v[120:123]
	v_mfma_f32_16x16x32_bf16 v[124:127], v[152:155], v[202:205], v[124:127]
	v_mfma_f32_16x16x32_bf16 v[92:95], v[144:147], v[210:213], v[92:95]
	v_mfma_f32_16x16x32_bf16 v[84:87], v[152:155], v[210:213], v[84:87]
	v_mfma_f32_16x16x32_bf16 v[72:75], v[148:151], v[190:193], v[72:75]
	v_mfma_f32_16x16x32_bf16 v[76:79], v[156:159], v[190:193], v[76:79]
	v_mfma_f32_16x16x32_bf16 v[96:99], v[148:151], v[198:201], v[96:99]
	v_mfma_f32_16x16x32_bf16 v[100:103], v[156:159], v[198:201], v[100:103]
	v_mfma_f32_16x16x32_bf16 v[120:123], v[148:151], v[206:209], v[120:123]
	v_mfma_f32_16x16x32_bf16 v[124:127], v[156:159], v[206:209], v[124:127]
	v_mfma_f32_16x16x32_bf16 v[92:95], v[148:151], v[214:217], v[92:95]
	v_mfma_f32_16x16x32_bf16 v[84:87], v[156:159], v[214:217], v[84:87]
	s_setprio 0
	s_setprio 1
	v_mfma_f32_16x16x32_bf16 v[80:83], v[160:163], v[176:179], v[80:83]
	v_mfma_f32_16x16x32_bf16 v[88:91], v[168:171], v[176:179], v[88:91]
	v_mfma_f32_16x16x32_bf16 v[108:111], v[160:163], v[194:197], v[108:111]
	v_mfma_f32_16x16x32_bf16 v[112:115], v[168:171], v[194:197], v[112:115]
	v_mfma_f32_16x16x32_bf16 v[116:119], v[160:163], v[202:205], v[116:119]
	v_mfma_f32_16x16x32_bf16 v[104:107], v[168:171], v[202:205], v[104:107]
	v_mfma_f32_16x16x32_bf16 v[68:71], v[160:163], v[210:213], v[68:71]
	v_mfma_f32_16x16x32_bf16 v[64:67], v[168:171], v[210:213], v[64:67]
	v_mfma_f32_16x16x32_bf16 v[80:83], v[164:167], v[190:193], v[80:83]
	v_mfma_f32_16x16x32_bf16 v[88:91], v[172:175], v[190:193], v[88:91]
	v_mfma_f32_16x16x32_bf16 v[108:111], v[164:167], v[198:201], v[108:111]
	v_mfma_f32_16x16x32_bf16 v[112:115], v[172:175], v[198:201], v[112:115]
	v_mfma_f32_16x16x32_bf16 v[116:119], v[164:167], v[206:209], v[116:119]
	v_mfma_f32_16x16x32_bf16 v[104:107], v[172:175], v[206:209], v[104:107]
	v_mfma_f32_16x16x32_bf16 v[68:71], v[164:167], v[214:217], v[68:71]
	v_mfma_f32_16x16x32_bf16 v[64:67], v[172:175], v[214:217], v[64:67]
	s_setprio 0
	s_setprio 1
	v_mfma_f32_16x16x32_bf16 v[60:63], v[144:147], v[220:223], v[60:63]
	v_mfma_f32_16x16x32_bf16 v[56:59], v[152:155], v[220:223], v[56:59]
	v_mfma_f32_16x16x32_bf16 v[44:47], v[144:147], v[228:231], v[44:47]
	v_mfma_f32_16x16x32_bf16 v[40:43], v[152:155], v[228:231], v[40:43]
	v_mfma_f32_16x16x32_bf16 v[28:31], v[144:147], v[236:239], v[28:31]
	v_mfma_f32_16x16x32_bf16 v[24:27], v[152:155], v[236:239], v[24:27]
	v_mfma_f32_16x16x32_bf16 v[12:15], v[144:147], v[244:247], v[12:15]
	v_mfma_f32_16x16x32_bf16 v[8:11], v[152:155], v[244:247], v[8:11]
	v_mfma_f32_16x16x32_bf16 v[60:63], v[148:151], v[224:227], v[60:63]
	v_mfma_f32_16x16x32_bf16 v[56:59], v[156:159], v[224:227], v[56:59]
	v_mfma_f32_16x16x32_bf16 v[44:47], v[148:151], v[232:235], v[44:47]
	v_mfma_f32_16x16x32_bf16 v[40:43], v[156:159], v[232:235], v[40:43]
	v_mfma_f32_16x16x32_bf16 v[28:31], v[148:151], v[240:243], v[28:31]
	v_mfma_f32_16x16x32_bf16 v[24:27], v[156:159], v[240:243], v[24:27]
	v_mfma_f32_16x16x32_bf16 v[12:15], v[148:151], v[248:251], v[12:15]
	v_mfma_f32_16x16x32_bf16 v[8:11], v[156:159], v[248:251], v[8:11]
	s_setprio 0
	s_setprio 1
	v_mfma_f32_16x16x32_bf16 v[52:55], v[160:163], v[220:223], v[52:55]
	v_mfma_f32_16x16x32_bf16 v[48:51], v[168:171], v[220:223], v[48:51]
	v_mfma_f32_16x16x32_bf16 v[36:39], v[160:163], v[228:231], v[36:39]
	v_mfma_f32_16x16x32_bf16 v[32:35], v[168:171], v[228:231], v[32:35]
	v_mfma_f32_16x16x32_bf16 v[20:23], v[160:163], v[236:239], v[20:23]
	v_mfma_f32_16x16x32_bf16 v[16:19], v[168:171], v[236:239], v[16:19]
	v_mfma_f32_16x16x32_bf16 v[4:7], v[160:163], v[244:247], v[4:7]
	v_mfma_f32_16x16x32_bf16 v[0:3], v[168:171], v[244:247], v[0:3]
	v_mfma_f32_16x16x32_bf16 v[52:55], v[164:167], v[224:227], v[52:55]
	v_mfma_f32_16x16x32_bf16 v[48:51], v[172:175], v[224:227], v[48:51]
	v_mfma_f32_16x16x32_bf16 v[36:39], v[164:167], v[232:235], v[36:39]
	v_mfma_f32_16x16x32_bf16 v[32:35], v[172:175], v[232:235], v[32:35]
	v_mfma_f32_16x16x32_bf16 v[20:23], v[164:167], v[240:243], v[20:23]
	v_mfma_f32_16x16x32_bf16 v[16:19], v[172:175], v[240:243], v[16:19]
	v_mfma_f32_16x16x32_bf16 v[4:7], v[164:167], v[248:251], v[4:7]
	v_mfma_f32_16x16x32_bf16 v[0:3], v[172:175], v[248:251], v[0:3]
	s_setprio 0
.Lk64_zj_p7_t:
	s_waitcnt vmcnt(0)
	s_barrier
	s_add_u32 vcc_lo, s28, 0x0
	s_addc_u32 vcc_hi, s29, 0
	s_add_i32 m0, s30, 0x2000
	s_nop 0
	global_load_lds_dwordx4 v132, vcc
	s_add_u32 vcc_lo, vcc_lo, 0x58000
	s_addc_u32 vcc_hi, vcc_hi, 0
	s_add_i32 m0, s30, 0x1000
	s_nop 0
	global_load_lds_dwordx4 v128, vcc
	s_add_u32 vcc_lo, vcc_lo, 0x108000
	s_addc_u32 vcc_hi, vcc_hi, 0
	s_add_i32 m0, s30, 0x6000
	s_nop 0
	global_load_lds_dwordx4 v132, vcc
	s_add_u32 vcc_lo, vcc_lo, 0x58000
	s_addc_u32 vcc_hi, vcc_hi, 0
	s_add_i32 m0, s30, 0x5000
	s_nop 0
	global_load_lds_dwordx4 v128, vcc
	s_add_u32 vcc_lo, s28, 0x80
	s_addc_u32 vcc_hi, s29, 0
	s_add_i32 m0, s30, 0x8000
	s_nop 0
	global_load_lds_dwordx4 v128, vcc
	s_sub_u32 vcc_lo, vcc_lo, 0x58000
	s_subb_u32 vcc_hi, vcc_hi, 0
	s_add_i32 m0, s30, 0x7000
	s_nop 0
	global_load_lds_dwordx4 v128, vcc
	s_add_u32 vcc_lo, vcc_lo, 0x1b8000
	s_addc_u32 vcc_hi, vcc_hi, 0
	s_add_i32 m0, s30, 0xc000
	s_nop 0
	global_load_lds_dwordx4 v128, vcc
	s_sub_u32 vcc_lo, vcc_lo, 0x58000
	s_subb_u32 vcc_hi, vcc_hi, 0
	s_add_i32 m0, s30, 0xb000
	s_nop 0
	global_load_lds_dwordx4 v128, vcc
	ds_read_b128 v[144:147], v185 offset:32768
	ds_read_b128 v[148:151], v185 offset:33792
	ds_read_b128 v[152:155], v185 offset:34816
	ds_read_b128 v[156:159], v185 offset:35840
	ds_read_b128 v[160:163], v186 offset:32768
	ds_read_b128 v[164:167], v186 offset:33792
	ds_read_b128 v[168:171], v186 offset:34816
	ds_read_b128 v[172:175], v186 offset:35840
	ds_read_b128 v[176:179], v187 offset:32768
	ds_read_b128 v[190:193], v187 offset:33792
	ds_read_b128 v[194:197], v187 offset:34816
	ds_read_b128 v[198:201], v187 offset:35840
	ds_read_b128 v[202:205], v187 offset:36864
	ds_read_b128 v[206:209], v187 offset:37888
	ds_read_b128 v[210:213], v187 offset:38912
	ds_read_b128 v[214:217], v187 offset:39936
	ds_read_b128 v[220:223], v187 offset:49152
	ds_read_b128 v[224:227], v187 offset:50176
	ds_read_b128 v[228:231], v187 offset:51200
	ds_read_b128 v[232:235], v187 offset:52224
	ds_read_b128 v[236:239], v187 offset:53248
	ds_read_b128 v[240:243], v187 offset:54272
	ds_read_b128 v[244:247], v187 offset:55296
	ds_read_b128 v[248:251], v187 offset:56320
	s_nop 15
	s_nop 15
	s_waitcnt lgkmcnt(0)
	s_barrier
	s_setprio 1
	v_mfma_f32_16x16x32_bf16 v[72:75], v[144:147], v[176:179], v[72:75]
	v_mfma_f32_16x16x32_bf16 v[76:79], v[152:155], v[176:179], v[76:79]
	v_mfma_f32_16x16x32_bf16 v[96:99], v[144:147], v[194:197], v[96:99]
	v_mfma_f32_16x16x32_bf16 v[100:103], v[152:155], v[194:197], v[100:103]
	v_mfma_f32_16x16x32_bf16 v[120:123], v[144:147], v[202:205], v[120:123]
	v_mfma_f32_16x16x32_bf16 v[124:127], v[152:155], v[202:205], v[124:127]
	v_mfma_f32_16x16x32_bf16 v[92:95], v[144:147], v[210:213], v[92:95]
	v_mfma_f32_16x16x32_bf16 v[84:87], v[152:155], v[210:213], v[84:87]
	v_mfma_f32_16x16x32_bf16 v[72:75], v[148:151], v[190:193], v[72:75]
	v_mfma_f32_16x16x32_bf16 v[76:79], v[156:159], v[190:193], v[76:79]
	v_mfma_f32_16x16x32_bf16 v[96:99], v[148:151], v[198:201], v[96:99]
	v_mfma_f32_16x16x32_bf16 v[100:103], v[156:159], v[198:201], v[100:103]
	v_mfma_f32_16x16x32_bf16 v[120:123], v[148:151], v[206:209], v[120:123]
	v_mfma_f32_16x16x32_bf16 v[124:127], v[156:159], v[206:209], v[124:127]
	v_mfma_f32_16x16x32_bf16 v[92:95], v[148:151], v[214:217], v[92:95]
	v_mfma_f32_16x16x32_bf16 v[84:87], v[156:159], v[214:217], v[84:87]
	s_setprio 0
	s_setprio 1
	v_mfma_f32_16x16x32_bf16 v[80:83], v[160:163], v[176:179], v[80:83]
	v_mfma_f32_16x16x32_bf16 v[88:91], v[168:171], v[176:179], v[88:91]
	v_mfma_f32_16x16x32_bf16 v[108:111], v[160:163], v[194:197], v[108:111]
	v_mfma_f32_16x16x32_bf16 v[112:115], v[168:171], v[194:197], v[112:115]
	v_mfma_f32_16x16x32_bf16 v[116:119], v[160:163], v[202:205], v[116:119]
	v_mfma_f32_16x16x32_bf16 v[104:107], v[168:171], v[202:205], v[104:107]
	v_mfma_f32_16x16x32_bf16 v[68:71], v[160:163], v[210:213], v[68:71]
	v_mfma_f32_16x16x32_bf16 v[64:67], v[168:171], v[210:213], v[64:67]
	v_mfma_f32_16x16x32_bf16 v[80:83], v[164:167], v[190:193], v[80:83]
	v_mfma_f32_16x16x32_bf16 v[88:91], v[172:175], v[190:193], v[88:91]
	v_mfma_f32_16x16x32_bf16 v[108:111], v[164:167], v[198:201], v[108:111]
	v_mfma_f32_16x16x32_bf16 v[112:115], v[172:175], v[198:201], v[112:115]
	v_mfma_f32_16x16x32_bf16 v[116:119], v[164:167], v[206:209], v[116:119]
	v_mfma_f32_16x16x32_bf16 v[104:107], v[172:175], v[206:209], v[104:107]
	v_mfma_f32_16x16x32_bf16 v[68:71], v[164:167], v[214:217], v[68:71]
	v_mfma_f32_16x16x32_bf16 v[64:67], v[172:175], v[214:217], v[64:67]
	s_setprio 0
	s_setprio 1
	v_mfma_f32_16x16x32_bf16 v[60:63], v[144:147], v[220:223], v[60:63]
	v_mfma_f32_16x16x32_bf16 v[56:59], v[152:155], v[220:223], v[56:59]
	v_mfma_f32_16x16x32_bf16 v[44:47], v[144:147], v[228:231], v[44:47]
	v_mfma_f32_16x16x32_bf16 v[40:43], v[152:155], v[228:231], v[40:43]
	v_mfma_f32_16x16x32_bf16 v[28:31], v[144:147], v[236:239], v[28:31]
	v_mfma_f32_16x16x32_bf16 v[24:27], v[152:155], v[236:239], v[24:27]
	v_mfma_f32_16x16x32_bf16 v[12:15], v[144:147], v[244:247], v[12:15]
	v_mfma_f32_16x16x32_bf16 v[8:11], v[152:155], v[244:247], v[8:11]
	v_mfma_f32_16x16x32_bf16 v[60:63], v[148:151], v[224:227], v[60:63]
	v_mfma_f32_16x16x32_bf16 v[56:59], v[156:159], v[224:227], v[56:59]
	v_mfma_f32_16x16x32_bf16 v[44:47], v[148:151], v[232:235], v[44:47]
	v_mfma_f32_16x16x32_bf16 v[40:43], v[156:159], v[232:235], v[40:43]
	v_mfma_f32_16x16x32_bf16 v[28:31], v[148:151], v[240:243], v[28:31]
	v_mfma_f32_16x16x32_bf16 v[24:27], v[156:159], v[240:243], v[24:27]
	v_mfma_f32_16x16x32_bf16 v[12:15], v[148:151], v[248:251], v[12:15]
	v_mfma_f32_16x16x32_bf16 v[8:11], v[156:159], v[248:251], v[8:11]
	s_setprio 0
	s_setprio 1
	v_mfma_f32_16x16x32_bf16 v[52:55], v[160:163], v[220:223], v[52:55]
	v_mfma_f32_16x16x32_bf16 v[48:51], v[168:171], v[220:223], v[48:51]
	v_mfma_f32_16x16x32_bf16 v[36:39], v[160:163], v[228:231], v[36:39]
	v_mfma_f32_16x16x32_bf16 v[32:35], v[168:171], v[228:231], v[32:35]
	v_mfma_f32_16x16x32_bf16 v[20:23], v[160:163], v[236:239], v[20:23]
	v_mfma_f32_16x16x32_bf16 v[16:19], v[168:171], v[236:239], v[16:19]
	v_mfma_f32_16x16x32_bf16 v[4:7], v[160:163], v[244:247], v[4:7]
	v_mfma_f32_16x16x32_bf16 v[0:3], v[168:171], v[244:247], v[0:3]
	v_mfma_f32_16x16x32_bf16 v[52:55], v[164:167], v[224:227], v[52:55]
	v_mfma_f32_16x16x32_bf16 v[48:51], v[172:175], v[224:227], v[48:51]
	v_mfma_f32_16x16x32_bf16 v[36:39], v[164:167], v[232:235], v[36:39]
	v_mfma_f32_16x16x32_bf16 v[32:35], v[172:175], v[232:235], v[32:35]
	v_mfma_f32_16x16x32_bf16 v[20:23], v[164:167], v[240:243], v[20:23]
	v_mfma_f32_16x16x32_bf16 v[16:19], v[172:175], v[240:243], v[16:19]
	v_mfma_f32_16x16x32_bf16 v[4:7], v[164:167], v[248:251], v[4:7]
	v_mfma_f32_16x16x32_bf16 v[0:3], v[172:175], v[248:251], v[0:3]
	s_setprio 0
	s_waitcnt vmcnt(0)
	s_barrier
	s_add_i32 s56, s56, 2
	s_add_u32 s46, s46, 0x100
	s_addc_u32 s47, s47, 0
	s_cmpk_gt_u32 s56, 0x55
	s_mov_b64 s[22:23], s[24:25]
	s_cbranch_scc0 .LBB0_940
	s_branch .Lk64_done_p7
